# best + all remaining packed f32 VOP3P ops (S3 epilogues, LN) split into plain ops, bit-identical
# baseline (speedup 1.0000x reference)
; __device__ __forceinline__ float bflo(unsigned u) { return __uint_as_float(u << 16); }
; __device__ __forceinline__ float bfhi(unsigned u) { return __uint_as_float(u & 0xffff0000u); }
; __device__ __forceinline__ void conv_unit(int u, const bf16* qkv, bf16* Y, const float* cw) {
;     ...
;     for (int j = 0; j < 8; ++j) { w0[j] = cw[8 * cgp + j]; w1[j] = cw[512 + 8 * cgp + j]; w2[j] = cw[1024 + 8 * cgp + j]; }
;     float u2[8], u1[8];
;     auto ldu = [&](int rowi, float (&uu)[8]) {
;         const bf16* p = qkv + (size_t)rowi * PA + 8 * cgp; const u32x4 hv = *(const u32x4*)(p + C_BH), cv = *(const u32x4*)(p + C_BC);
;         uu[0] = bflo(hv.x) * bflo(cv.x); uu[1] = bfhi(hv.x) * bfhi(cv.x); uu[2] = bflo(hv.y) * bflo(cv.y); uu[3] = bfhi(hv.y) * bfhi(cv.y);
;         uu[4] = bflo(hv.z) * bflo(cv.z); uu[5] = bfhi(hv.z) * bfhi(cv.z); uu[6] = bflo(hv.w) * bflo(cv.w); uu[7] = bfhi(hv.w) * bfhi(cv.w); };
;     if ((tok0 & (SEQ - 1)) == 0) {
; #pragma unroll
;         for (int j = 0; j < 8; ++j) { u2[j] = 0.f; u1[j] = 0.f; }
;     } else { ldu(tok0 - 2, u2); ldu(tok0 - 1, u1); }
.LBB0_409:
	v_mov_b32_e32 v24, v206
	v_mov_b32_e32 v40, 0
	v_lshlrev_b32_e32 v0, 3, v24
	v_and_b32_e32 v25, 0x1f8, v0
	v_lshlrev_b32_e32 v64, 2, v25
	v_lshl_add_u64 v[8:9], s[0:1], 0, v[64:65]
	v_lshl_add_u64 v[10:11], v[8:9], 0, s[56:57]
	global_load_dwordx4 v[0:3], v64, s[0:1] offset:16
	global_load_dwordx4 v[12:15], v64, s[0:1]
	global_load_dwordx4 v[4:7], v64, s[0:1] offset:2064
	global_load_dwordx4 v[16:19], v64, s[0:1] offset:2048
	v_add_co_u32_e32 v8, vcc, 0x1000, v8
	v_ashrrev_i32_e32 v24, 3, v24
	s_nop 0
	v_addc_co_u32_e32 v9, vcc, 0, v9, vcc
	global_load_dwordx4 v[20:23], v[8:9], off
	s_nop 0
	global_load_dwordx4 v[8:11], v[10:11], off offset:16
	v_and_b32_e32 v24, -8, v24
	v_add_u32_e32 v50, s4, v24
	v_add_u32_e32 v46, -7, v50
	v_and_b32_e32 v24, 0x1ff8, v46
	v_cmp_ne_u32_e32 vcc, 0, v24
	v_lshlrev_b32_e32 v64, 1, v25
	v_mov_b32_e32 v41, 0
	v_mov_b32_e32 v42, 0
	v_mov_b32_e32 v43, 0
	v_mov_b32_e32 v30, 0
	v_mov_b32_e32 v31, 0
	v_mov_b32_e32 v24, 0
	v_mov_b32_e32 v25, 0
	v_mov_b32_e32 v26, 0
	v_mov_b32_e32 v27, 0
	v_mov_b32_e32 v32, 0
	v_mov_b32_e32 v33, 0
	v_mov_b32_e32 v34, 0
	v_mov_b32_e32 v35, 0
	v_mov_b32_e32 v36, 0
	v_mov_b32_e32 v37, 0
	s_and_saveexec_b64 s[2:3], vcc
	s_cbranch_execz .LBB0_408
	v_add_u32_e32 v24, -9, v50
	v_mov_b64_e32 v[32:33], s[36:37]
	s_movk_i32 s8, 0x1e00
	v_mad_i64_i32 v[24:25], s[6:7], v24, s8, v[32:33]
	v_lshl_add_u64 v[28:29], v[24:25], 0, v[64:65]
	global_load_dwordx4 v[24:27], v[28:29], off offset:1536
	s_nop 0
	global_load_dwordx4 v[28:31], v[28:29], off offset:3584
	s_waitcnt vmcnt(1)
	v_lshlrev_b32_e32 v40, 16, v26
	v_and_b32_e32 v41, 0xffff0000, v26
	v_add_u32_e32 v26, -8, v50
	v_lshlrev_b32_e32 v34, 16, v24
	v_and_b32_e32 v35, 0xffff0000, v24
	v_lshlrev_b32_e32 v38, 16, v25
	v_and_b32_e32 v39, 0xffff0000, v25
	v_lshlrev_b32_e32 v24, 16, v27
	v_and_b32_e32 v25, 0xffff0000, v27
	v_mad_i64_i32 v[26:27], s[6:7], v26, s8, v[32:33]
	s_waitcnt vmcnt(0)
	v_lshlrev_b32_e32 v36, 16, v28
	v_and_b32_e32 v37, 0xffff0000, v28
	v_lshlrev_b32_e32 v28, 16, v29
	v_and_b32_e32 v29, 0xffff0000, v29
	v_lshlrev_b32_e32 v44, 16, v30
	v_and_b32_e32 v45, 0xffff0000, v30
	v_lshlrev_b32_e32 v30, 16, v31
	v_and_b32_e32 v31, 0xffff0000, v31
	v_lshl_add_u64 v[32:33], v[26:27], 0, v[64:65]
	v_pk_mul_f32 v[24:25], v[24:25], v[30:31]
	v_pk_mul_f32 v[42:43], v[38:39], v[28:29]
	v_pk_mul_f32 v[30:31], v[40:41], v[44:45]
	v_pk_mul_f32 v[40:41], v[34:35], v[36:37]
	global_load_dwordx4 v[26:29], v[32:33], off offset:1536
	s_nop 0
	global_load_dwordx4 v[32:35], v[32:33], off offset:3584
	s_waitcnt vmcnt(1)
	v_lshlrev_b32_e32 v38, 16, v26
	v_and_b32_e32 v39, 0xffff0000, v26
	s_waitcnt vmcnt(0)
	v_lshlrev_b32_e32 v44, 16, v32
	v_and_b32_e32 v45, 0xffff0000, v32
	v_lshlrev_b32_e32 v26, 16, v27
	v_and_b32_e32 v27, 0xffff0000, v27
	v_lshlrev_b32_e32 v32, 16, v33
	v_and_b32_e32 v33, 0xffff0000, v33
	v_lshlrev_b32_e32 v48, 16, v28
	v_and_b32_e32 v49, 0xffff0000, v28
	v_lshlrev_b32_e32 v52, 16, v34
	v_and_b32_e32 v53, 0xffff0000, v34
	v_lshlrev_b32_e32 v28, 16, v29
	v_lshlrev_b32_e32 v34, 16, v35
	v_and_b32_e32 v35, 0xffff0000, v35
	v_and_b32_e32 v29, 0xffff0000, v29
	v_mul_f32_e32 v36, v28, v34
	v_mul_f32_e32 v37, v29, v35
	v_mul_f32_e32 v32, v26, v32
	v_mul_f32_e32 v33, v27, v33
	v_mul_f32_e32 v34, v48, v52
	v_mul_f32_e32 v35, v49, v53
	v_mul_f32_e32 v26, v38, v44
	v_mul_f32_e32 v27, v39, v45
	s_branch .LBB0_408

; __device__ __forceinline__ unsigned cvt_pk_bf16(float lo, float hi) { f32x2 v = {lo, hi}; bf16x2_t b = __builtin_convertvector(v, bf16x2_t); return __builtin_bit_cast(unsigned, b); }
; __device__ __forceinline__ float bf_lo(unsigned u) { return __uint_as_float(u << 16); }
; __device__ __forceinline__ float bf_hi(unsigned u) { return __uint_as_float(u & 0xffff0000u); }
;     __device__ __forceinline__ void operator()(const f32x4 (&acc)[2][2][4][2], const Unit& u, int wr, int wc, int fr, int fq) const {
;     ...
;                 for (int bj = 0; bj < 2; ++bj) { const size_t off = off0 + (size_t)(ai * HALF + m * 16) * 1024 + bj * HALF;
;                     g[m][bj] = *(const u32x4*)(G + off); o[m][bj] = (u32x4){0u, 0u, 0u, 0u}; if (!first) o[m][bj] = *(const u32x4*)(Mg + off); }
; #pragma unroll
;             for (int m = 0; m < 4; ++m)
; #pragma unroll
;                 for (int bj = 0; bj < 2; ++bj) { const size_t off = off0 + (size_t)(ai * HALF + m * 16) * 1024 + bj * HALF;
;                     const f32x4 v0 = acc[ai][bj][m][0], v1 = acc[ai][bj][m][1]; const u32x4 gg = g[m][bj], oo = o[m][bj]; u32x4 w;
;                     w.x = cvt_pk_bf16(bf_lo(oo.x) + bf_lo(gg.x) * v0[0], bf_hi(oo.x) + bf_hi(gg.x) * v0[1]);
;                     w.y = cvt_pk_bf16(bf_lo(oo.y) + bf_lo(gg.y) * v0[2], bf_hi(oo.y) + bf_hi(gg.y) * v0[3]);
;                     w.z = cvt_pk_bf16(bf_lo(oo.z) + bf_lo(gg.z) * v1[0], bf_hi(oo.z) + bf_hi(gg.z) * v1[1]);
;                     w.w = cvt_pk_bf16(bf_lo(oo.w) + bf_lo(gg.w) * v1[2], bf_hi(oo.w) + bf_hi(gg.w) * v1[3]);
;                     *(u32x4*)(Mg + off) = w; }
.LBB0_507:
	s_waitcnt vmcnt(0)
	v_lshlrev_b32_e32 v214, 16, v190
	v_and_b32_e32 v215, 0xffff0000, v190
	v_lshlrev_b32_e32 v216, 16, v186
	v_and_b32_e32 v217, 0xffff0000, v186
	v_lshlrev_b32_e32 v190, 16, v191
	v_and_b32_e32 v191, 0xffff0000, v191
	v_lshlrev_b32_e32 v186, 16, v187
	v_and_b32_e32 v187, 0xffff0000, v187
	v_fma_f32 v126, v126, v216, v214
	v_fma_f32 v127, v127, v217, v215
	v_fma_f32 v128, v128, v186, v190
	v_fma_f32 v129, v129, v187, v191
	v_cvt_pk_bf16_f32 v126, v126, v127
	v_cvt_pk_bf16_f32 v127, v128, v129
	v_lshlrev_b32_e32 v128, 16, v192
	v_and_b32_e32 v129, 0xffff0000, v192
	v_lshlrev_b32_e32 v186, 16, v188
	v_and_b32_e32 v187, 0xffff0000, v188
	v_fma_f32 v122, v122, v186, v128
	v_fma_f32 v123, v123, v187, v129
	v_lshlrev_b32_e32 v186, 16, v189
	v_cvt_pk_bf16_f32 v128, v122, v123
	v_lshlrev_b32_e32 v122, 16, v193
	v_and_b32_e32 v123, 0xffff0000, v193
	v_and_b32_e32 v187, 0xffff0000, v189
	v_fma_f32 v122, v124, v186, v122
	v_fma_f32 v123, v125, v187, v123
	v_lshlrev_b32_e32 v124, 16, v178
	v_cvt_pk_bf16_f32 v129, v122, v123
	v_lshlrev_b32_e32 v122, 16, v166
	v_and_b32_e32 v123, 0xffff0000, v166
	v_and_b32_e32 v125, 0xffff0000, v178
	v_fma_f32 v118, v118, v124, v122
	v_fma_f32 v119, v119, v125, v123
	v_lshlrev_b32_e32 v122, 16, v167
	v_and_b32_e32 v123, 0xffff0000, v167
	v_lshlrev_b32_e32 v124, 16, v179
	v_and_b32_e32 v125, 0xffff0000, v179
	v_fma_f32 v120, v120, v124, v122
	v_fma_f32 v121, v121, v125, v123
	v_cvt_pk_bf16_f32 v118, v118, v119
	v_cvt_pk_bf16_f32 v119, v120, v121
	v_lshlrev_b32_e32 v120, 16, v168
	v_and_b32_e32 v121, 0xffff0000, v168
	v_lshlrev_b32_e32 v122, 16, v180
	v_and_b32_e32 v123, 0xffff0000, v180
	v_fma_f32 v110, v110, v122, v120
	v_fma_f32 v111, v111, v123, v121
	v_lshlrev_b32_e32 v122, 16, v181
	v_cvt_pk_bf16_f32 v120, v110, v111
	v_lshlrev_b32_e32 v110, 16, v169
	v_and_b32_e32 v111, 0xffff0000, v169
	v_and_b32_e32 v123, 0xffff0000, v181
	v_fma_f32 v110, v112, v122, v110
	v_fma_f32 v111, v113, v123, v111
	v_lshlrev_b32_e32 v112, 16, v174
	v_cvt_pk_bf16_f32 v121, v110, v111
	v_lshlrev_b32_e32 v110, 16, v182
	v_and_b32_e32 v111, 0xffff0000, v182
	v_and_b32_e32 v113, 0xffff0000, v174
	v_fma_f32 v110, v114, v112, v110
	v_fma_f32 v111, v115, v113, v111
	v_lshlrev_b32_e32 v112, 16, v183
	v_and_b32_e32 v113, 0xffff0000, v183
	v_lshlrev_b32_e32 v114, 16, v175
	v_and_b32_e32 v115, 0xffff0000, v175
	v_fma_f32 v112, v116, v114, v112
	v_fma_f32 v113, v117, v115, v113
	v_cvt_pk_bf16_f32 v110, v110, v111
	v_cvt_pk_bf16_f32 v111, v112, v113
	v_lshlrev_b32_e32 v112, 16, v184
	v_and_b32_e32 v113, 0xffff0000, v184
	v_lshlrev_b32_e32 v114, 16, v176
	v_and_b32_e32 v115, 0xffff0000, v176
	v_fma_f32 v106, v106, v114, v112
	v_fma_f32 v107, v107, v115, v113
	v_lshlrev_b32_e32 v114, 16, v177
	v_cvt_pk_bf16_f32 v112, v106, v107
	v_lshlrev_b32_e32 v106, 16, v185
	v_and_b32_e32 v107, 0xffff0000, v185
	v_and_b32_e32 v115, 0xffff0000, v177
	v_fma_f32 v106, v108, v114, v106
	v_fma_f32 v107, v109, v115, v107
	v_lshlrev_b32_e32 v108, 16, v150
	v_cvt_pk_bf16_f32 v113, v106, v107
	v_add_co_u32_e32 v106, vcc, s64, v208
	v_and_b32_e32 v109, 0xffff0000, v150
	s_nop 0
	v_addc_co_u32_e32 v107, vcc, 0, v209, vcc
	global_store_dwordx4 v[106:107], v[110:113], off
	global_store_dwordx4 v[208:209], v[126:129], off
	global_store_dwordx4 v[208:209], v[118:121], off offset:256
	v_lshlrev_b32_e32 v110, 16, v162
	v_and_b32_e32 v111, 0xffff0000, v162
	v_fma_f32 v102, v102, v110, v108
	v_fma_f32 v103, v103, v111, v109
	v_lshlrev_b32_e32 v108, 16, v151
	v_and_b32_e32 v109, 0xffff0000, v151
	v_lshlrev_b32_e32 v110, 16, v163
	v_and_b32_e32 v111, 0xffff0000, v163
	v_fma_f32 v104, v104, v110, v108
	v_fma_f32 v105, v105, v111, v109
	v_cvt_pk_bf16_f32 v102, v102, v103
	v_cvt_pk_bf16_f32 v103, v104, v105
	v_lshlrev_b32_e32 v104, 16, v152
	v_and_b32_e32 v105, 0xffff0000, v152
	v_lshlrev_b32_e32 v108, 16, v164
	v_and_b32_e32 v109, 0xffff0000, v164
	v_fma_f32 v94, v94, v108, v104
	v_fma_f32 v95, v95, v109, v105
	v_lshlrev_b32_e32 v108, 16, v165
	v_cvt_pk_bf16_f32 v104, v94, v95
	v_lshlrev_b32_e32 v94, 16, v153
	v_and_b32_e32 v95, 0xffff0000, v153
	v_and_b32_e32 v109, 0xffff0000, v165
	v_fma_f32 v94, v96, v108, v94
	v_fma_f32 v95, v97, v109, v95
	v_lshlrev_b32_e32 v96, 16, v158
	v_cvt_pk_bf16_f32 v105, v94, v95
	v_lshlrev_b32_e32 v94, 16, v170
	v_and_b32_e32 v95, 0xffff0000, v170
	v_and_b32_e32 v97, 0xffff0000, v158
	v_fma_f32 v94, v98, v96, v94
	v_fma_f32 v95, v99, v97, v95
; __device__ __forceinline__ unsigned cvt_pk_bf16(float lo, float hi) { f32x2 v = {lo, hi}; bf16x2_t b = __builtin_convertvector(v, bf16x2_t); return __builtin_bit_cast(unsigned, b); }
; __device__ __forceinline__ float bf_lo(unsigned u) { return __uint_as_float(u << 16); }
; __device__ __forceinline__ float bf_hi(unsigned u) { return __uint_as_float(u & 0xffff0000u); }
;     __device__ __forceinline__ void operator()(const f32x4 (&acc)[2][2][4][2], const Unit& u, int wr, int wc, int fr, int fq) const {
;     ...
;             for (int m = 0; m < 4; ++m)
; #pragma unroll
;                 for (int bj = 0; bj < 2; ++bj) { const size_t off = off0 + (size_t)(ai * HALF + m * 16) * 1024 + bj * HALF;
;                     g[m][bj] = *(const u32x4*)(G + off); o[m][bj] = (u32x4){0u, 0u, 0u, 0u}; if (!first) o[m][bj] = *(const u32x4*)(Mg + off); }
; #pragma unroll
;             for (int m = 0; m < 4; ++m)
; #pragma unroll
;                 for (int bj = 0; bj < 2; ++bj) { const size_t off = off0 + (size_t)(ai * HALF + m * 16) * 1024 + bj * HALF;
;                     const f32x4 v0 = acc[ai][bj][m][0], v1 = acc[ai][bj][m][1]; const u32x4 gg = g[m][bj], oo = o[m][bj]; u32x4 w;
;                     w.x = cvt_pk_bf16(bf_lo(oo.x) + bf_lo(gg.x) * v0[0], bf_hi(oo.x) + bf_hi(gg.x) * v0[1]);
;                     w.y = cvt_pk_bf16(bf_lo(oo.y) + bf_lo(gg.y) * v0[2], bf_hi(oo.y) + bf_hi(gg.y) * v0[3]);
;                     w.z = cvt_pk_bf16(bf_lo(oo.z) + bf_lo(gg.z) * v1[0], bf_hi(oo.z) + bf_hi(gg.z) * v1[1]);
;                     w.w = cvt_pk_bf16(bf_lo(oo.w) + bf_lo(gg.w) * v1[2], bf_hi(oo.w) + bf_hi(gg.w) * v1[3]);
;                     *(u32x4*)(Mg + off) = w; }
	v_lshlrev_b32_e32 v96, 16, v171
	v_and_b32_e32 v97, 0xffff0000, v171
	v_lshlrev_b32_e32 v98, 16, v159
	v_and_b32_e32 v99, 0xffff0000, v159
	v_fma_f32 v96, v100, v98, v96
	v_fma_f32 v97, v101, v99, v97
	v_cvt_pk_bf16_f32 v94, v94, v95
	v_cvt_pk_bf16_f32 v95, v96, v97
	v_lshlrev_b32_e32 v96, 16, v172
	v_and_b32_e32 v97, 0xffff0000, v172
	v_lshlrev_b32_e32 v98, 16, v160
	v_and_b32_e32 v99, 0xffff0000, v160
	v_fma_f32 v90, v90, v98, v96
	v_fma_f32 v91, v91, v99, v97
	v_lshlrev_b32_e32 v98, 16, v161
	v_cvt_pk_bf16_f32 v96, v90, v91
	v_lshlrev_b32_e32 v90, 16, v173
	v_and_b32_e32 v91, 0xffff0000, v173
	v_and_b32_e32 v99, 0xffff0000, v161
	v_fma_f32 v90, v92, v98, v90
	v_fma_f32 v91, v93, v99, v91
	v_lshlrev_b32_e32 v92, 16, v138
	v_cvt_pk_bf16_f32 v97, v90, v91
	v_add_co_u32_e32 v90, vcc, s33, v208
	v_and_b32_e32 v93, 0xffff0000, v138
	s_nop 0
	v_addc_co_u32_e32 v91, vcc, 0, v209, vcc
	global_store_dwordx4 v[90:91], v[94:97], off
	global_store_dwordx4 v[106:107], v[102:105], off offset:256
	v_mov_b32_e32 v126, 0
	v_lshlrev_b32_e32 v94, 16, v146
	v_and_b32_e32 v95, 0xffff0000, v146
	v_fma_f32 v86, v86, v94, v92
	v_fma_f32 v87, v87, v95, v93
	v_lshlrev_b32_e32 v92, 16, v139
	v_and_b32_e32 v93, 0xffff0000, v139
	v_lshlrev_b32_e32 v94, 16, v147
	v_and_b32_e32 v95, 0xffff0000, v147
	v_fma_f32 v88, v88, v94, v92
	v_fma_f32 v89, v89, v95, v93
	v_cvt_pk_bf16_f32 v86, v86, v87
	v_cvt_pk_bf16_f32 v87, v88, v89
	v_lshlrev_b32_e32 v88, 16, v140
	v_and_b32_e32 v89, 0xffff0000, v140
	v_lshlrev_b32_e32 v92, 16, v148
	v_and_b32_e32 v93, 0xffff0000, v148
	v_fma_f32 v78, v78, v92, v88
	v_fma_f32 v79, v79, v93, v89
	v_lshlrev_b32_e32 v92, 16, v149
	v_cvt_pk_bf16_f32 v88, v78, v79
	v_lshlrev_b32_e32 v78, 16, v141
	v_and_b32_e32 v79, 0xffff0000, v141
	v_and_b32_e32 v93, 0xffff0000, v149
	v_fma_f32 v78, v80, v92, v78
	v_fma_f32 v79, v81, v93, v79
	v_lshlrev_b32_e32 v80, 16, v142
	v_cvt_pk_bf16_f32 v89, v78, v79
	v_lshlrev_b32_e32 v78, 16, v154
	v_and_b32_e32 v79, 0xffff0000, v154
	v_and_b32_e32 v81, 0xffff0000, v142
	v_fma_f32 v78, v82, v80, v78
	v_fma_f32 v79, v83, v81, v79
	v_lshlrev_b32_e32 v80, 16, v155
	v_and_b32_e32 v81, 0xffff0000, v155
	v_lshlrev_b32_e32 v82, 16, v143
	v_and_b32_e32 v83, 0xffff0000, v143
	v_fma_f32 v80, v84, v82, v80
	v_fma_f32 v81, v85, v83, v81
	v_cvt_pk_bf16_f32 v78, v78, v79
	v_cvt_pk_bf16_f32 v79, v80, v81
	v_lshlrev_b32_e32 v80, 16, v156
	v_and_b32_e32 v81, 0xffff0000, v156
	v_lshlrev_b32_e32 v82, 16, v144
	v_and_b32_e32 v83, 0xffff0000, v144
	v_fma_f32 v74, v74, v82, v80
	v_fma_f32 v75, v75, v83, v81
	v_lshlrev_b32_e32 v82, 16, v145
	v_cvt_pk_bf16_f32 v80, v74, v75
	v_lshlrev_b32_e32 v74, 16, v157
	v_and_b32_e32 v75, 0xffff0000, v157
	v_and_b32_e32 v83, 0xffff0000, v145
	v_fma_f32 v74, v76, v82, v74
	v_fma_f32 v75, v77, v83, v75
	v_lshlrev_b32_e32 v76, 16, v130
	v_cvt_pk_bf16_f32 v81, v74, v75
	v_add_co_u32_e32 v74, vcc, s63, v208
	v_and_b32_e32 v77, 0xffff0000, v130
	s_nop 0
	v_addc_co_u32_e32 v75, vcc, 0, v209, vcc
	global_store_dwordx4 v[74:75], v[78:81], off
	global_store_dwordx4 v[90:91], v[86:89], off offset:256
	v_mov_b32_e32 v102, 0
	v_lshlrev_b32_e32 v78, 16, v134
	v_and_b32_e32 v79, 0xffff0000, v134
	v_fma_f32 v70, v70, v78, v76
	v_fma_f32 v71, v71, v79, v77
	v_lshlrev_b32_e32 v76, 16, v131
	v_and_b32_e32 v77, 0xffff0000, v131
	v_lshlrev_b32_e32 v78, 16, v135
	v_and_b32_e32 v79, 0xffff0000, v135
	v_fma_f32 v72, v72, v78, v76
	v_fma_f32 v73, v73, v79, v77
	v_cvt_pk_bf16_f32 v70, v70, v71
	v_cvt_pk_bf16_f32 v71, v72, v73
	v_lshlrev_b32_e32 v72, 16, v132
	v_and_b32_e32 v73, 0xffff0000, v132
	v_lshlrev_b32_e32 v76, 16, v136
	v_and_b32_e32 v77, 0xffff0000, v136
	v_fma_f32 v66, v66, v76, v72
	v_fma_f32 v67, v67, v77, v73
	v_lshlrev_b32_e32 v76, 16, v137
	v_cvt_pk_bf16_f32 v72, v66, v67
	v_lshlrev_b32_e32 v66, 16, v133
	v_and_b32_e32 v67, 0xffff0000, v133
	v_and_b32_e32 v77, 0xffff0000, v137
	v_fma_f32 v66, v68, v76, v66
	v_fma_f32 v67, v69, v77, v67
	v_mov_b32_e32 v127, 0
	v_cvt_pk_bf16_f32 v73, v66, v67
	global_store_dwordx4 v[74:75], v[70:73], off offset:256
	v_add_co_u32_e32 v66, vcc, 0x40000, v210
	v_mov_b32_e32 v128, 0
	s_nop 0
	v_addc_co_u32_e32 v67, vcc, 0, v211, vcc
	global_load_dwordx4 v[122:125], v[66:67], off
	s_and_b64 vcc, exec, s[0:1]
	v_mov_b32_e32 v129, 0
	s_cbranch_vccnz .LBB0_509
	v_add_co_u32_e32 v66, vcc, 0x40000, v208
	s_nop 1
	v_addc_co_u32_e32 v67, vcc, 0, v209, vcc
	global_load_dwordx4 v[126:129], v[66:67], off

; __device__ __forceinline__ unsigned cvt_pk_bf16(float lo, float hi) { f32x2 v = {lo, hi}; bf16x2_t b = __builtin_convertvector(v, bf16x2_t); return __builtin_bit_cast(unsigned, b); }
; __device__ __forceinline__ float bf_lo(unsigned u) { return __uint_as_float(u << 16); }
; __device__ __forceinline__ float bf_hi(unsigned u) { return __uint_as_float(u & 0xffff0000u); }
;     __device__ __forceinline__ void operator()(const f32x4 (&acc)[2][2][4][2], const Unit& u, int wr, int wc, int fr, int fq) const {
;     ...
;             for (int m = 0; m < 4; ++m)
; #pragma unroll
;                 for (int bj = 0; bj < 2; ++bj) { const size_t off = off0 + (size_t)(ai * HALF + m * 16) * 1024 + bj * HALF;
;                     const f32x4 v0 = acc[ai][bj][m][0], v1 = acc[ai][bj][m][1]; const u32x4 gg = g[m][bj], oo = o[m][bj]; u32x4 w;
;                     w.x = cvt_pk_bf16(bf_lo(oo.x) + bf_lo(gg.x) * v0[0], bf_hi(oo.x) + bf_hi(gg.x) * v0[1]);
;                     w.y = cvt_pk_bf16(bf_lo(oo.y) + bf_lo(gg.y) * v0[2], bf_hi(oo.y) + bf_hi(gg.y) * v0[3]);
;                     w.z = cvt_pk_bf16(bf_lo(oo.z) + bf_lo(gg.z) * v1[0], bf_hi(oo.z) + bf_hi(gg.z) * v1[1]);
;                     w.w = cvt_pk_bf16(bf_lo(oo.w) + bf_lo(gg.w) * v1[2], bf_hi(oo.w) + bf_hi(gg.w) * v1[3]);
;                     *(u32x4*)(Mg + off) = w; }
.LBB0_523:
	s_waitcnt vmcnt(7)
	v_lshlrev_b32_e32 v130, 16, v126
	v_and_b32_e32 v131, 0xffff0000, v126
	v_lshlrev_b32_e32 v132, 16, v122
	v_and_b32_e32 v133, 0xffff0000, v122
	v_lshlrev_b32_e32 v126, 16, v127
	v_and_b32_e32 v127, 0xffff0000, v127
	v_lshlrev_b32_e32 v122, 16, v123
	v_and_b32_e32 v123, 0xffff0000, v123
	v_fma_f32 v60, v60, v132, v130
	v_fma_f32 v61, v61, v133, v131
	v_fma_f32 v62, v62, v122, v126
	v_fma_f32 v63, v63, v123, v127
	v_cvt_pk_bf16_f32 v60, v60, v61
	v_cvt_pk_bf16_f32 v61, v62, v63
	v_lshlrev_b32_e32 v62, 16, v128
	v_and_b32_e32 v63, 0xffff0000, v128
	v_lshlrev_b32_e32 v122, 16, v124
	v_and_b32_e32 v123, 0xffff0000, v124
	v_fma_f32 v56, v56, v122, v62
	v_fma_f32 v57, v57, v123, v63
	v_lshlrev_b32_e32 v122, 16, v125
	v_cvt_pk_bf16_f32 v62, v56, v57
	v_lshlrev_b32_e32 v56, 16, v129
	v_and_b32_e32 v57, 0xffff0000, v129
	v_and_b32_e32 v123, 0xffff0000, v125
	v_fma_f32 v56, v58, v122, v56
	v_fma_f32 v57, v59, v123, v57
	s_waitcnt vmcnt(6)
	v_lshlrev_b32_e32 v58, 16, v102
	v_cvt_pk_bf16_f32 v63, v56, v57
	v_add_co_u32_e32 v56, vcc, s40, v208
	v_and_b32_e32 v59, 0xffff0000, v102
	s_nop 0
	v_addc_co_u32_e32 v57, vcc, 0, v209, vcc
	global_store_dwordx4 v[56:57], v[60:63], off
	s_cmp_eq_u32 s81, 3
	s_mov_b64 s[0:1], -1
	v_lshlrev_b32_e32 v60, 16, v114
	v_and_b32_e32 v61, 0xffff0000, v114
	v_fma_f32 v52, v52, v60, v58
	v_fma_f32 v53, v53, v61, v59
	v_lshlrev_b32_e32 v58, 16, v103
	v_and_b32_e32 v59, 0xffff0000, v103
	v_lshlrev_b32_e32 v60, 16, v115
	v_and_b32_e32 v61, 0xffff0000, v115
	v_fma_f32 v54, v54, v60, v58
	v_fma_f32 v55, v55, v61, v59
	v_cvt_pk_bf16_f32 v52, v52, v53
	v_cvt_pk_bf16_f32 v53, v54, v55
	v_lshlrev_b32_e32 v54, 16, v104
	v_and_b32_e32 v55, 0xffff0000, v104
	v_lshlrev_b32_e32 v58, 16, v116
	v_and_b32_e32 v59, 0xffff0000, v116
	v_fma_f32 v44, v44, v58, v54
	v_fma_f32 v45, v45, v59, v55
	v_lshlrev_b32_e32 v58, 16, v117
	v_cvt_pk_bf16_f32 v54, v44, v45
	v_lshlrev_b32_e32 v44, 16, v105
	v_and_b32_e32 v45, 0xffff0000, v105
	v_and_b32_e32 v59, 0xffff0000, v117
	v_fma_f32 v44, v46, v58, v44
	v_fma_f32 v45, v47, v59, v45
	s_waitcnt vmcnt(6)
	v_lshlrev_b32_e32 v46, 16, v110
	v_cvt_pk_bf16_f32 v55, v44, v45
	v_lshlrev_b32_e32 v44, 16, v118
	v_and_b32_e32 v45, 0xffff0000, v118
	v_and_b32_e32 v47, 0xffff0000, v110
	v_fma_f32 v44, v48, v46, v44
	v_fma_f32 v45, v49, v47, v45
	v_lshlrev_b32_e32 v46, 16, v119
	v_and_b32_e32 v47, 0xffff0000, v119
	v_lshlrev_b32_e32 v48, 16, v111
	v_and_b32_e32 v49, 0xffff0000, v111
	v_fma_f32 v46, v50, v48, v46
	v_fma_f32 v47, v51, v49, v47
	v_cvt_pk_bf16_f32 v44, v44, v45
	v_cvt_pk_bf16_f32 v45, v46, v47
	v_lshlrev_b32_e32 v46, 16, v120
	v_and_b32_e32 v47, 0xffff0000, v120
	v_lshlrev_b32_e32 v48, 16, v112
	v_and_b32_e32 v49, 0xffff0000, v112
	v_fma_f32 v40, v40, v48, v46
	v_fma_f32 v41, v41, v49, v47
	v_lshlrev_b32_e32 v48, 16, v113
	v_cvt_pk_bf16_f32 v46, v40, v41
	v_lshlrev_b32_e32 v40, 16, v121
	v_and_b32_e32 v41, 0xffff0000, v121
	v_and_b32_e32 v49, 0xffff0000, v113
	v_fma_f32 v40, v42, v48, v40
	v_fma_f32 v41, v43, v49, v41
	s_waitcnt vmcnt(5)
	v_lshlrev_b32_e32 v42, 16, v86
	v_cvt_pk_bf16_f32 v47, v40, v41
	v_add_co_u32_e32 v40, vcc, s41, v208
	v_and_b32_e32 v43, 0xffff0000, v86
	s_nop 0
	v_addc_co_u32_e32 v41, vcc, 0, v209, vcc
	global_store_dwordx4 v[40:41], v[44:47], off
	global_store_dwordx4 v[56:57], v[52:55], off offset:256
	s_nop 0
	v_lshlrev_b32_e32 v44, 16, v98
	v_and_b32_e32 v45, 0xffff0000, v98
	v_fma_f32 v36, v36, v44, v42
	v_fma_f32 v37, v37, v45, v43
	v_lshlrev_b32_e32 v42, 16, v87
	v_and_b32_e32 v43, 0xffff0000, v87
	v_lshlrev_b32_e32 v44, 16, v99
	v_and_b32_e32 v45, 0xffff0000, v99
	v_fma_f32 v38, v38, v44, v42
	v_fma_f32 v39, v39, v45, v43
	v_cvt_pk_bf16_f32 v36, v36, v37
	v_cvt_pk_bf16_f32 v37, v38, v39
	v_lshlrev_b32_e32 v38, 16, v88
	v_and_b32_e32 v39, 0xffff0000, v88
	v_lshlrev_b32_e32 v42, 16, v100
	v_and_b32_e32 v43, 0xffff0000, v100
	v_fma_f32 v28, v28, v42, v38
	v_fma_f32 v29, v29, v43, v39
	v_lshlrev_b32_e32 v42, 16, v101
	v_cvt_pk_bf16_f32 v38, v28, v29
	v_lshlrev_b32_e32 v28, 16, v89
	v_and_b32_e32 v29, 0xffff0000, v89
	v_and_b32_e32 v43, 0xffff0000, v101
	v_fma_f32 v28, v30, v42, v28
	v_fma_f32 v29, v31, v43, v29
	s_waitcnt vmcnt(6)
; __device__ __forceinline__ unsigned cvt_pk_bf16(float lo, float hi) { f32x2 v = {lo, hi}; bf16x2_t b = __builtin_convertvector(v, bf16x2_t); return __builtin_bit_cast(unsigned, b); }
; __device__ __forceinline__ float bf_lo(unsigned u) { return __uint_as_float(u << 16); }
; __device__ __forceinline__ float bf_hi(unsigned u) { return __uint_as_float(u & 0xffff0000u); }
;     __device__ __forceinline__ void operator()(const f32x4 (&acc)[2][2][4][2], const Unit& u, int wr, int wc, int fr, int fq) const {
;     ...
;             for (int m = 0; m < 4; ++m)
; #pragma unroll
;                 for (int bj = 0; bj < 2; ++bj) { const size_t off = off0 + (size_t)(ai * HALF + m * 16) * 1024 + bj * HALF;
;                     const f32x4 v0 = acc[ai][bj][m][0], v1 = acc[ai][bj][m][1]; const u32x4 gg = g[m][bj], oo = o[m][bj]; u32x4 w;
;                     w.x = cvt_pk_bf16(bf_lo(oo.x) + bf_lo(gg.x) * v0[0], bf_hi(oo.x) + bf_hi(gg.x) * v0[1]);
;                     w.y = cvt_pk_bf16(bf_lo(oo.y) + bf_lo(gg.y) * v0[2], bf_hi(oo.y) + bf_hi(gg.y) * v0[3]);
;                     w.z = cvt_pk_bf16(bf_lo(oo.z) + bf_lo(gg.z) * v1[0], bf_hi(oo.z) + bf_hi(gg.z) * v1[1]);
;                     w.w = cvt_pk_bf16(bf_lo(oo.w) + bf_lo(gg.w) * v1[2], bf_hi(oo.w) + bf_hi(gg.w) * v1[3]);
;                     *(u32x4*)(Mg + off) = w; }
	v_lshlrev_b32_e32 v30, 16, v94
	v_cvt_pk_bf16_f32 v39, v28, v29
	v_lshlrev_b32_e32 v28, 16, v106
	v_and_b32_e32 v29, 0xffff0000, v106
	v_and_b32_e32 v31, 0xffff0000, v94
	v_fma_f32 v28, v32, v30, v28
	v_fma_f32 v29, v33, v31, v29
	v_lshlrev_b32_e32 v30, 16, v107
	v_and_b32_e32 v31, 0xffff0000, v107
	v_lshlrev_b32_e32 v32, 16, v95
	v_and_b32_e32 v33, 0xffff0000, v95
	v_fma_f32 v30, v34, v32, v30
	v_fma_f32 v31, v35, v33, v31
	v_cvt_pk_bf16_f32 v28, v28, v29
	v_cvt_pk_bf16_f32 v29, v30, v31
	v_lshlrev_b32_e32 v30, 16, v108
	v_and_b32_e32 v31, 0xffff0000, v108
	v_lshlrev_b32_e32 v32, 16, v96
	v_and_b32_e32 v33, 0xffff0000, v96
	v_fma_f32 v24, v24, v32, v30
	v_fma_f32 v25, v25, v33, v31
	v_lshlrev_b32_e32 v32, 16, v97
	v_cvt_pk_bf16_f32 v30, v24, v25
	v_lshlrev_b32_e32 v24, 16, v109
	v_and_b32_e32 v25, 0xffff0000, v109
	v_and_b32_e32 v33, 0xffff0000, v97
	v_fma_f32 v24, v26, v32, v24
	v_fma_f32 v25, v27, v33, v25
	s_waitcnt vmcnt(5)
	v_lshlrev_b32_e32 v26, 16, v74
	v_cvt_pk_bf16_f32 v31, v24, v25
	v_add_co_u32_e32 v24, vcc, s65, v208
	v_and_b32_e32 v27, 0xffff0000, v74
	s_nop 0
	v_addc_co_u32_e32 v25, vcc, 0, v209, vcc
	global_store_dwordx4 v[24:25], v[28:31], off
	global_store_dwordx4 v[40:41], v[36:39], off offset:256
	s_nop 0
	v_lshlrev_b32_e32 v28, 16, v82
	v_and_b32_e32 v29, 0xffff0000, v82
	v_fma_f32 v20, v20, v28, v26
	v_fma_f32 v21, v21, v29, v27
	v_lshlrev_b32_e32 v26, 16, v75
	v_and_b32_e32 v27, 0xffff0000, v75
	v_lshlrev_b32_e32 v28, 16, v83
	v_and_b32_e32 v29, 0xffff0000, v83
	v_fma_f32 v22, v22, v28, v26
	v_fma_f32 v23, v23, v29, v27
	v_cvt_pk_bf16_f32 v20, v20, v21
	v_cvt_pk_bf16_f32 v21, v22, v23
	v_lshlrev_b32_e32 v22, 16, v76
	v_and_b32_e32 v23, 0xffff0000, v76
	v_lshlrev_b32_e32 v26, 16, v84
	v_and_b32_e32 v27, 0xffff0000, v84
	v_fma_f32 v12, v12, v26, v22
	v_fma_f32 v13, v13, v27, v23
	v_lshlrev_b32_e32 v26, 16, v85
	v_cvt_pk_bf16_f32 v22, v12, v13
	v_lshlrev_b32_e32 v12, 16, v77
	v_and_b32_e32 v13, 0xffff0000, v77
	v_and_b32_e32 v27, 0xffff0000, v85
	v_fma_f32 v12, v14, v26, v12
	v_fma_f32 v13, v15, v27, v13
	s_waitcnt vmcnt(6)
	v_lshlrev_b32_e32 v14, 16, v78
	v_cvt_pk_bf16_f32 v23, v12, v13
	v_lshlrev_b32_e32 v12, 16, v90
	v_and_b32_e32 v13, 0xffff0000, v90
	v_and_b32_e32 v15, 0xffff0000, v78
	v_fma_f32 v12, v16, v14, v12
	v_fma_f32 v13, v17, v15, v13
	v_lshlrev_b32_e32 v14, 16, v91
	v_and_b32_e32 v15, 0xffff0000, v91
	v_lshlrev_b32_e32 v16, 16, v79
	v_and_b32_e32 v17, 0xffff0000, v79
	v_fma_f32 v14, v18, v16, v14
	v_fma_f32 v15, v19, v17, v15
	v_cvt_pk_bf16_f32 v12, v12, v13
	v_cvt_pk_bf16_f32 v13, v14, v15
	v_lshlrev_b32_e32 v14, 16, v92
	v_and_b32_e32 v15, 0xffff0000, v92
	v_lshlrev_b32_e32 v16, 16, v80
	v_and_b32_e32 v17, 0xffff0000, v80
	v_fma_f32 v8, v8, v16, v14
	v_fma_f32 v9, v9, v17, v15
	v_lshlrev_b32_e32 v16, 16, v81
	v_cvt_pk_bf16_f32 v14, v8, v9
	v_lshlrev_b32_e32 v8, 16, v93
	v_and_b32_e32 v9, 0xffff0000, v93
	v_and_b32_e32 v17, 0xffff0000, v81
	v_fma_f32 v8, v10, v16, v8
	v_fma_f32 v9, v11, v17, v9
	s_waitcnt vmcnt(5)
	v_lshlrev_b32_e32 v10, 16, v66
	v_cvt_pk_bf16_f32 v15, v8, v9
	v_add_co_u32_e32 v8, vcc, s66, v208
	v_and_b32_e32 v11, 0xffff0000, v66
	s_nop 0
	v_addc_co_u32_e32 v9, vcc, 0, v209, vcc
	global_store_dwordx4 v[8:9], v[12:15], off
	global_store_dwordx4 v[24:25], v[20:23], off offset:256
	s_nop 0
	v_lshlrev_b32_e32 v12, 16, v70
	v_and_b32_e32 v13, 0xffff0000, v70
	v_fma_f32 v4, v4, v12, v10
	v_fma_f32 v5, v5, v13, v11
	v_lshlrev_b32_e32 v10, 16, v67
	v_and_b32_e32 v11, 0xffff0000, v67
	v_lshlrev_b32_e32 v12, 16, v71
	v_and_b32_e32 v13, 0xffff0000, v71
	v_fma_f32 v6, v6, v12, v10
	v_fma_f32 v7, v7, v13, v11
	v_cvt_pk_bf16_f32 v4, v4, v5
	v_cvt_pk_bf16_f32 v5, v6, v7
	v_lshlrev_b32_e32 v6, 16, v68
	v_and_b32_e32 v7, 0xffff0000, v68
	v_lshlrev_b32_e32 v10, 16, v72
	v_and_b32_e32 v11, 0xffff0000, v72
	v_fma_f32 v0, v0, v10, v6
	v_fma_f32 v1, v1, v11, v7
	v_lshlrev_b32_e32 v10, 16, v73
	v_cvt_pk_bf16_f32 v6, v0, v1
	v_lshlrev_b32_e32 v0, 16, v69
	v_and_b32_e32 v1, 0xffff0000, v69
	v_and_b32_e32 v11, 0xffff0000, v73
	v_fma_f32 v0, v2, v10, v0
	v_fma_f32 v1, v3, v11, v1
	s_nop 0
	v_cvt_pk_bf16_f32 v7, v0, v1
	global_store_dwordx4 v[8:9], v[4:7], off offset:256
	s_cbranch_scc1 .LBB0_486
	s_andn2_b64 vcc, exec, s[10:11]
	s_cbranch_vccnz .LBB0_485
	s_barrier
	s_branch .LBB0_485

; __device__ __forceinline__ float bflo(unsigned u) { return __uint_as_float(u << 16); }
; __device__ __forceinline__ float bfhi(unsigned u) { return __uint_as_float(u & 0xffff0000u); }
; __device__ __forceinline__ void ln_panel(int pm, const float* resf, const bf16* rlo, const bf16* dlt, float* xo, const float* gam, const float* bet, bf16* xb, bf16* wlo, bool fin, float alpha) {
;     ...
;         for (int j = 0; j < 4; ++j) { f32x4 x; const u32x2 d = *(const u32x2*)(dlt + prow + 256 * j);
;             if (resf) x = *(const f32x4*)(resf + grow + 256 * j);
;             else { const u32x2 h = *(const u32x2*)(xb + grow + 256 * j), l = *(const u32x2*)(rlo + prow + 256 * j);
;                    x = (f32x4){bflo(h.x) + bflo(l.x), bfhi(h.x) + bfhi(l.x), bflo(h.y) + bflo(l.y), bfhi(h.y) + bfhi(l.y)}; }
;             v[j] = (f32x4){x.x * alpha + bflo(d.x), x.y * alpha + bfhi(d.x), x.z * alpha + bflo(d.y), x.w * alpha + bfhi(d.y)}; s += (v[j].x + v[j].y) + (v[j].z + v[j].w); }
;         const float mean = wave_sum(s) * (1.f / DM); float s2 = 0.f;
; #pragma unroll
;         for (int j = 0; j < 4; ++j) { v[j] = v[j] - mean; s2 += (v[j].x * v[j].x + v[j].y * v[j].y) + (v[j].z * v[j].z + v[j].w * v[j].w); }
;         const float rstd = 1.f / sqrtf(wave_sum(s2) * (1.f / DM) + LN_EPS);
.Lmy_ln1h_entry:
	v_lshlrev_b32_e32 v150, 16, v66
	v_and_b32_e32 v151, 0xffff0000, v66
	v_lshlrev_b32_e32 v152, 16, v74
	v_and_b32_e32 v153, 0xffff0000, v74
	v_add_f32_e32 v150, v150, v152
	v_add_f32_e32 v151, v151, v153
	v_lshlrev_b32_e32 v152, 16, v82
	v_and_b32_e32 v153, 0xffff0000, v82
	v_fma_f32 v114, v150, v164, v152
	v_fma_f32 v115, v151, v165, v153
	v_lshlrev_b32_e32 v150, 16, v67
	v_and_b32_e32 v151, 0xffff0000, v67
	v_lshlrev_b32_e32 v152, 16, v75
	v_and_b32_e32 v153, 0xffff0000, v75
	v_add_f32_e32 v150, v150, v152
	v_add_f32_e32 v151, v151, v153
	v_lshlrev_b32_e32 v152, 16, v83
	v_and_b32_e32 v153, 0xffff0000, v83
	v_fma_f32 v116, v150, v164, v152
	v_fma_f32 v117, v151, v165, v153
	v_lshlrev_b32_e32 v150, 16, v68
	v_and_b32_e32 v151, 0xffff0000, v68
	v_lshlrev_b32_e32 v152, 16, v76
	v_and_b32_e32 v153, 0xffff0000, v76
	v_add_f32_e32 v150, v150, v152
	v_add_f32_e32 v151, v151, v153
	v_lshlrev_b32_e32 v152, 16, v84
	v_and_b32_e32 v153, 0xffff0000, v84
	v_fma_f32 v118, v150, v164, v152
	v_fma_f32 v119, v151, v165, v153
	v_lshlrev_b32_e32 v150, 16, v69
	v_and_b32_e32 v151, 0xffff0000, v69
	v_lshlrev_b32_e32 v152, 16, v77
	v_and_b32_e32 v153, 0xffff0000, v77
	v_add_f32_e32 v150, v150, v152
	v_add_f32_e32 v151, v151, v153
	v_lshlrev_b32_e32 v152, 16, v85
	v_and_b32_e32 v153, 0xffff0000, v85
	v_fma_f32 v120, v150, v164, v152
	v_fma_f32 v121, v151, v165, v153
	v_lshlrev_b32_e32 v150, 16, v70
	v_and_b32_e32 v151, 0xffff0000, v70
	v_lshlrev_b32_e32 v152, 16, v78
	v_and_b32_e32 v153, 0xffff0000, v78
	v_add_f32_e32 v150, v150, v152
	v_add_f32_e32 v151, v151, v153
	v_lshlrev_b32_e32 v152, 16, v86
	v_and_b32_e32 v153, 0xffff0000, v86
	v_fma_f32 v122, v150, v164, v152
	v_fma_f32 v123, v151, v165, v153
	v_lshlrev_b32_e32 v150, 16, v71
	v_and_b32_e32 v151, 0xffff0000, v71
	v_lshlrev_b32_e32 v152, 16, v79
	v_and_b32_e32 v153, 0xffff0000, v79
	v_add_f32_e32 v150, v150, v152
	v_add_f32_e32 v151, v151, v153
	v_lshlrev_b32_e32 v152, 16, v87
	v_and_b32_e32 v153, 0xffff0000, v87
	v_fma_f32 v124, v150, v164, v152
	v_fma_f32 v125, v151, v165, v153
	v_lshlrev_b32_e32 v150, 16, v72
	v_and_b32_e32 v151, 0xffff0000, v72
	v_lshlrev_b32_e32 v152, 16, v80
	v_and_b32_e32 v153, 0xffff0000, v80
	v_add_f32_e32 v150, v150, v152
	v_add_f32_e32 v151, v151, v153
	v_lshlrev_b32_e32 v152, 16, v88
	v_and_b32_e32 v153, 0xffff0000, v88
	v_fma_f32 v126, v150, v164, v152
	v_fma_f32 v127, v151, v165, v153
	v_lshlrev_b32_e32 v150, 16, v73
	v_and_b32_e32 v151, 0xffff0000, v73
	v_lshlrev_b32_e32 v152, 16, v81
	v_and_b32_e32 v153, 0xffff0000, v81
	v_add_f32_e32 v150, v150, v152
	v_add_f32_e32 v151, v151, v153
	v_lshlrev_b32_e32 v152, 16, v89
	v_and_b32_e32 v153, 0xffff0000, v89
	v_fma_f32 v128, v150, v164, v152
	v_fma_f32 v129, v151, v165, v153
	v_add_f32_e32 v154, v114, v116
	v_add_f32_e32 v155, v115, v117
	v_add_f32_e32 v156, v118, v120
	v_add_f32_e32 v157, v119, v121
	v_add_f32_e32 v154, v154, v156
	v_add_f32_e32 v155, v155, v157
	v_add_f32_e32 v156, v122, v124
	v_add_f32_e32 v157, v123, v125
	v_add_f32_e32 v154, v154, v156
	v_add_f32_e32 v155, v155, v157
	v_add_f32_e32 v156, v126, v128
	v_add_f32_e32 v157, v127, v129
	v_add_f32_e32 v154, v154, v156
	v_add_f32_e32 v155, v155, v157
	v_add_f32_e32 v154, v154, v155
	s_nop 1
	v_add_f32_dpp v160, v154, v154 quad_perm:[1,0,3,2] row_mask:0xf bank_mask:0xf
	s_nop 1
	v_add_f32_dpp v160, v160, v160 quad_perm:[2,3,0,1] row_mask:0xf bank_mask:0xf
	s_nop 1
	v_add_f32_dpp v160, v160, v160 row_half_mirror row_mask:0xf bank_mask:0xf
	s_nop 1
	v_add_f32_dpp v160, v160, v160 row_mirror row_mask:0xf bank_mask:0xf
	s_nop 1
	v_add_f32_dpp v160, v160, v160 row_bcast:15 row_mask:0xa bank_mask:0xf
	s_nop 1
	v_add_f32_dpp v160, v160, v160 row_bcast:31 row_mask:0xc bank_mask:0xf
	s_nop 1
	v_readlane_b32 s0, v160, 63
	s_nop 2
	v_mov_b32_e32 v170, s0
	v_mul_f32_e32 v156, 0xba800000, v170
	v_mul_f32_e32 v157, 0xba800000, v170
	v_add_f32_e32 v114, v114, v156
	v_add_f32_e32 v115, v115, v157
	v_add_f32_e32 v116, v116, v156
	v_add_f32_e32 v117, v117, v157
	v_add_f32_e32 v118, v118, v156
	v_add_f32_e32 v119, v119, v157
	v_add_f32_e32 v120, v120, v156
	v_add_f32_e32 v121, v121, v157
	v_add_f32_e32 v122, v122, v156
	v_add_f32_e32 v123, v123, v157
	v_add_f32_e32 v124, v124, v156
	v_add_f32_e32 v125, v125, v157
	v_add_f32_e32 v126, v126, v156
	v_add_f32_e32 v127, v127, v157
	v_add_f32_e32 v128, v128, v156
	v_add_f32_e32 v129, v129, v157
	v_mul_f32_e32 v154, v114, v114
	v_mul_f32_e32 v155, v115, v115
	v_fma_f32 v154, v116, v116, v154
	v_fma_f32 v155, v117, v117, v155
	v_fma_f32 v154, v118, v118, v154
	v_fma_f32 v155, v119, v119, v155
	v_fma_f32 v154, v120, v120, v154
	v_fma_f32 v155, v121, v121, v155
	v_fma_f32 v154, v122, v122, v154
	v_fma_f32 v155, v123, v123, v155
	v_fma_f32 v154, v124, v124, v154
	v_fma_f32 v155, v125, v125, v155
	v_fma_f32 v154, v126, v126, v154
	v_fma_f32 v155, v127, v127, v155
	v_fma_f32 v154, v128, v128, v154
	v_fma_f32 v155, v129, v129, v155
	v_add_f32_e32 v154, v154, v155
	s_nop 1
	v_add_f32_dpp v160, v154, v154 quad_perm:[1,0,3,2] row_mask:0xf bank_mask:0xf
	s_nop 1
	v_add_f32_dpp v160, v160, v160 quad_perm:[2,3,0,1] row_mask:0xf bank_mask:0xf
	s_nop 1
	v_add_f32_dpp v160, v160, v160 row_half_mirror row_mask:0xf bank_mask:0xf
	s_nop 1
	v_add_f32_dpp v160, v160, v160 row_mirror row_mask:0xf bank_mask:0xf
	s_nop 1
	v_add_f32_dpp v160, v160, v160 row_bcast:15 row_mask:0xa bank_mask:0xf
	s_nop 1
	v_add_f32_dpp v160, v160, v160 row_bcast:31 row_mask:0xc bank_mask:0xf
	s_nop 1
	v_readlane_b32 s0, v160, 63
	s_nop 2
	v_mov_b32_e32 v170, s0
	v_fmamk_f32 v154, v170, 0x3a800000, v166
	s_mov_b32 s0, 0xf800000
	v_mul_f32_e32 v155, 0x4f800000, v154
; __device__ __forceinline__ unsigned pk2(float lo, float hi) { return pg8::cvt_pk_bf16(lo, hi); }
; __device__ __forceinline__ float bflo(unsigned u) { return __uint_as_float(u << 16); }
; __device__ __forceinline__ float bfhi(unsigned u) { return __uint_as_float(u & 0xffff0000u); }
; __device__ __forceinline__ void ln_panel(int pm, const float* resf, const bf16* rlo, const bf16* dlt, float* xo, const float* gam, const float* bet, bf16* xb, bf16* wlo, bool fin, float alpha) {
;     ...
;         const float rstd = 1.f / sqrtf(wave_sum(s2) * (1.f / DM) + LN_EPS);
; #pragma unroll
;         for (int j = 0; j < 4; ++j) { const f32x4 o = v[j] * rstd * gv[j] + bv[j];
;             if (fin) *(f32x4*)(xo + grow + 256 * j) = o;
;             else { u32x2 w; w.x = pk2(o.x, o.y); w.y = pk2(o.z, o.w); *(u32x2*)(xb + grow + 256 * j) = w;
;                    u32x2 q; q.x = pk2(o.x - bflo(w.x), o.y - bfhi(w.x)); q.y = pk2(o.z - bflo(w.y), o.w - bfhi(w.y)); *(u32x2*)(wlo + prow + 256 * j) = q; } }
	v_cmp_gt_f32_e32 vcc, s0, v154
	s_nop 1
	v_cndmask_b32_e32 v154, v154, v155, vcc
	v_sqrt_f32_e32 v155, v154
	s_nop 0
	v_add_u32_e32 v156, -1, v155
	v_fma_f32 v157, -v156, v155, v154
	v_cmp_ge_f32_e64 s[0:1], 0, v157
	v_add_u32_e32 v157, 1, v155
	s_nop 0
	v_cndmask_b32_e64 v156, v155, v156, s[0:1]
	v_fma_f32 v155, -v157, v155, v154
	v_cmp_lt_f32_e64 s[0:1], 0, v155
	s_nop 1
	v_cndmask_b32_e64 v155, v156, v157, s[0:1]
	v_mul_f32_e32 v156, 0x37800000, v155
	v_cndmask_b32_e32 v155, v155, v156, vcc
	v_cmp_class_f32_e32 vcc, v154, v167
	s_nop 1
	v_cndmask_b32_e32 v154, v155, v154, vcc
	v_div_scale_f32 v155, s[0:1], v154, v154, 1.0
	v_rcp_f32_e32 v156, v155
	s_nop 0
	v_fma_f32 v157, -v155, v156, 1.0
	v_fmac_f32_e32 v156, v157, v156
	v_div_scale_f32 v157, vcc, 1.0, v154, 1.0
	v_mul_f32_e32 v158, v157, v156
	v_fma_f32 v159, -v155, v158, v157
	v_fmac_f32_e32 v158, v159, v156
	v_fma_f32 v155, -v155, v158, v157
	s_nop 0
	v_div_fmas_f32 v155, v155, v156, v158
	v_div_fixup_f32 v168, v155, v154, 1.0
	s_add_i32 s0, s98, 0
	s_lshl_b32 s0, s0, 11
	s_mov_b32 s1, 0
	v_lshl_add_u64 v[184:185], s[0:1], 0, v[172:173]
	v_lshl_add_u64 v[186:187], s[0:1], 0, v[180:181]
	v_mul_f32_e32 v150, v114, v168
	v_mul_f32_e32 v151, v115, v168
	v_fma_f32 v150, v0, v150, v8
	v_fma_f32 v151, v1, v151, v9
	v_mul_f32_e32 v152, v116, v168
	v_mul_f32_e32 v153, v117, v168
	v_fma_f32 v152, v2, v152, v10
	v_fma_f32 v153, v3, v153, v11
	v_cvt_pk_bf16_f32 v190, v150, v151
	v_cvt_pk_bf16_f32 v191, v152, v153
	v_lshlrev_b32_e32 v154, 16, v190
	v_and_b32_e32 v155, 0xffff0000, v190
	v_sub_f32_e32 v150, v150, v154
	v_sub_f32_e32 v151, v151, v155
	v_cvt_pk_bf16_f32 v198, v150, v151
	v_lshlrev_b32_e32 v154, 16, v191
	v_and_b32_e32 v155, 0xffff0000, v191
	v_sub_f32_e32 v152, v152, v154
	v_sub_f32_e32 v153, v153, v155
	v_cvt_pk_bf16_f32 v199, v152, v153
	v_mul_f32_e32 v150, v118, v168
	v_mul_f32_e32 v151, v119, v168
	v_fma_f32 v150, v4, v150, v12
	v_fma_f32 v151, v5, v151, v13
	v_mul_f32_e32 v152, v120, v168
	v_mul_f32_e32 v153, v121, v168
	v_fma_f32 v152, v6, v152, v14
	v_fma_f32 v153, v7, v153, v15
	v_cvt_pk_bf16_f32 v192, v150, v151
	v_cvt_pk_bf16_f32 v193, v152, v153
	v_lshlrev_b32_e32 v154, 16, v192
	v_and_b32_e32 v155, 0xffff0000, v192
	v_sub_f32_e32 v150, v150, v154
	v_sub_f32_e32 v151, v151, v155
	v_cvt_pk_bf16_f32 v200, v150, v151
	v_lshlrev_b32_e32 v154, 16, v193
	v_and_b32_e32 v155, 0xffff0000, v193
	v_sub_f32_e32 v152, v152, v154
	v_sub_f32_e32 v153, v153, v155
	v_cvt_pk_bf16_f32 v201, v152, v153
	v_mul_f32_e32 v150, v122, v168
	v_mul_f32_e32 v151, v123, v168
	v_fma_f32 v150, v16, v150, v24
	v_fma_f32 v151, v17, v151, v25
	v_mul_f32_e32 v152, v124, v168
	v_mul_f32_e32 v153, v125, v168
	v_fma_f32 v152, v18, v152, v26
	v_fma_f32 v153, v19, v153, v27
	v_cvt_pk_bf16_f32 v194, v150, v151
	v_cvt_pk_bf16_f32 v195, v152, v153
	v_lshlrev_b32_e32 v154, 16, v194
	v_and_b32_e32 v155, 0xffff0000, v194
	v_sub_f32_e32 v150, v150, v154
	v_sub_f32_e32 v151, v151, v155
	v_cvt_pk_bf16_f32 v202, v150, v151
	v_lshlrev_b32_e32 v154, 16, v195
	v_and_b32_e32 v155, 0xffff0000, v195
	v_sub_f32_e32 v152, v152, v154
	v_sub_f32_e32 v153, v153, v155
	v_cvt_pk_bf16_f32 v203, v152, v153
	v_mul_f32_e32 v150, v126, v168
	v_mul_f32_e32 v151, v127, v168
	v_fma_f32 v150, v20, v150, v28
	v_fma_f32 v151, v21, v151, v29
	v_mul_f32_e32 v152, v128, v168
	v_mul_f32_e32 v153, v129, v168
	v_fma_f32 v152, v22, v152, v30
	v_fma_f32 v153, v23, v153, v31
	v_cvt_pk_bf16_f32 v196, v150, v151
	v_cvt_pk_bf16_f32 v197, v152, v153
	v_lshlrev_b32_e32 v154, 16, v196
	v_and_b32_e32 v155, 0xffff0000, v196
	v_sub_f32_e32 v150, v150, v154
	v_sub_f32_e32 v151, v151, v155
	v_cvt_pk_bf16_f32 v204, v150, v151
	v_lshlrev_b32_e32 v154, 16, v197
	v_and_b32_e32 v155, 0xffff0000, v197
	v_sub_f32_e32 v152, v152, v154
	v_sub_f32_e32 v153, v153, v155
	v_cvt_pk_bf16_f32 v205, v152, v153
	global_store_dwordx2 v[184:185], v[190:191], off offset:0
	global_store_dwordx2 v[184:185], v[192:193], off offset:512
	global_store_dwordx2 v[184:185], v[194:195], off offset:1024
	global_store_dwordx2 v[184:185], v[196:197], off offset:1536
	global_store_dwordx2 v[186:187], v[198:199], off offset:0
	global_store_dwordx2 v[186:187], v[200:201], off offset:512
	global_store_dwordx2 v[186:187], v[202:203], off offset:1024
	global_store_dwordx2 v[186:187], v[204:205], off offset:1536
	s_add_i32 s0, s98, 2
	s_min_u32 s0, s0, 31
	s_lshl_b32 s0, s0, 11
	s_mov_b32 s1, 0
	v_lshl_add_u64 v[184:185], s[0:1], 0, v[178:179]
	v_lshl_add_u64 v[186:187], s[0:1], 0, v[172:173]
	v_lshl_add_u64 v[188:189], s[0:1], 0, v[176:177]
	global_load_dwordx2 v[82:83], v[184:185], off offset:-1024
	global_load_dwordx2 v[84:85], v[184:185], off offset:-512
	global_load_dwordx2 v[86:87], v[184:185], off offset:0
	global_load_dwordx2 v[88:89], v[184:185], off offset:512
	global_load_dwordx2 v[66:67], v[186:187], off offset:0
	global_load_dwordx2 v[68:69], v[186:187], off offset:512
	global_load_dwordx2 v[70:71], v[186:187], off offset:1024
	global_load_dwordx2 v[72:73], v[186:187], off offset:1536
	global_load_dwordx2 v[74:75], v[188:189], off offset:0
	global_load_dwordx2 v[76:77], v[188:189], off offset:512
	global_load_dwordx2 v[78:79], v[188:189], off offset:1024
	global_load_dwordx2 v[80:81], v[188:189], off offset:1536
	s_waitcnt vmcnt(20)
; __device__ __forceinline__ float bflo(unsigned u) { return __uint_as_float(u << 16); }
; __device__ __forceinline__ float bfhi(unsigned u) { return __uint_as_float(u & 0xffff0000u); }
; __device__ __forceinline__ void ln_panel(int pm, const float* resf, const bf16* rlo, const bf16* dlt, float* xo, const float* gam, const float* bet, bf16* xb, bf16* wlo, bool fin, float alpha) {
;     ...
;         for (int j = 0; j < 4; ++j) { f32x4 x; const u32x2 d = *(const u32x2*)(dlt + prow + 256 * j);
;             if (resf) x = *(const f32x4*)(resf + grow + 256 * j);
;             else { const u32x2 h = *(const u32x2*)(xb + grow + 256 * j), l = *(const u32x2*)(rlo + prow + 256 * j);
;                    x = (f32x4){bflo(h.x) + bflo(l.x), bfhi(h.x) + bfhi(l.x), bflo(h.y) + bflo(l.y), bfhi(h.y) + bfhi(l.y)}; }
;             v[j] = (f32x4){x.x * alpha + bflo(d.x), x.y * alpha + bfhi(d.x), x.z * alpha + bflo(d.y), x.w * alpha + bfhi(d.y)}; s += (v[j].x + v[j].y) + (v[j].z + v[j].w); }
;         const float mean = wave_sum(s) * (1.f / DM); float s2 = 0.f;
; #pragma unroll
;         for (int j = 0; j < 4; ++j) { v[j] = v[j] - mean; s2 += (v[j].x * v[j].x + v[j].y * v[j].y) + (v[j].z * v[j].z + v[j].w * v[j].w); }
;         const float rstd = 1.f / sqrtf(wave_sum(s2) * (1.f / DM) + LN_EPS);
	v_lshlrev_b32_e32 v150, 16, v90
	v_and_b32_e32 v151, 0xffff0000, v90
	v_lshlrev_b32_e32 v152, 16, v98
	v_and_b32_e32 v153, 0xffff0000, v98
	v_add_f32_e32 v150, v150, v152
	v_add_f32_e32 v151, v151, v153
	v_lshlrev_b32_e32 v152, 16, v106
	v_and_b32_e32 v153, 0xffff0000, v106
	v_fma_f32 v114, v150, v164, v152
	v_fma_f32 v115, v151, v165, v153
	v_lshlrev_b32_e32 v150, 16, v91
	v_and_b32_e32 v151, 0xffff0000, v91
	v_lshlrev_b32_e32 v152, 16, v99
	v_and_b32_e32 v153, 0xffff0000, v99
	v_add_f32_e32 v150, v150, v152
	v_add_f32_e32 v151, v151, v153
	v_lshlrev_b32_e32 v152, 16, v107
	v_and_b32_e32 v153, 0xffff0000, v107
	v_fma_f32 v116, v150, v164, v152
	v_fma_f32 v117, v151, v165, v153
	v_lshlrev_b32_e32 v150, 16, v92
	v_and_b32_e32 v151, 0xffff0000, v92
	v_lshlrev_b32_e32 v152, 16, v100
	v_and_b32_e32 v153, 0xffff0000, v100
	v_add_f32_e32 v150, v150, v152
	v_add_f32_e32 v151, v151, v153
	v_lshlrev_b32_e32 v152, 16, v108
	v_and_b32_e32 v153, 0xffff0000, v108
	v_fma_f32 v118, v150, v164, v152
	v_fma_f32 v119, v151, v165, v153
	v_lshlrev_b32_e32 v150, 16, v93
	v_and_b32_e32 v151, 0xffff0000, v93
	v_lshlrev_b32_e32 v152, 16, v101
	v_and_b32_e32 v153, 0xffff0000, v101
	v_add_f32_e32 v150, v150, v152
	v_add_f32_e32 v151, v151, v153
	v_lshlrev_b32_e32 v152, 16, v109
	v_and_b32_e32 v153, 0xffff0000, v109
	v_fma_f32 v120, v150, v164, v152
	v_fma_f32 v121, v151, v165, v153
	v_lshlrev_b32_e32 v150, 16, v94
	v_and_b32_e32 v151, 0xffff0000, v94
	v_lshlrev_b32_e32 v152, 16, v102
	v_and_b32_e32 v153, 0xffff0000, v102
	v_add_f32_e32 v150, v150, v152
	v_add_f32_e32 v151, v151, v153
	v_lshlrev_b32_e32 v152, 16, v110
	v_and_b32_e32 v153, 0xffff0000, v110
	v_fma_f32 v122, v150, v164, v152
	v_fma_f32 v123, v151, v165, v153
	v_lshlrev_b32_e32 v150, 16, v95
	v_and_b32_e32 v151, 0xffff0000, v95
	v_lshlrev_b32_e32 v152, 16, v103
	v_and_b32_e32 v153, 0xffff0000, v103
	v_add_f32_e32 v150, v150, v152
	v_add_f32_e32 v151, v151, v153
	v_lshlrev_b32_e32 v152, 16, v111
	v_and_b32_e32 v153, 0xffff0000, v111
	v_fma_f32 v124, v150, v164, v152
	v_fma_f32 v125, v151, v165, v153
	v_lshlrev_b32_e32 v150, 16, v96
	v_and_b32_e32 v151, 0xffff0000, v96
	v_lshlrev_b32_e32 v152, 16, v104
	v_and_b32_e32 v153, 0xffff0000, v104
	v_add_f32_e32 v150, v150, v152
	v_add_f32_e32 v151, v151, v153
	v_lshlrev_b32_e32 v152, 16, v112
	v_and_b32_e32 v153, 0xffff0000, v112
	v_fma_f32 v126, v150, v164, v152
	v_fma_f32 v127, v151, v165, v153
	v_lshlrev_b32_e32 v150, 16, v97
	v_and_b32_e32 v151, 0xffff0000, v97
	v_lshlrev_b32_e32 v152, 16, v105
	v_and_b32_e32 v153, 0xffff0000, v105
	v_add_f32_e32 v150, v150, v152
	v_add_f32_e32 v151, v151, v153
	v_lshlrev_b32_e32 v152, 16, v113
	v_and_b32_e32 v153, 0xffff0000, v113
	v_fma_f32 v128, v150, v164, v152
	v_fma_f32 v129, v151, v165, v153
	v_add_f32_e32 v154, v114, v116
	v_add_f32_e32 v155, v115, v117
	v_add_f32_e32 v156, v118, v120
	v_add_f32_e32 v157, v119, v121
	v_add_f32_e32 v154, v154, v156
	v_add_f32_e32 v155, v155, v157
	v_add_f32_e32 v156, v122, v124
	v_add_f32_e32 v157, v123, v125
	v_add_f32_e32 v154, v154, v156
	v_add_f32_e32 v155, v155, v157
	v_add_f32_e32 v156, v126, v128
	v_add_f32_e32 v157, v127, v129
	v_add_f32_e32 v154, v154, v156
	v_add_f32_e32 v155, v155, v157
	v_add_f32_e32 v154, v154, v155
	s_nop 1
	v_add_f32_dpp v160, v154, v154 quad_perm:[1,0,3,2] row_mask:0xf bank_mask:0xf
	s_nop 1
	v_add_f32_dpp v160, v160, v160 quad_perm:[2,3,0,1] row_mask:0xf bank_mask:0xf
	s_nop 1
	v_add_f32_dpp v160, v160, v160 row_half_mirror row_mask:0xf bank_mask:0xf
	s_nop 1
	v_add_f32_dpp v160, v160, v160 row_mirror row_mask:0xf bank_mask:0xf
	s_nop 1
	v_add_f32_dpp v160, v160, v160 row_bcast:15 row_mask:0xa bank_mask:0xf
	s_nop 1
	v_add_f32_dpp v160, v160, v160 row_bcast:31 row_mask:0xc bank_mask:0xf
	s_nop 1
	v_readlane_b32 s0, v160, 63
	s_nop 2
	v_mov_b32_e32 v170, s0
	v_mul_f32_e32 v156, 0xba800000, v170
	v_mul_f32_e32 v157, 0xba800000, v170
	v_add_f32_e32 v114, v114, v156
	v_add_f32_e32 v115, v115, v157
	v_add_f32_e32 v116, v116, v156
	v_add_f32_e32 v117, v117, v157
	v_add_f32_e32 v118, v118, v156
	v_add_f32_e32 v119, v119, v157
	v_add_f32_e32 v120, v120, v156
	v_add_f32_e32 v121, v121, v157
	v_add_f32_e32 v122, v122, v156
	v_add_f32_e32 v123, v123, v157
	v_add_f32_e32 v124, v124, v156
	v_add_f32_e32 v125, v125, v157
	v_add_f32_e32 v126, v126, v156
	v_add_f32_e32 v127, v127, v157
	v_add_f32_e32 v128, v128, v156
	v_add_f32_e32 v129, v129, v157
	v_mul_f32_e32 v154, v114, v114
	v_mul_f32_e32 v155, v115, v115
	v_fma_f32 v154, v116, v116, v154
	v_fma_f32 v155, v117, v117, v155
	v_fma_f32 v154, v118, v118, v154
	v_fma_f32 v155, v119, v119, v155
	v_fma_f32 v154, v120, v120, v154
	v_fma_f32 v155, v121, v121, v155
	v_fma_f32 v154, v122, v122, v154
	v_fma_f32 v155, v123, v123, v155
	v_fma_f32 v154, v124, v124, v154
	v_fma_f32 v155, v125, v125, v155
	v_fma_f32 v154, v126, v126, v154
	v_fma_f32 v155, v127, v127, v155
	v_fma_f32 v154, v128, v128, v154
	v_fma_f32 v155, v129, v129, v155
	v_add_f32_e32 v154, v154, v155
	s_nop 1
	v_add_f32_dpp v160, v154, v154 quad_perm:[1,0,3,2] row_mask:0xf bank_mask:0xf
	s_nop 1
	v_add_f32_dpp v160, v160, v160 quad_perm:[2,3,0,1] row_mask:0xf bank_mask:0xf
	s_nop 1
	v_add_f32_dpp v160, v160, v160 row_half_mirror row_mask:0xf bank_mask:0xf
	s_nop 1
	v_add_f32_dpp v160, v160, v160 row_mirror row_mask:0xf bank_mask:0xf
	s_nop 1
	v_add_f32_dpp v160, v160, v160 row_bcast:15 row_mask:0xa bank_mask:0xf
	s_nop 1
	v_add_f32_dpp v160, v160, v160 row_bcast:31 row_mask:0xc bank_mask:0xf
	s_nop 1
	v_readlane_b32 s0, v160, 63
	s_nop 2
; __device__ __forceinline__ unsigned pk2(float lo, float hi) { return pg8::cvt_pk_bf16(lo, hi); }
; __device__ __forceinline__ float bflo(unsigned u) { return __uint_as_float(u << 16); }
; __device__ __forceinline__ float bfhi(unsigned u) { return __uint_as_float(u & 0xffff0000u); }
; __device__ __forceinline__ void ln_panel(int pm, const float* resf, const bf16* rlo, const bf16* dlt, float* xo, const float* gam, const float* bet, bf16* xb, bf16* wlo, bool fin, float alpha) {
;     ...
;         const float rstd = 1.f / sqrtf(wave_sum(s2) * (1.f / DM) + LN_EPS);
; #pragma unroll
;         for (int j = 0; j < 4; ++j) { const f32x4 o = v[j] * rstd * gv[j] + bv[j];
;             if (fin) *(f32x4*)(xo + grow + 256 * j) = o;
;             else { u32x2 w; w.x = pk2(o.x, o.y); w.y = pk2(o.z, o.w); *(u32x2*)(xb + grow + 256 * j) = w;
;                    u32x2 q; q.x = pk2(o.x - bflo(w.x), o.y - bfhi(w.x)); q.y = pk2(o.z - bflo(w.y), o.w - bfhi(w.y)); *(u32x2*)(wlo + prow + 256 * j) = q; } }
	v_mov_b32_e32 v170, s0
	v_fmamk_f32 v154, v170, 0x3a800000, v166
	s_mov_b32 s0, 0xf800000
	v_mul_f32_e32 v155, 0x4f800000, v154
	v_cmp_gt_f32_e32 vcc, s0, v154
	s_nop 1
	v_cndmask_b32_e32 v154, v154, v155, vcc
	v_sqrt_f32_e32 v155, v154
	s_nop 0
	v_add_u32_e32 v156, -1, v155
	v_fma_f32 v157, -v156, v155, v154
	v_cmp_ge_f32_e64 s[0:1], 0, v157
	v_add_u32_e32 v157, 1, v155
	s_nop 0
	v_cndmask_b32_e64 v156, v155, v156, s[0:1]
	v_fma_f32 v155, -v157, v155, v154
	v_cmp_lt_f32_e64 s[0:1], 0, v155
	s_nop 1
	v_cndmask_b32_e64 v155, v156, v157, s[0:1]
	v_mul_f32_e32 v156, 0x37800000, v155
	v_cndmask_b32_e32 v155, v155, v156, vcc
	v_cmp_class_f32_e32 vcc, v154, v167
	s_nop 1
	v_cndmask_b32_e32 v154, v155, v154, vcc
	v_div_scale_f32 v155, s[0:1], v154, v154, 1.0
	v_rcp_f32_e32 v156, v155
	s_nop 0
	v_fma_f32 v157, -v155, v156, 1.0
	v_fmac_f32_e32 v156, v157, v156
	v_div_scale_f32 v157, vcc, 1.0, v154, 1.0
	v_mul_f32_e32 v158, v157, v156
	v_fma_f32 v159, -v155, v158, v157
	v_fmac_f32_e32 v158, v159, v156
	v_fma_f32 v155, -v155, v158, v157
	s_nop 0
	v_div_fmas_f32 v155, v155, v156, v158
	v_div_fixup_f32 v168, v155, v154, 1.0
	s_add_i32 s0, s98, 1
	s_lshl_b32 s0, s0, 11
	s_mov_b32 s1, 0
	v_lshl_add_u64 v[184:185], s[0:1], 0, v[172:173]
	v_lshl_add_u64 v[186:187], s[0:1], 0, v[180:181]
	v_mul_f32_e32 v150, v114, v168
	v_mul_f32_e32 v151, v115, v168
	v_fma_f32 v150, v0, v150, v8
	v_fma_f32 v151, v1, v151, v9
	v_mul_f32_e32 v152, v116, v168
	v_mul_f32_e32 v153, v117, v168
	v_fma_f32 v152, v2, v152, v10
	v_fma_f32 v153, v3, v153, v11
	v_cvt_pk_bf16_f32 v190, v150, v151
	v_cvt_pk_bf16_f32 v191, v152, v153
	v_lshlrev_b32_e32 v154, 16, v190
	v_and_b32_e32 v155, 0xffff0000, v190
	v_sub_f32_e32 v150, v150, v154
	v_sub_f32_e32 v151, v151, v155
	v_cvt_pk_bf16_f32 v198, v150, v151
	v_lshlrev_b32_e32 v154, 16, v191
	v_and_b32_e32 v155, 0xffff0000, v191
	v_sub_f32_e32 v152, v152, v154
	v_sub_f32_e32 v153, v153, v155
	v_cvt_pk_bf16_f32 v199, v152, v153
	v_mul_f32_e32 v150, v118, v168
	v_mul_f32_e32 v151, v119, v168
	v_fma_f32 v150, v4, v150, v12
	v_fma_f32 v151, v5, v151, v13
	v_mul_f32_e32 v152, v120, v168
	v_mul_f32_e32 v153, v121, v168
	v_fma_f32 v152, v6, v152, v14
	v_fma_f32 v153, v7, v153, v15
	v_cvt_pk_bf16_f32 v192, v150, v151
	v_cvt_pk_bf16_f32 v193, v152, v153
	v_lshlrev_b32_e32 v154, 16, v192
	v_and_b32_e32 v155, 0xffff0000, v192
	v_sub_f32_e32 v150, v150, v154
	v_sub_f32_e32 v151, v151, v155
	v_cvt_pk_bf16_f32 v200, v150, v151
	v_lshlrev_b32_e32 v154, 16, v193
	v_and_b32_e32 v155, 0xffff0000, v193
	v_sub_f32_e32 v152, v152, v154
	v_sub_f32_e32 v153, v153, v155
	v_cvt_pk_bf16_f32 v201, v152, v153
	v_mul_f32_e32 v150, v122, v168
	v_mul_f32_e32 v151, v123, v168
	v_fma_f32 v150, v16, v150, v24
	v_fma_f32 v151, v17, v151, v25
	v_mul_f32_e32 v152, v124, v168
	v_mul_f32_e32 v153, v125, v168
	v_fma_f32 v152, v18, v152, v26
	v_fma_f32 v153, v19, v153, v27
	v_cvt_pk_bf16_f32 v194, v150, v151
	v_cvt_pk_bf16_f32 v195, v152, v153
	v_lshlrev_b32_e32 v154, 16, v194
	v_and_b32_e32 v155, 0xffff0000, v194
	v_sub_f32_e32 v150, v150, v154
	v_sub_f32_e32 v151, v151, v155
	v_cvt_pk_bf16_f32 v202, v150, v151
	v_lshlrev_b32_e32 v154, 16, v195
	v_and_b32_e32 v155, 0xffff0000, v195
	v_sub_f32_e32 v152, v152, v154
	v_sub_f32_e32 v153, v153, v155
	v_cvt_pk_bf16_f32 v203, v152, v153
	v_mul_f32_e32 v150, v126, v168
	v_mul_f32_e32 v151, v127, v168
	v_fma_f32 v150, v20, v150, v28
	v_fma_f32 v151, v21, v151, v29
	v_mul_f32_e32 v152, v128, v168
	v_mul_f32_e32 v153, v129, v168
	v_fma_f32 v152, v22, v152, v30
	v_fma_f32 v153, v23, v153, v31
	v_cvt_pk_bf16_f32 v196, v150, v151
	v_cvt_pk_bf16_f32 v197, v152, v153
	v_lshlrev_b32_e32 v154, 16, v196
	v_and_b32_e32 v155, 0xffff0000, v196
	v_sub_f32_e32 v150, v150, v154
	v_sub_f32_e32 v151, v151, v155
	v_cvt_pk_bf16_f32 v204, v150, v151
	v_lshlrev_b32_e32 v154, 16, v197
	v_and_b32_e32 v155, 0xffff0000, v197
	v_sub_f32_e32 v152, v152, v154
	v_sub_f32_e32 v153, v153, v155
	v_cvt_pk_bf16_f32 v205, v152, v153
	global_store_dwordx2 v[184:185], v[190:191], off offset:0
	global_store_dwordx2 v[184:185], v[192:193], off offset:512
	global_store_dwordx2 v[184:185], v[194:195], off offset:1024
	global_store_dwordx2 v[184:185], v[196:197], off offset:1536
	global_store_dwordx2 v[186:187], v[198:199], off offset:0
	global_store_dwordx2 v[186:187], v[200:201], off offset:512
	global_store_dwordx2 v[186:187], v[202:203], off offset:1024
	global_store_dwordx2 v[186:187], v[204:205], off offset:1536
	s_add_i32 s0, s98, 3
	s_min_u32 s0, s0, 31
	s_lshl_b32 s0, s0, 11
	s_mov_b32 s1, 0
	v_lshl_add_u64 v[184:185], s[0:1], 0, v[178:179]
	v_lshl_add_u64 v[186:187], s[0:1], 0, v[172:173]
	v_lshl_add_u64 v[188:189], s[0:1], 0, v[176:177]
	global_load_dwordx2 v[106:107], v[184:185], off offset:-1024
	global_load_dwordx2 v[108:109], v[184:185], off offset:-512
	global_load_dwordx2 v[110:111], v[184:185], off offset:0
	global_load_dwordx2 v[112:113], v[184:185], off offset:512
	global_load_dwordx2 v[90:91], v[186:187], off offset:0
	global_load_dwordx2 v[92:93], v[186:187], off offset:512
	global_load_dwordx2 v[94:95], v[186:187], off offset:1024
	global_load_dwordx2 v[96:97], v[186:187], off offset:1536
	global_load_dwordx2 v[98:99], v[188:189], off offset:0
	global_load_dwordx2 v[100:101], v[188:189], off offset:512
	global_load_dwordx2 v[102:103], v[188:189], off offset:1024
	global_load_dwordx2 v[104:105], v[188:189], off offset:1536
	s_add_i32 s98, s98, 2
	s_cmp_lt_u32 s98, 32
	s_cbranch_scc1 .Lmy_ln1h_loop
	s_waitcnt vmcnt(0)
	s_branch .LBB0_557

; __device__ __forceinline__ float bflo(unsigned u) { return __uint_as_float(u << 16); }
; __device__ __forceinline__ float bfhi(unsigned u) { return __uint_as_float(u & 0xffff0000u); }
; __device__ __forceinline__ void ln_panel(int pm, const float* resf, const bf16* rlo, const bf16* dlt, float* xo, const float* gam, const float* bet, bf16* xb, bf16* wlo, bool fin, float alpha) {
;     ...
;         for (int j = 0; j < 4; ++j) { f32x4 x; const u32x2 d = *(const u32x2*)(dlt + prow + 256 * j);
;             if (resf) x = *(const f32x4*)(resf + grow + 256 * j);
;             else { const u32x2 h = *(const u32x2*)(xb + grow + 256 * j), l = *(const u32x2*)(rlo + prow + 256 * j);
;                    x = (f32x4){bflo(h.x) + bflo(l.x), bfhi(h.x) + bfhi(l.x), bflo(h.y) + bflo(l.y), bfhi(h.y) + bfhi(l.y)}; }
;             v[j] = (f32x4){x.x * alpha + bflo(d.x), x.y * alpha + bfhi(d.x), x.z * alpha + bflo(d.y), x.w * alpha + bfhi(d.y)}; s += (v[j].x + v[j].y) + (v[j].z + v[j].w); }
;         const float mean = wave_sum(s) * (1.f / DM); float s2 = 0.f;
; #pragma unroll
;         for (int j = 0; j < 4; ++j) { v[j] = v[j] - mean; s2 += (v[j].x * v[j].x + v[j].y * v[j].y) + (v[j].z * v[j].z + v[j].w * v[j].w); }
;         const float rstd = 1.f / sqrtf(wave_sum(s2) * (1.f / DM) + LN_EPS);
; #pragma unroll
;         for (int j = 0; j < 4; ++j) { const f32x4 o = v[j] * rstd * gv[j] + bv[j];
.Lmy_ln1r_entry:
	v_lshlrev_b32_e32 v152, 16, v82
	v_and_b32_e32 v153, 0xffff0000, v82
	v_fma_f32 v114, v66, v164, v152
	v_fma_f32 v115, v67, v165, v153
	v_lshlrev_b32_e32 v152, 16, v83
	v_and_b32_e32 v153, 0xffff0000, v83
	v_fma_f32 v116, v68, v164, v152
	v_fma_f32 v117, v69, v165, v153
	v_lshlrev_b32_e32 v152, 16, v84
	v_and_b32_e32 v153, 0xffff0000, v84
	v_fma_f32 v118, v70, v164, v152
	v_fma_f32 v119, v71, v165, v153
	v_lshlrev_b32_e32 v152, 16, v85
	v_and_b32_e32 v153, 0xffff0000, v85
	v_fma_f32 v120, v72, v164, v152
	v_fma_f32 v121, v73, v165, v153
	v_lshlrev_b32_e32 v152, 16, v86
	v_and_b32_e32 v153, 0xffff0000, v86
	v_fma_f32 v122, v74, v164, v152
	v_fma_f32 v123, v75, v165, v153
	v_lshlrev_b32_e32 v152, 16, v87
	v_and_b32_e32 v153, 0xffff0000, v87
	v_fma_f32 v124, v76, v164, v152
	v_fma_f32 v125, v77, v165, v153
	v_lshlrev_b32_e32 v152, 16, v88
	v_and_b32_e32 v153, 0xffff0000, v88
	v_fma_f32 v126, v78, v164, v152
	v_fma_f32 v127, v79, v165, v153
	v_lshlrev_b32_e32 v152, 16, v89
	v_and_b32_e32 v153, 0xffff0000, v89
	v_fma_f32 v128, v80, v164, v152
	v_fma_f32 v129, v81, v165, v153
	v_add_f32_e32 v154, v114, v116
	v_add_f32_e32 v155, v115, v117
	v_add_f32_e32 v156, v118, v120
	v_add_f32_e32 v157, v119, v121
	v_add_f32_e32 v154, v154, v156
	v_add_f32_e32 v155, v155, v157
	v_add_f32_e32 v156, v122, v124
	v_add_f32_e32 v157, v123, v125
	v_add_f32_e32 v154, v154, v156
	v_add_f32_e32 v155, v155, v157
	v_add_f32_e32 v156, v126, v128
	v_add_f32_e32 v157, v127, v129
	v_add_f32_e32 v154, v154, v156
	v_add_f32_e32 v155, v155, v157
	v_add_f32_e32 v154, v154, v155
	s_nop 1
	v_add_f32_dpp v160, v154, v154 quad_perm:[1,0,3,2] row_mask:0xf bank_mask:0xf
	s_nop 1
	v_add_f32_dpp v160, v160, v160 quad_perm:[2,3,0,1] row_mask:0xf bank_mask:0xf
	s_nop 1
	v_add_f32_dpp v160, v160, v160 row_half_mirror row_mask:0xf bank_mask:0xf
	s_nop 1
	v_add_f32_dpp v160, v160, v160 row_mirror row_mask:0xf bank_mask:0xf
	s_nop 1
	v_add_f32_dpp v160, v160, v160 row_bcast:15 row_mask:0xa bank_mask:0xf
	s_nop 1
	v_add_f32_dpp v160, v160, v160 row_bcast:31 row_mask:0xc bank_mask:0xf
	s_nop 1
	v_readlane_b32 s0, v160, 63
	s_nop 2
	v_mov_b32_e32 v170, s0
	v_mul_f32_e32 v156, 0xba800000, v170
	v_mul_f32_e32 v157, 0xba800000, v170
	v_add_f32_e32 v114, v114, v156
	v_add_f32_e32 v115, v115, v157
	v_add_f32_e32 v116, v116, v156
	v_add_f32_e32 v117, v117, v157
	v_add_f32_e32 v118, v118, v156
	v_add_f32_e32 v119, v119, v157
	v_add_f32_e32 v120, v120, v156
	v_add_f32_e32 v121, v121, v157
	v_add_f32_e32 v122, v122, v156
	v_add_f32_e32 v123, v123, v157
	v_add_f32_e32 v124, v124, v156
	v_add_f32_e32 v125, v125, v157
	v_add_f32_e32 v126, v126, v156
	v_add_f32_e32 v127, v127, v157
	v_add_f32_e32 v128, v128, v156
	v_add_f32_e32 v129, v129, v157
	v_mul_f32_e32 v154, v114, v114
	v_mul_f32_e32 v155, v115, v115
	v_fma_f32 v154, v116, v116, v154
	v_fma_f32 v155, v117, v117, v155
	v_fma_f32 v154, v118, v118, v154
	v_fma_f32 v155, v119, v119, v155
	v_fma_f32 v154, v120, v120, v154
	v_fma_f32 v155, v121, v121, v155
	v_fma_f32 v154, v122, v122, v154
	v_fma_f32 v155, v123, v123, v155
	v_fma_f32 v154, v124, v124, v154
	v_fma_f32 v155, v125, v125, v155
	v_fma_f32 v154, v126, v126, v154
	v_fma_f32 v155, v127, v127, v155
	v_fma_f32 v154, v128, v128, v154
	v_fma_f32 v155, v129, v129, v155
	v_add_f32_e32 v154, v154, v155
	s_nop 1
	v_add_f32_dpp v160, v154, v154 quad_perm:[1,0,3,2] row_mask:0xf bank_mask:0xf
	s_nop 1
	v_add_f32_dpp v160, v160, v160 quad_perm:[2,3,0,1] row_mask:0xf bank_mask:0xf
	s_nop 1
	v_add_f32_dpp v160, v160, v160 row_half_mirror row_mask:0xf bank_mask:0xf
	s_nop 1
	v_add_f32_dpp v160, v160, v160 row_mirror row_mask:0xf bank_mask:0xf
	s_nop 1
	v_add_f32_dpp v160, v160, v160 row_bcast:15 row_mask:0xa bank_mask:0xf
	s_nop 1
	v_add_f32_dpp v160, v160, v160 row_bcast:31 row_mask:0xc bank_mask:0xf
	s_nop 1
	v_readlane_b32 s0, v160, 63
	s_nop 2
	v_mov_b32_e32 v170, s0
	v_fmamk_f32 v154, v170, 0x3a800000, v166
	s_mov_b32 s0, 0xf800000
	v_mul_f32_e32 v155, 0x4f800000, v154
	v_cmp_gt_f32_e32 vcc, s0, v154
	s_nop 1
	v_cndmask_b32_e32 v154, v154, v155, vcc
	v_sqrt_f32_e32 v155, v154
	s_nop 0
	v_add_u32_e32 v156, -1, v155
	v_fma_f32 v157, -v156, v155, v154
	v_cmp_ge_f32_e64 s[0:1], 0, v157
	v_add_u32_e32 v157, 1, v155
	s_nop 0
	v_cndmask_b32_e64 v156, v155, v156, s[0:1]
	v_fma_f32 v155, -v157, v155, v154
	v_cmp_lt_f32_e64 s[0:1], 0, v155
	s_nop 1
	v_cndmask_b32_e64 v155, v156, v157, s[0:1]
	v_mul_f32_e32 v156, 0x37800000, v155
	v_cndmask_b32_e32 v155, v155, v156, vcc
	v_cmp_class_f32_e32 vcc, v154, v167
	s_nop 1
	v_cndmask_b32_e32 v154, v155, v154, vcc
	v_div_scale_f32 v155, s[0:1], v154, v154, 1.0
	v_rcp_f32_e32 v156, v155
	s_nop 0
	v_fma_f32 v157, -v155, v156, 1.0
	v_fmac_f32_e32 v156, v157, v156
	v_div_scale_f32 v157, vcc, 1.0, v154, 1.0
	v_mul_f32_e32 v158, v157, v156
	v_fma_f32 v159, -v155, v158, v157
	v_fmac_f32_e32 v158, v159, v156
	v_fma_f32 v155, -v155, v158, v157
	s_nop 0
	v_div_fmas_f32 v155, v155, v156, v158
	v_div_fixup_f32 v168, v155, v154, 1.0
	s_add_i32 s0, s98, 0
	s_lshl_b32 s0, s0, 11
	s_mov_b32 s1, 0
	v_lshl_add_u64 v[184:185], s[0:1], 0, v[172:173]
	v_lshl_add_u64 v[186:187], s[0:1], 0, v[180:181]
	v_mul_f32_e32 v150, v114, v168
	v_mul_f32_e32 v151, v115, v168
	v_fma_f32 v150, v0, v150, v8
	v_fma_f32 v151, v1, v151, v9
	v_mul_f32_e32 v152, v116, v168
	v_mul_f32_e32 v153, v117, v168
	v_fma_f32 v152, v2, v152, v10
	v_fma_f32 v153, v3, v153, v11
	v_cvt_pk_bf16_f32 v190, v150, v151
	v_cvt_pk_bf16_f32 v191, v152, v153
	v_lshlrev_b32_e32 v154, 16, v190
	v_and_b32_e32 v155, 0xffff0000, v190
	v_sub_f32_e32 v150, v150, v154
	v_sub_f32_e32 v151, v151, v155
	v_cvt_pk_bf16_f32 v198, v150, v151
; __device__ __forceinline__ unsigned pk2(float lo, float hi) { return pg8::cvt_pk_bf16(lo, hi); }
; __device__ __forceinline__ float bflo(unsigned u) { return __uint_as_float(u << 16); }
; __device__ __forceinline__ float bfhi(unsigned u) { return __uint_as_float(u & 0xffff0000u); }
; __device__ __forceinline__ void ln_panel(int pm, const float* resf, const bf16* rlo, const bf16* dlt, float* xo, const float* gam, const float* bet, bf16* xb, bf16* wlo, bool fin, float alpha) {
;     ...
;         for (int j = 0; j < 4; ++j) { f32x4 x; const u32x2 d = *(const u32x2*)(dlt + prow + 256 * j);
;             if (resf) x = *(const f32x4*)(resf + grow + 256 * j);
;             else { const u32x2 h = *(const u32x2*)(xb + grow + 256 * j), l = *(const u32x2*)(rlo + prow + 256 * j);
;                    x = (f32x4){bflo(h.x) + bflo(l.x), bfhi(h.x) + bfhi(l.x), bflo(h.y) + bflo(l.y), bfhi(h.y) + bfhi(l.y)}; }
;             v[j] = (f32x4){x.x * alpha + bflo(d.x), x.y * alpha + bfhi(d.x), x.z * alpha + bflo(d.y), x.w * alpha + bfhi(d.y)}; s += (v[j].x + v[j].y) + (v[j].z + v[j].w); }
;     ...
;         for (int j = 0; j < 4; ++j) { const f32x4 o = v[j] * rstd * gv[j] + bv[j];
;             if (fin) *(f32x4*)(xo + grow + 256 * j) = o;
;             else { u32x2 w; w.x = pk2(o.x, o.y); w.y = pk2(o.z, o.w); *(u32x2*)(xb + grow + 256 * j) = w;
;                    u32x2 q; q.x = pk2(o.x - bflo(w.x), o.y - bfhi(w.x)); q.y = pk2(o.z - bflo(w.y), o.w - bfhi(w.y)); *(u32x2*)(wlo + prow + 256 * j) = q; } }
	v_lshlrev_b32_e32 v154, 16, v191
	v_and_b32_e32 v155, 0xffff0000, v191
	v_sub_f32_e32 v152, v152, v154
	v_sub_f32_e32 v153, v153, v155
	v_cvt_pk_bf16_f32 v199, v152, v153
	v_mul_f32_e32 v150, v118, v168
	v_mul_f32_e32 v151, v119, v168
	v_fma_f32 v150, v4, v150, v12
	v_fma_f32 v151, v5, v151, v13
	v_mul_f32_e32 v152, v120, v168
	v_mul_f32_e32 v153, v121, v168
	v_fma_f32 v152, v6, v152, v14
	v_fma_f32 v153, v7, v153, v15
	v_cvt_pk_bf16_f32 v192, v150, v151
	v_cvt_pk_bf16_f32 v193, v152, v153
	v_lshlrev_b32_e32 v154, 16, v192
	v_and_b32_e32 v155, 0xffff0000, v192
	v_sub_f32_e32 v150, v150, v154
	v_sub_f32_e32 v151, v151, v155
	v_cvt_pk_bf16_f32 v200, v150, v151
	v_lshlrev_b32_e32 v154, 16, v193
	v_and_b32_e32 v155, 0xffff0000, v193
	v_sub_f32_e32 v152, v152, v154
	v_sub_f32_e32 v153, v153, v155
	v_cvt_pk_bf16_f32 v201, v152, v153
	v_mul_f32_e32 v150, v122, v168
	v_mul_f32_e32 v151, v123, v168
	v_fma_f32 v150, v16, v150, v24
	v_fma_f32 v151, v17, v151, v25
	v_mul_f32_e32 v152, v124, v168
	v_mul_f32_e32 v153, v125, v168
	v_fma_f32 v152, v18, v152, v26
	v_fma_f32 v153, v19, v153, v27
	v_cvt_pk_bf16_f32 v194, v150, v151
	v_cvt_pk_bf16_f32 v195, v152, v153
	v_lshlrev_b32_e32 v154, 16, v194
	v_and_b32_e32 v155, 0xffff0000, v194
	v_sub_f32_e32 v150, v150, v154
	v_sub_f32_e32 v151, v151, v155
	v_cvt_pk_bf16_f32 v202, v150, v151
	v_lshlrev_b32_e32 v154, 16, v195
	v_and_b32_e32 v155, 0xffff0000, v195
	v_sub_f32_e32 v152, v152, v154
	v_sub_f32_e32 v153, v153, v155
	v_cvt_pk_bf16_f32 v203, v152, v153
	v_mul_f32_e32 v150, v126, v168
	v_mul_f32_e32 v151, v127, v168
	v_fma_f32 v150, v20, v150, v28
	v_fma_f32 v151, v21, v151, v29
	v_mul_f32_e32 v152, v128, v168
	v_mul_f32_e32 v153, v129, v168
	v_fma_f32 v152, v22, v152, v30
	v_fma_f32 v153, v23, v153, v31
	v_cvt_pk_bf16_f32 v196, v150, v151
	v_cvt_pk_bf16_f32 v197, v152, v153
	v_lshlrev_b32_e32 v154, 16, v196
	v_and_b32_e32 v155, 0xffff0000, v196
	v_sub_f32_e32 v150, v150, v154
	v_sub_f32_e32 v151, v151, v155
	v_cvt_pk_bf16_f32 v204, v150, v151
	v_lshlrev_b32_e32 v154, 16, v197
	v_and_b32_e32 v155, 0xffff0000, v197
	v_sub_f32_e32 v152, v152, v154
	v_sub_f32_e32 v153, v153, v155
	v_cvt_pk_bf16_f32 v205, v152, v153
	global_store_dwordx2 v[184:185], v[190:191], off offset:0
	global_store_dwordx2 v[184:185], v[192:193], off offset:512
	global_store_dwordx2 v[184:185], v[194:195], off offset:1024
	global_store_dwordx2 v[184:185], v[196:197], off offset:1536
	global_store_dwordx2 v[186:187], v[198:199], off offset:0
	global_store_dwordx2 v[186:187], v[200:201], off offset:512
	global_store_dwordx2 v[186:187], v[202:203], off offset:1024
	global_store_dwordx2 v[186:187], v[204:205], off offset:1536
	s_add_i32 s0, s98, 2
	s_min_u32 s0, s0, 31
	s_lshl_b32 s0, s0, 11
	s_mov_b32 s1, 0
	v_lshl_add_u64 v[184:185], s[0:1], 0, v[178:179]
	v_lshl_add_u64 v[186:187], s[0:1], 1, v[182:183]
	global_load_dwordx2 v[82:83], v[184:185], off offset:-1024
	global_load_dwordx2 v[84:85], v[184:185], off offset:-512
	global_load_dwordx2 v[86:87], v[184:185], off offset:0
	global_load_dwordx2 v[88:89], v[184:185], off offset:512
	global_load_dwordx4 v[66:69], v[186:187], off offset:0
	global_load_dwordx4 v[70:73], v[186:187], off offset:1024
	global_load_dwordx4 v[74:77], v[186:187], off offset:2048
	global_load_dwordx4 v[78:81], v[186:187], off offset:3072
	s_waitcnt vmcnt(16)
	v_lshlrev_b32_e32 v152, 16, v106
	v_and_b32_e32 v153, 0xffff0000, v106
	v_fma_f32 v114, v90, v164, v152
	v_fma_f32 v115, v91, v165, v153
	v_lshlrev_b32_e32 v152, 16, v107
	v_and_b32_e32 v153, 0xffff0000, v107
	v_fma_f32 v116, v92, v164, v152
	v_fma_f32 v117, v93, v165, v153
	v_lshlrev_b32_e32 v152, 16, v108
	v_and_b32_e32 v153, 0xffff0000, v108
	v_fma_f32 v118, v94, v164, v152
	v_fma_f32 v119, v95, v165, v153
	v_lshlrev_b32_e32 v152, 16, v109
	v_and_b32_e32 v153, 0xffff0000, v109
	v_fma_f32 v120, v96, v164, v152
	v_fma_f32 v121, v97, v165, v153
	v_lshlrev_b32_e32 v152, 16, v110
	v_and_b32_e32 v153, 0xffff0000, v110
	v_fma_f32 v122, v98, v164, v152
	v_fma_f32 v123, v99, v165, v153
	v_lshlrev_b32_e32 v152, 16, v111
	v_and_b32_e32 v153, 0xffff0000, v111
	v_fma_f32 v124, v100, v164, v152
	v_fma_f32 v125, v101, v165, v153
	v_lshlrev_b32_e32 v152, 16, v112
	v_and_b32_e32 v153, 0xffff0000, v112
	v_fma_f32 v126, v102, v164, v152
	v_fma_f32 v127, v103, v165, v153
	v_lshlrev_b32_e32 v152, 16, v113
	v_and_b32_e32 v153, 0xffff0000, v113
	v_fma_f32 v128, v104, v164, v152
	v_fma_f32 v129, v105, v165, v153
	v_add_f32_e32 v154, v114, v116
	v_add_f32_e32 v155, v115, v117
	v_add_f32_e32 v156, v118, v120
	v_add_f32_e32 v157, v119, v121
	v_add_f32_e32 v154, v154, v156
	v_add_f32_e32 v155, v155, v157
	v_add_f32_e32 v156, v122, v124
	v_add_f32_e32 v157, v123, v125
	v_add_f32_e32 v154, v154, v156
	v_add_f32_e32 v155, v155, v157
	v_add_f32_e32 v156, v126, v128
	v_add_f32_e32 v157, v127, v129
	v_add_f32_e32 v154, v154, v156
	v_add_f32_e32 v155, v155, v157
	v_add_f32_e32 v154, v154, v155
	s_nop 1
	v_add_f32_dpp v160, v154, v154 quad_perm:[1,0,3,2] row_mask:0xf bank_mask:0xf
	s_nop 1
	v_add_f32_dpp v160, v160, v160 quad_perm:[2,3,0,1] row_mask:0xf bank_mask:0xf
	s_nop 1
	v_add_f32_dpp v160, v160, v160 row_half_mirror row_mask:0xf bank_mask:0xf
	s_nop 1
	v_add_f32_dpp v160, v160, v160 row_mirror row_mask:0xf bank_mask:0xf
	s_nop 1
	v_add_f32_dpp v160, v160, v160 row_bcast:15 row_mask:0xa bank_mask:0xf
	s_nop 1
	v_add_f32_dpp v160, v160, v160 row_bcast:31 row_mask:0xc bank_mask:0xf
	s_nop 1
	v_readlane_b32 s0, v160, 63
	s_nop 2
	v_mov_b32_e32 v170, s0
	v_mul_f32_e32 v156, 0xba800000, v170
	v_mul_f32_e32 v157, 0xba800000, v170
	v_add_f32_e32 v114, v114, v156
	v_add_f32_e32 v115, v115, v157
; __device__ __forceinline__ unsigned pk2(float lo, float hi) { return pg8::cvt_pk_bf16(lo, hi); }
; __device__ __forceinline__ float bflo(unsigned u) { return __uint_as_float(u << 16); }
; __device__ __forceinline__ float bfhi(unsigned u) { return __uint_as_float(u & 0xffff0000u); }
; __device__ __forceinline__ void ln_panel(int pm, const float* resf, const bf16* rlo, const bf16* dlt, float* xo, const float* gam, const float* bet, bf16* xb, bf16* wlo, bool fin, float alpha) {
;     ...
;         for (int j = 0; j < 4; ++j) { v[j] = v[j] - mean; s2 += (v[j].x * v[j].x + v[j].y * v[j].y) + (v[j].z * v[j].z + v[j].w * v[j].w); }
;         const float rstd = 1.f / sqrtf(wave_sum(s2) * (1.f / DM) + LN_EPS);
; #pragma unroll
;         for (int j = 0; j < 4; ++j) { const f32x4 o = v[j] * rstd * gv[j] + bv[j];
;             if (fin) *(f32x4*)(xo + grow + 256 * j) = o;
;             else { u32x2 w; w.x = pk2(o.x, o.y); w.y = pk2(o.z, o.w); *(u32x2*)(xb + grow + 256 * j) = w;
;                    u32x2 q; q.x = pk2(o.x - bflo(w.x), o.y - bfhi(w.x)); q.y = pk2(o.z - bflo(w.y), o.w - bfhi(w.y)); *(u32x2*)(wlo + prow + 256 * j) = q; } }
	v_add_f32_e32 v116, v116, v156
	v_add_f32_e32 v117, v117, v157
	v_add_f32_e32 v118, v118, v156
	v_add_f32_e32 v119, v119, v157
	v_add_f32_e32 v120, v120, v156
	v_add_f32_e32 v121, v121, v157
	v_add_f32_e32 v122, v122, v156
	v_add_f32_e32 v123, v123, v157
	v_add_f32_e32 v124, v124, v156
	v_add_f32_e32 v125, v125, v157
	v_add_f32_e32 v126, v126, v156
	v_add_f32_e32 v127, v127, v157
	v_add_f32_e32 v128, v128, v156
	v_add_f32_e32 v129, v129, v157
	v_mul_f32_e32 v154, v114, v114
	v_mul_f32_e32 v155, v115, v115
	v_fma_f32 v154, v116, v116, v154
	v_fma_f32 v155, v117, v117, v155
	v_fma_f32 v154, v118, v118, v154
	v_fma_f32 v155, v119, v119, v155
	v_fma_f32 v154, v120, v120, v154
	v_fma_f32 v155, v121, v121, v155
	v_fma_f32 v154, v122, v122, v154
	v_fma_f32 v155, v123, v123, v155
	v_fma_f32 v154, v124, v124, v154
	v_fma_f32 v155, v125, v125, v155
	v_fma_f32 v154, v126, v126, v154
	v_fma_f32 v155, v127, v127, v155
	v_fma_f32 v154, v128, v128, v154
	v_fma_f32 v155, v129, v129, v155
	v_add_f32_e32 v154, v154, v155
	s_nop 1
	v_add_f32_dpp v160, v154, v154 quad_perm:[1,0,3,2] row_mask:0xf bank_mask:0xf
	s_nop 1
	v_add_f32_dpp v160, v160, v160 quad_perm:[2,3,0,1] row_mask:0xf bank_mask:0xf
	s_nop 1
	v_add_f32_dpp v160, v160, v160 row_half_mirror row_mask:0xf bank_mask:0xf
	s_nop 1
	v_add_f32_dpp v160, v160, v160 row_mirror row_mask:0xf bank_mask:0xf
	s_nop 1
	v_add_f32_dpp v160, v160, v160 row_bcast:15 row_mask:0xa bank_mask:0xf
	s_nop 1
	v_add_f32_dpp v160, v160, v160 row_bcast:31 row_mask:0xc bank_mask:0xf
	s_nop 1
	v_readlane_b32 s0, v160, 63
	s_nop 2
	v_mov_b32_e32 v170, s0
	v_fmamk_f32 v154, v170, 0x3a800000, v166
	s_mov_b32 s0, 0xf800000
	v_mul_f32_e32 v155, 0x4f800000, v154
	v_cmp_gt_f32_e32 vcc, s0, v154
	s_nop 1
	v_cndmask_b32_e32 v154, v154, v155, vcc
	v_sqrt_f32_e32 v155, v154
	s_nop 0
	v_add_u32_e32 v156, -1, v155
	v_fma_f32 v157, -v156, v155, v154
	v_cmp_ge_f32_e64 s[0:1], 0, v157
	v_add_u32_e32 v157, 1, v155
	s_nop 0
	v_cndmask_b32_e64 v156, v155, v156, s[0:1]
	v_fma_f32 v155, -v157, v155, v154
	v_cmp_lt_f32_e64 s[0:1], 0, v155
	s_nop 1
	v_cndmask_b32_e64 v155, v156, v157, s[0:1]
	v_mul_f32_e32 v156, 0x37800000, v155
	v_cndmask_b32_e32 v155, v155, v156, vcc
	v_cmp_class_f32_e32 vcc, v154, v167
	s_nop 1
	v_cndmask_b32_e32 v154, v155, v154, vcc
	v_div_scale_f32 v155, s[0:1], v154, v154, 1.0
	v_rcp_f32_e32 v156, v155
	s_nop 0
	v_fma_f32 v157, -v155, v156, 1.0
	v_fmac_f32_e32 v156, v157, v156
	v_div_scale_f32 v157, vcc, 1.0, v154, 1.0
	v_mul_f32_e32 v158, v157, v156
	v_fma_f32 v159, -v155, v158, v157
	v_fmac_f32_e32 v158, v159, v156
	v_fma_f32 v155, -v155, v158, v157
	s_nop 0
	v_div_fmas_f32 v155, v155, v156, v158
	v_div_fixup_f32 v168, v155, v154, 1.0
	s_add_i32 s0, s98, 1
	s_lshl_b32 s0, s0, 11
	s_mov_b32 s1, 0
	v_lshl_add_u64 v[184:185], s[0:1], 0, v[172:173]
	v_lshl_add_u64 v[186:187], s[0:1], 0, v[180:181]
	v_mul_f32_e32 v150, v114, v168
	v_mul_f32_e32 v151, v115, v168
	v_fma_f32 v150, v0, v150, v8
	v_fma_f32 v151, v1, v151, v9
	v_mul_f32_e32 v152, v116, v168
	v_mul_f32_e32 v153, v117, v168
	v_fma_f32 v152, v2, v152, v10
	v_fma_f32 v153, v3, v153, v11
	v_cvt_pk_bf16_f32 v190, v150, v151
	v_cvt_pk_bf16_f32 v191, v152, v153
	v_lshlrev_b32_e32 v154, 16, v190
	v_and_b32_e32 v155, 0xffff0000, v190
	v_sub_f32_e32 v150, v150, v154
	v_sub_f32_e32 v151, v151, v155
	v_cvt_pk_bf16_f32 v198, v150, v151
	v_lshlrev_b32_e32 v154, 16, v191
	v_and_b32_e32 v155, 0xffff0000, v191
	v_sub_f32_e32 v152, v152, v154
	v_sub_f32_e32 v153, v153, v155
	v_cvt_pk_bf16_f32 v199, v152, v153
	v_mul_f32_e32 v150, v118, v168
	v_mul_f32_e32 v151, v119, v168
	v_fma_f32 v150, v4, v150, v12
	v_fma_f32 v151, v5, v151, v13
	v_mul_f32_e32 v152, v120, v168
	v_mul_f32_e32 v153, v121, v168
	v_fma_f32 v152, v6, v152, v14
	v_fma_f32 v153, v7, v153, v15
	v_cvt_pk_bf16_f32 v192, v150, v151
	v_cvt_pk_bf16_f32 v193, v152, v153
	v_lshlrev_b32_e32 v154, 16, v192
	v_and_b32_e32 v155, 0xffff0000, v192
	v_sub_f32_e32 v150, v150, v154
	v_sub_f32_e32 v151, v151, v155
	v_cvt_pk_bf16_f32 v200, v150, v151
	v_lshlrev_b32_e32 v154, 16, v193
	v_and_b32_e32 v155, 0xffff0000, v193
	v_sub_f32_e32 v152, v152, v154
	v_sub_f32_e32 v153, v153, v155
	v_cvt_pk_bf16_f32 v201, v152, v153
	v_mul_f32_e32 v150, v122, v168
	v_mul_f32_e32 v151, v123, v168
	v_fma_f32 v150, v16, v150, v24
	v_fma_f32 v151, v17, v151, v25
	v_mul_f32_e32 v152, v124, v168
	v_mul_f32_e32 v153, v125, v168
	v_fma_f32 v152, v18, v152, v26
	v_fma_f32 v153, v19, v153, v27
	v_cvt_pk_bf16_f32 v194, v150, v151
	v_cvt_pk_bf16_f32 v195, v152, v153
	v_lshlrev_b32_e32 v154, 16, v194
	v_and_b32_e32 v155, 0xffff0000, v194
	v_sub_f32_e32 v150, v150, v154
	v_sub_f32_e32 v151, v151, v155
	v_cvt_pk_bf16_f32 v202, v150, v151
	v_lshlrev_b32_e32 v154, 16, v195
	v_and_b32_e32 v155, 0xffff0000, v195
	v_sub_f32_e32 v152, v152, v154
	v_sub_f32_e32 v153, v153, v155
	v_cvt_pk_bf16_f32 v203, v152, v153
	v_mul_f32_e32 v150, v126, v168
	v_mul_f32_e32 v151, v127, v168
	v_fma_f32 v150, v20, v150, v28
	v_fma_f32 v151, v21, v151, v29
	v_mul_f32_e32 v152, v128, v168
	v_mul_f32_e32 v153, v129, v168
	v_fma_f32 v152, v22, v152, v30
	v_fma_f32 v153, v23, v153, v31
	v_cvt_pk_bf16_f32 v196, v150, v151
	v_cvt_pk_bf16_f32 v197, v152, v153
	v_lshlrev_b32_e32 v154, 16, v196
	v_and_b32_e32 v155, 0xffff0000, v196
	v_sub_f32_e32 v150, v150, v154
	v_sub_f32_e32 v151, v151, v155
	v_cvt_pk_bf16_f32 v204, v150, v151
	v_lshlrev_b32_e32 v154, 16, v197
	v_and_b32_e32 v155, 0xffff0000, v197
	v_sub_f32_e32 v152, v152, v154
	v_sub_f32_e32 v153, v153, v155
	v_cvt_pk_bf16_f32 v205, v152, v153
	global_store_dwordx2 v[184:185], v[190:191], off offset:0
	global_store_dwordx2 v[184:185], v[192:193], off offset:512
	global_store_dwordx2 v[184:185], v[194:195], off offset:1024
	global_store_dwordx2 v[184:185], v[196:197], off offset:1536
	global_store_dwordx2 v[186:187], v[198:199], off offset:0
	global_store_dwordx2 v[186:187], v[200:201], off offset:512
	global_store_dwordx2 v[186:187], v[202:203], off offset:1024
	global_store_dwordx2 v[186:187], v[204:205], off offset:1536
	s_add_i32 s0, s98, 3
	s_min_u32 s0, s0, 31
	s_lshl_b32 s0, s0, 11
	s_mov_b32 s1, 0
	v_lshl_add_u64 v[184:185], s[0:1], 0, v[178:179]
	v_lshl_add_u64 v[186:187], s[0:1], 1, v[182:183]
	global_load_dwordx2 v[106:107], v[184:185], off offset:-1024
	global_load_dwordx2 v[108:109], v[184:185], off offset:-512
	global_load_dwordx2 v[110:111], v[184:185], off offset:0
	global_load_dwordx2 v[112:113], v[184:185], off offset:512
	global_load_dwordx4 v[90:93], v[186:187], off offset:0
	global_load_dwordx4 v[94:97], v[186:187], off offset:1024
	global_load_dwordx4 v[98:101], v[186:187], off offset:2048
	global_load_dwordx4 v[102:105], v[186:187], off offset:3072
	s_add_i32 s98, s98, 2
	s_cmp_lt_u32 s98, 32
	s_cbranch_scc1 .Lmy_ln1r_loop
	s_waitcnt vmcnt(0)
	s_branch .LBB0_557

; __device__ __forceinline__ unsigned cvt_pk_bf16(float lo, float hi) { f32x2 v = {lo, hi}; bf16x2_t b = __builtin_convertvector(v, bf16x2_t); return __builtin_bit_cast(unsigned, b); }
; __device__ __forceinline__ float sigmoidf_(float x) { return __builtin_amdgcn_rcpf(1.0f + __builtin_amdgcn_exp2f(-1.4426950408889634f * x)); }
;     __device__ __forceinline__ void operator()(const f32x4 (&acc)[2][2][4][2], const Unit& u, int wr, int wc, int fr, int fq) const {
;     ...
;         for (int ai = 0; ai < 2; ++ai)
; #pragma unroll
;             for (int m = 0; m < 4; ++m) { float hv[8];
; #pragma unroll
;                 for (int n = 0; n < 2; ++n)
; #pragma unroll
;                     for (int i = 0; i < 4; ++i) { const float gt = acc[ai][0][m][n][i], up = acc[ai][1][m][n][i]; hv[n * 4 + i] = gt * sigmoidf_(gt) * up; }
;                 u32x4 w; w.x = cvt_pk_bf16(hv[0], hv[1]); w.y = cvt_pk_bf16(hv[2], hv[3]); w.z = cvt_pk_bf16(hv[4], hv[5]); w.w = cvt_pk_bf16(hv[6], hv[7]);
;                 *(u32x4*)(base + (size_t)(ai * HALF + m * 16) * 2816) = w; }
.LBB0_566:
	v_mul_f32_e32 v142, 0xbfb8aa3b, v126
	v_mul_f32_e32 v143, 0xbfb8aa3b, v127
	v_exp_f32_e32 v142, v142
	v_exp_f32_e32 v143, v143
	s_lshl_b32 s46, s53, 7
	s_mov_b32 s14, 0x16000
	v_add_f32_e32 v142, 1.0, v142
	v_add_f32_e32 v143, 1.0, v143
	v_rcp_f32_e32 v152, v142
	v_rcp_f32_e32 v153, v143
	v_lshl_add_u64 v[142:143], s[46:47], 1, v[136:137]
	s_cmp_eq_u32 s53, 21
	s_mov_b64 s[70:71], 0x2000
	v_mul_f32_e32 v126, v126, v152
	v_mul_f32_e32 v127, v127, v153
	v_mul_f32_e32 v152, 0xbfb8aa3b, v128
	v_mul_f32_e32 v153, 0xbfb8aa3b, v129
	v_exp_f32_e32 v152, v152
	v_exp_f32_e32 v153, v153
	v_mul_f32_e32 v118, v126, v118
	v_mul_f32_e32 v119, v127, v119
	v_add_f32_e32 v126, 1.0, v152
	v_add_f32_e32 v127, 1.0, v153
	v_mul_f32_e32 v152, 0xbfb8aa3b, v122
	v_mul_f32_e32 v153, 0xbfb8aa3b, v123
	v_rcp_f32_e32 v126, v126
	v_rcp_f32_e32 v127, v127
	v_exp_f32_e32 v152, v152
	v_exp_f32_e32 v153, v153
	v_mul_f32_e32 v126, v128, v126
	v_mul_f32_e32 v127, v129, v127
	v_add_f32_e32 v128, 1.0, v152
	v_add_f32_e32 v129, 1.0, v153
	v_mul_f32_e32 v152, 0xbfb8aa3b, v124
	v_mul_f32_e32 v153, 0xbfb8aa3b, v125
	v_exp_f32_e32 v152, v152
	v_exp_f32_e32 v153, v153
	v_rcp_f32_e32 v128, v128
	v_rcp_f32_e32 v129, v129
	v_add_f32_e32 v152, 1.0, v152
	v_add_f32_e32 v153, 1.0, v153
	v_rcp_f32_e32 v152, v152
	v_rcp_f32_e32 v153, v153
	v_mul_f32_e32 v122, v122, v128
	v_mul_f32_e32 v123, v123, v129
	v_mul_f32_e32 v120, v126, v120
	v_mul_f32_e32 v121, v127, v121
	v_mul_f32_e32 v122, v122, v114
	v_mul_f32_e32 v123, v123, v115
	v_mul_f32_e32 v114, v124, v152
	v_mul_f32_e32 v115, v125, v153
	s_nop 0
	v_mul_f32_e32 v124, v114, v116
	v_mul_f32_e32 v125, v115, v117
	v_mul_f32_e32 v115, 0xbfb8aa3b, v110
	v_exp_f32_e32 v116, v115
	v_mul_f32_e32 v115, 0xbfb8aa3b, v111
	v_exp_f32_e32 v117, v115
	v_cvt_pk_bf16_f32 v114, v118, v119
	v_add_f32_e32 v116, 1.0, v116
	v_rcp_f32_e32 v118, v116
	v_add_f32_e32 v116, 1.0, v117
	v_cvt_pk_bf16_f32 v115, v120, v121
	v_rcp_f32_e32 v119, v116
	v_cvt_pk_bf16_f32 v116, v122, v123
	v_cvt_pk_bf16_f32 v117, v124, v125
	global_store_dwordx4 v[142:143], v[114:117], off
	v_mul_f32_e32 v110, v110, v118
	v_mul_f32_e32 v111, v111, v119
	s_nop 0
	v_mul_f32_e32 v114, 0xbfb8aa3b, v112
	v_mul_f32_e32 v115, 0xbfb8aa3b, v113
	v_exp_f32_e32 v114, v114
	v_exp_f32_e32 v115, v115
	v_mul_f32_e32 v102, v110, v102
	v_mul_f32_e32 v103, v111, v103
	v_add_f32_e32 v110, 1.0, v114
	v_add_f32_e32 v111, 1.0, v115
	v_mul_f32_e32 v114, 0xbfb8aa3b, v106
	v_mul_f32_e32 v115, 0xbfb8aa3b, v107
	v_rcp_f32_e32 v110, v110
	v_rcp_f32_e32 v111, v111
	v_exp_f32_e32 v114, v114
	v_exp_f32_e32 v115, v115
	v_mul_f32_e32 v110, v112, v110
	v_mul_f32_e32 v111, v113, v111
	v_add_f32_e32 v112, 1.0, v114
	v_add_f32_e32 v113, 1.0, v115
	v_mul_f32_e32 v114, 0xbfb8aa3b, v108
	v_mul_f32_e32 v115, 0xbfb8aa3b, v109
	v_exp_f32_e32 v114, v114
	v_exp_f32_e32 v115, v115
	v_rcp_f32_e32 v112, v112
	v_rcp_f32_e32 v113, v113
	v_add_f32_e32 v114, 1.0, v114
	v_add_f32_e32 v115, 1.0, v115
	v_rcp_f32_e32 v114, v114
	v_rcp_f32_e32 v115, v115
	v_mul_f32_e32 v106, v106, v112
	v_mul_f32_e32 v107, v107, v113
	v_mul_f32_e32 v104, v110, v104
	v_mul_f32_e32 v105, v111, v105
	v_mul_f32_e32 v106, v106, v98
	v_mul_f32_e32 v107, v107, v99
	v_mul_f32_e32 v98, v108, v114
	v_mul_f32_e32 v99, v109, v115
	s_nop 0
	v_mul_f32_e32 v108, v98, v100
	v_mul_f32_e32 v109, v99, v101
	v_mul_f32_e32 v101, 0xbfb8aa3b, v94
	v_cvt_pk_bf16_f32 v98, v102, v103
	v_exp_f32_e32 v102, v101
	v_mul_f32_e32 v101, 0xbfb8aa3b, v95
	v_exp_f32_e32 v103, v101
	v_cvt_pk_bf16_f32 v99, v104, v105
	v_add_co_u32_e32 v104, vcc, s14, v142
	v_cvt_pk_bf16_f32 v100, v106, v107
	v_cvt_pk_bf16_f32 v101, v108, v109
	v_add_f32_e32 v102, 1.0, v102
	v_add_f32_e32 v103, 1.0, v103
	v_addc_co_u32_e32 v105, vcc, 0, v143, vcc
	v_rcp_f32_e32 v102, v102
	v_rcp_f32_e32 v103, v103
	global_store_dwordx4 v[104:105], v[98:101], off
	s_mov_b32 s14, 0x2c000
	v_mul_f32_e32 v94, v94, v102
	v_mul_f32_e32 v95, v95, v103
	v_mul_f32_e32 v98, 0xbfb8aa3b, v96
	v_mul_f32_e32 v99, 0xbfb8aa3b, v97
	v_exp_f32_e32 v98, v98
	v_exp_f32_e32 v99, v99
	v_mul_f32_e32 v86, v94, v86
	v_mul_f32_e32 v87, v95, v87
	v_add_f32_e32 v94, 1.0, v98
	v_add_f32_e32 v95, 1.0, v99
	v_mul_f32_e32 v98, 0xbfb8aa3b, v90
	v_mul_f32_e32 v99, 0xbfb8aa3b, v91
	v_rcp_f32_e32 v94, v94
	v_rcp_f32_e32 v95, v95
	v_exp_f32_e32 v98, v98
	v_exp_f32_e32 v99, v99
	v_mul_f32_e32 v94, v96, v94
	v_mul_f32_e32 v95, v97, v95
	v_add_f32_e32 v96, 1.0, v98
	v_add_f32_e32 v97, 1.0, v99
	v_mul_f32_e32 v98, 0xbfb8aa3b, v92
	v_mul_f32_e32 v99, 0xbfb8aa3b, v93
	v_exp_f32_e32 v98, v98
	v_exp_f32_e32 v99, v99
	v_rcp_f32_e32 v96, v96
	v_rcp_f32_e32 v97, v97
	v_add_f32_e32 v98, 1.0, v98
	v_add_f32_e32 v99, 1.0, v99
	v_rcp_f32_e32 v98, v98
	v_rcp_f32_e32 v99, v99
	v_mul_f32_e32 v90, v90, v96
	v_mul_f32_e32 v91, v91, v97
	v_mul_f32_e32 v88, v94, v88
	v_mul_f32_e32 v89, v95, v89
	v_mul_f32_e32 v90, v90, v82
	v_mul_f32_e32 v91, v91, v83
	v_mul_f32_e32 v82, v92, v98
	v_mul_f32_e32 v83, v93, v99
	s_nop 0
	v_mul_f32_e32 v92, v82, v84
	v_mul_f32_e32 v93, v83, v85
	v_mul_f32_e32 v85, 0xbfb8aa3b, v78
	v_cvt_pk_bf16_f32 v82, v86, v87
	v_exp_f32_e32 v86, v85
	v_mul_f32_e32 v85, 0xbfb8aa3b, v79
	v_exp_f32_e32 v87, v85
	v_cvt_pk_bf16_f32 v83, v88, v89
	v_add_co_u32_e32 v88, vcc, s14, v142
	v_cvt_pk_bf16_f32 v84, v90, v91
	v_cvt_pk_bf16_f32 v85, v92, v93
	v_add_f32_e32 v86, 1.0, v86
	v_add_f32_e32 v87, 1.0, v87
	v_addc_co_u32_e32 v89, vcc, 0, v143, vcc
	v_rcp_f32_e32 v86, v86
	v_rcp_f32_e32 v87, v87
	global_store_dwordx4 v[88:89], v[82:85], off
	s_mov_b32 s14, 0x42000
	v_mul_f32_e32 v78, v78, v86
	v_mul_f32_e32 v79, v79, v87
	v_mul_f32_e32 v82, 0xbfb8aa3b, v80
; __device__ __forceinline__ unsigned cvt_pk_bf16(float lo, float hi) { f32x2 v = {lo, hi}; bf16x2_t b = __builtin_convertvector(v, bf16x2_t); return __builtin_bit_cast(unsigned, b); }
; __device__ __forceinline__ float sigmoidf_(float x) { return __builtin_amdgcn_rcpf(1.0f + __builtin_amdgcn_exp2f(-1.4426950408889634f * x)); }
;     __device__ __forceinline__ void operator()(const f32x4 (&acc)[2][2][4][2], const Unit& u, int wr, int wc, int fr, int fq) const {
;     ...
;         for (int ai = 0; ai < 2; ++ai)
; #pragma unroll
;             for (int m = 0; m < 4; ++m) { float hv[8];
; #pragma unroll
;                 for (int n = 0; n < 2; ++n)
; #pragma unroll
;                     for (int i = 0; i < 4; ++i) { const float gt = acc[ai][0][m][n][i], up = acc[ai][1][m][n][i]; hv[n * 4 + i] = gt * sigmoidf_(gt) * up; }
;                 u32x4 w; w.x = cvt_pk_bf16(hv[0], hv[1]); w.y = cvt_pk_bf16(hv[2], hv[3]); w.z = cvt_pk_bf16(hv[4], hv[5]); w.w = cvt_pk_bf16(hv[6], hv[7]);
;                 *(u32x4*)(base + (size_t)(ai * HALF + m * 16) * 2816) = w; }
	v_mul_f32_e32 v83, 0xbfb8aa3b, v81
	v_exp_f32_e32 v82, v82
	v_exp_f32_e32 v83, v83
	v_mul_f32_e32 v70, v78, v70
	v_mul_f32_e32 v71, v79, v71
	v_add_f32_e32 v78, 1.0, v82
	v_add_f32_e32 v79, 1.0, v83
	v_mul_f32_e32 v82, 0xbfb8aa3b, v74
	v_mul_f32_e32 v83, 0xbfb8aa3b, v75
	v_rcp_f32_e32 v78, v78
	v_rcp_f32_e32 v79, v79
	v_exp_f32_e32 v82, v82
	v_exp_f32_e32 v83, v83
	v_mul_f32_e32 v78, v80, v78
	v_mul_f32_e32 v79, v81, v79
	v_add_f32_e32 v80, 1.0, v82
	v_add_f32_e32 v81, 1.0, v83
	v_mul_f32_e32 v82, 0xbfb8aa3b, v76
	v_mul_f32_e32 v83, 0xbfb8aa3b, v77
	v_exp_f32_e32 v82, v82
	v_exp_f32_e32 v83, v83
	v_rcp_f32_e32 v80, v80
	v_rcp_f32_e32 v81, v81
	v_add_f32_e32 v82, 1.0, v82
	v_add_f32_e32 v83, 1.0, v83
	v_rcp_f32_e32 v82, v82
	v_rcp_f32_e32 v83, v83
	v_mul_f32_e32 v74, v74, v80
	v_mul_f32_e32 v75, v75, v81
	v_mul_f32_e32 v72, v78, v72
	v_mul_f32_e32 v73, v79, v73
	v_mul_f32_e32 v74, v74, v66
	v_mul_f32_e32 v75, v75, v67
	v_mul_f32_e32 v66, v76, v82
	v_mul_f32_e32 v67, v77, v83
	s_nop 0
	v_mul_f32_e32 v76, v66, v68
	v_mul_f32_e32 v77, v67, v69
	v_mul_f32_e32 v69, 0xbfb8aa3b, v60
	v_cvt_pk_bf16_f32 v66, v70, v71
	v_exp_f32_e32 v70, v69
	v_mul_f32_e32 v69, 0xbfb8aa3b, v61
	v_exp_f32_e32 v71, v69
	v_cvt_pk_bf16_f32 v67, v72, v73
	v_add_co_u32_e32 v72, vcc, s14, v142
	v_cvt_pk_bf16_f32 v68, v74, v75
	v_cvt_pk_bf16_f32 v69, v76, v77
	v_add_f32_e32 v70, 1.0, v70
	v_add_f32_e32 v71, 1.0, v71
	v_addc_co_u32_e32 v73, vcc, 0, v143, vcc
	v_rcp_f32_e32 v70, v70
	v_rcp_f32_e32 v71, v71
	global_store_dwordx4 v[72:73], v[66:69], off
	s_mov_b32 s14, 0xb0000
	v_mul_f32_e32 v60, v60, v70
	v_mul_f32_e32 v61, v61, v71
	v_mul_f32_e32 v66, 0xbfb8aa3b, v62
	v_mul_f32_e32 v67, 0xbfb8aa3b, v63
	v_exp_f32_e32 v66, v66
	v_exp_f32_e32 v67, v67
	v_mul_f32_e32 v52, v60, v52
	v_mul_f32_e32 v53, v61, v53
	v_add_f32_e32 v60, 1.0, v66
	v_add_f32_e32 v61, 1.0, v67
	v_mul_f32_e32 v66, 0xbfb8aa3b, v56
	v_mul_f32_e32 v67, 0xbfb8aa3b, v57
	v_rcp_f32_e32 v60, v60
	v_rcp_f32_e32 v61, v61
	v_exp_f32_e32 v66, v66
	v_exp_f32_e32 v67, v67
	v_mul_f32_e32 v60, v62, v60
	v_mul_f32_e32 v61, v63, v61
	v_add_f32_e32 v62, 1.0, v66
	v_add_f32_e32 v63, 1.0, v67
	v_mul_f32_e32 v66, 0xbfb8aa3b, v58
	v_mul_f32_e32 v67, 0xbfb8aa3b, v59
	v_exp_f32_e32 v66, v66
	v_exp_f32_e32 v67, v67
	v_rcp_f32_e32 v62, v62
	v_rcp_f32_e32 v63, v63
	v_add_f32_e32 v66, 1.0, v66
	v_add_f32_e32 v67, 1.0, v67
	v_rcp_f32_e32 v66, v66
	v_rcp_f32_e32 v67, v67
	v_mul_f32_e32 v56, v56, v62
	v_mul_f32_e32 v57, v57, v63
	v_mul_f32_e32 v54, v60, v54
	v_mul_f32_e32 v55, v61, v55
	v_mul_f32_e32 v56, v56, v48
	v_mul_f32_e32 v57, v57, v49
	v_mul_f32_e32 v48, v58, v66
	v_mul_f32_e32 v49, v59, v67
	s_nop 0
	v_mul_f32_e32 v58, v48, v50
	v_mul_f32_e32 v59, v49, v51
	v_mul_f32_e32 v51, 0xbfb8aa3b, v44
	v_cvt_pk_bf16_f32 v48, v52, v53
	v_exp_f32_e32 v52, v51
	v_mul_f32_e32 v51, 0xbfb8aa3b, v45
	v_exp_f32_e32 v53, v51
	v_cvt_pk_bf16_f32 v49, v54, v55
	v_add_co_u32_e32 v54, vcc, s14, v142
	v_cvt_pk_bf16_f32 v50, v56, v57
	v_cvt_pk_bf16_f32 v51, v58, v59
	v_add_f32_e32 v52, 1.0, v52
	v_add_f32_e32 v53, 1.0, v53
	v_addc_co_u32_e32 v55, vcc, 0, v143, vcc
	v_rcp_f32_e32 v52, v52
	v_rcp_f32_e32 v53, v53
	global_store_dwordx4 v[54:55], v[48:51], off
	s_mov_b32 s14, 0xc6000
	v_mul_f32_e32 v44, v44, v52
	v_mul_f32_e32 v45, v45, v53
	v_mul_f32_e32 v48, 0xbfb8aa3b, v46
	v_mul_f32_e32 v49, 0xbfb8aa3b, v47
	v_exp_f32_e32 v48, v48
	v_exp_f32_e32 v49, v49
	v_mul_f32_e32 v36, v44, v36
	v_mul_f32_e32 v37, v45, v37
	v_add_f32_e32 v44, 1.0, v48
	v_add_f32_e32 v45, 1.0, v49
	v_mul_f32_e32 v48, 0xbfb8aa3b, v40
	v_mul_f32_e32 v49, 0xbfb8aa3b, v41
	v_rcp_f32_e32 v44, v44
	v_rcp_f32_e32 v45, v45
	v_exp_f32_e32 v48, v48
	v_exp_f32_e32 v49, v49
	v_mul_f32_e32 v44, v46, v44
	v_mul_f32_e32 v45, v47, v45
	v_add_f32_e32 v46, 1.0, v48
	v_add_f32_e32 v47, 1.0, v49
	v_mul_f32_e32 v48, 0xbfb8aa3b, v42
	v_mul_f32_e32 v49, 0xbfb8aa3b, v43
	v_exp_f32_e32 v48, v48
	v_exp_f32_e32 v49, v49
	v_rcp_f32_e32 v46, v46
	v_rcp_f32_e32 v47, v47
	v_add_f32_e32 v48, 1.0, v48
	v_add_f32_e32 v49, 1.0, v49
; __device__ __forceinline__ unsigned cvt_pk_bf16(float lo, float hi) { f32x2 v = {lo, hi}; bf16x2_t b = __builtin_convertvector(v, bf16x2_t); return __builtin_bit_cast(unsigned, b); }
; __device__ __forceinline__ float sigmoidf_(float x) { return __builtin_amdgcn_rcpf(1.0f + __builtin_amdgcn_exp2f(-1.4426950408889634f * x)); }
;     __device__ __forceinline__ void operator()(const f32x4 (&acc)[2][2][4][2], const Unit& u, int wr, int wc, int fr, int fq) const {
;     ...
;         for (int ai = 0; ai < 2; ++ai)
; #pragma unroll
;             for (int m = 0; m < 4; ++m) { float hv[8];
; #pragma unroll
;                 for (int n = 0; n < 2; ++n)
; #pragma unroll
;                     for (int i = 0; i < 4; ++i) { const float gt = acc[ai][0][m][n][i], up = acc[ai][1][m][n][i]; hv[n * 4 + i] = gt * sigmoidf_(gt) * up; }
;                 u32x4 w; w.x = cvt_pk_bf16(hv[0], hv[1]); w.y = cvt_pk_bf16(hv[2], hv[3]); w.z = cvt_pk_bf16(hv[4], hv[5]); w.w = cvt_pk_bf16(hv[6], hv[7]);
;                 *(u32x4*)(base + (size_t)(ai * HALF + m * 16) * 2816) = w; }
	v_rcp_f32_e32 v48, v48
	v_rcp_f32_e32 v49, v49
	v_mul_f32_e32 v40, v40, v46
	v_mul_f32_e32 v41, v41, v47
	v_mul_f32_e32 v38, v44, v38
	v_mul_f32_e32 v39, v45, v39
	v_mul_f32_e32 v40, v40, v32
	v_mul_f32_e32 v41, v41, v33
	v_mul_f32_e32 v32, v42, v48
	v_mul_f32_e32 v33, v43, v49
	s_nop 0
	v_mul_f32_e32 v42, v32, v34
	v_mul_f32_e32 v43, v33, v35
	v_mul_f32_e32 v35, 0xbfb8aa3b, v28
	v_cvt_pk_bf16_f32 v32, v36, v37
	v_exp_f32_e32 v36, v35
	v_mul_f32_e32 v35, 0xbfb8aa3b, v29
	v_exp_f32_e32 v37, v35
	v_cvt_pk_bf16_f32 v33, v38, v39
	v_add_co_u32_e32 v38, vcc, s14, v142
	v_cvt_pk_bf16_f32 v34, v40, v41
	v_cvt_pk_bf16_f32 v35, v42, v43
	v_add_f32_e32 v36, 1.0, v36
	v_add_f32_e32 v37, 1.0, v37
	v_addc_co_u32_e32 v39, vcc, 0, v143, vcc
	v_rcp_f32_e32 v36, v36
	v_rcp_f32_e32 v37, v37
	global_store_dwordx4 v[38:39], v[32:35], off
	s_mov_b32 s14, 0xdc000
	v_mul_f32_e32 v28, v28, v36
	v_mul_f32_e32 v29, v29, v37
	v_mul_f32_e32 v32, 0xbfb8aa3b, v30
	v_mul_f32_e32 v33, 0xbfb8aa3b, v31
	v_exp_f32_e32 v32, v32
	v_exp_f32_e32 v33, v33
	v_mul_f32_e32 v20, v28, v20
	v_mul_f32_e32 v21, v29, v21
	v_add_f32_e32 v28, 1.0, v32
	v_add_f32_e32 v29, 1.0, v33
	v_mul_f32_e32 v32, 0xbfb8aa3b, v24
	v_mul_f32_e32 v33, 0xbfb8aa3b, v25
	v_rcp_f32_e32 v28, v28
	v_rcp_f32_e32 v29, v29
	v_exp_f32_e32 v32, v32
	v_exp_f32_e32 v33, v33
	v_mul_f32_e32 v28, v30, v28
	v_mul_f32_e32 v29, v31, v29
	v_add_f32_e32 v30, 1.0, v32
	v_add_f32_e32 v31, 1.0, v33
	v_mul_f32_e32 v32, 0xbfb8aa3b, v26
	v_mul_f32_e32 v33, 0xbfb8aa3b, v27
	v_exp_f32_e32 v32, v32
	v_exp_f32_e32 v33, v33
	v_rcp_f32_e32 v30, v30
	v_rcp_f32_e32 v31, v31
	v_add_f32_e32 v32, 1.0, v32
	v_add_f32_e32 v33, 1.0, v33
	v_rcp_f32_e32 v32, v32
	v_rcp_f32_e32 v33, v33
	v_mul_f32_e32 v24, v24, v30
	v_mul_f32_e32 v25, v25, v31
	v_mul_f32_e32 v22, v28, v22
	v_mul_f32_e32 v23, v29, v23
	v_mul_f32_e32 v24, v24, v16
	v_mul_f32_e32 v25, v25, v17
	v_mul_f32_e32 v16, v26, v32
	v_mul_f32_e32 v17, v27, v33
	s_nop 0
	v_mul_f32_e32 v26, v16, v18
	v_mul_f32_e32 v27, v17, v19
	v_mul_f32_e32 v19, 0xbfb8aa3b, v12
	v_cvt_pk_bf16_f32 v16, v20, v21
	v_exp_f32_e32 v20, v19
	v_mul_f32_e32 v19, 0xbfb8aa3b, v13
	v_exp_f32_e32 v21, v19
	v_cvt_pk_bf16_f32 v17, v22, v23
	v_add_co_u32_e32 v22, vcc, s14, v142
	v_cvt_pk_bf16_f32 v18, v24, v25
	v_cvt_pk_bf16_f32 v19, v26, v27
	v_add_f32_e32 v20, 1.0, v20
	v_add_f32_e32 v21, 1.0, v21
	v_addc_co_u32_e32 v23, vcc, 0, v143, vcc
	v_rcp_f32_e32 v20, v20
	v_rcp_f32_e32 v21, v21
	global_store_dwordx4 v[22:23], v[16:19], off
	s_mov_b64 s[14:15], -1
	v_mul_f32_e32 v12, v12, v20
	v_mul_f32_e32 v13, v13, v21
	v_mul_f32_e32 v16, 0xbfb8aa3b, v14
	v_mul_f32_e32 v17, 0xbfb8aa3b, v15
	v_exp_f32_e32 v16, v16
	v_exp_f32_e32 v17, v17
	v_mul_f32_e32 v4, v12, v4
	v_mul_f32_e32 v5, v13, v5
	v_add_f32_e32 v12, 1.0, v16
	v_add_f32_e32 v13, 1.0, v17
	v_mul_f32_e32 v16, 0xbfb8aa3b, v8
	v_mul_f32_e32 v17, 0xbfb8aa3b, v9
	v_rcp_f32_e32 v12, v12
	v_rcp_f32_e32 v13, v13
	v_exp_f32_e32 v16, v16
	v_exp_f32_e32 v17, v17
	v_mul_f32_e32 v12, v14, v12
	v_mul_f32_e32 v13, v15, v13
	v_add_f32_e32 v14, 1.0, v16
	v_add_f32_e32 v15, 1.0, v17
	v_mul_f32_e32 v16, 0xbfb8aa3b, v10
	v_mul_f32_e32 v17, 0xbfb8aa3b, v11
	v_exp_f32_e32 v16, v16
	v_exp_f32_e32 v17, v17
	v_rcp_f32_e32 v14, v14
	v_rcp_f32_e32 v15, v15
	v_add_f32_e32 v16, 1.0, v16
	v_add_f32_e32 v17, 1.0, v17
	v_rcp_f32_e32 v16, v16
	v_rcp_f32_e32 v17, v17
	v_mul_f32_e32 v8, v8, v14
	v_mul_f32_e32 v9, v9, v15
	v_mul_f32_e32 v6, v12, v6
	v_mul_f32_e32 v7, v13, v7
	v_mul_f32_e32 v8, v8, v0
	v_mul_f32_e32 v9, v9, v1
	v_mul_f32_e32 v0, v10, v16
	v_mul_f32_e32 v1, v11, v17
	s_nop 0
	v_mul_f32_e32 v10, v0, v2
	v_mul_f32_e32 v11, v1, v3
	v_cvt_pk_bf16_f32 v0, v4, v5
	v_add_co_u32_e32 v4, vcc, 0xf2000, v142
	v_cvt_pk_bf16_f32 v1, v6, v7
	v_cvt_pk_bf16_f32 v2, v8, v9
	v_cvt_pk_bf16_f32 v3, v10, v11
	v_addc_co_u32_e32 v5, vcc, 0, v143, vcc
	global_store_dwordx4 v[4:5], v[0:3], off
	s_cbranch_scc1 .LBB0_561
	s_andn2_b64 vcc, exec, s[0:1]
	s_cbranch_vccnz .LBB0_560
	s_barrier
	s_branch .LBB0_560

; __device__ __forceinline__ float bflo(unsigned u) { return __uint_as_float(u << 16); }
; __device__ __forceinline__ float bfhi(unsigned u) { return __uint_as_float(u & 0xffff0000u); }
; __device__ __forceinline__ void ln_panel(int pm, const float* resf, const bf16* rlo, const bf16* dlt, float* xo, const float* gam, const float* bet, bf16* xb, bf16* wlo, bool fin, float alpha) {
;     ...
;         for (int j = 0; j < 4; ++j) { f32x4 x; const u32x2 d = *(const u32x2*)(dlt + prow + 256 * j);
;             if (resf) x = *(const f32x4*)(resf + grow + 256 * j);
;             else { const u32x2 h = *(const u32x2*)(xb + grow + 256 * j), l = *(const u32x2*)(rlo + prow + 256 * j);
;                    x = (f32x4){bflo(h.x) + bflo(l.x), bfhi(h.x) + bfhi(l.x), bflo(h.y) + bflo(l.y), bfhi(h.y) + bfhi(l.y)}; }
;             v[j] = (f32x4){x.x * alpha + bflo(d.x), x.y * alpha + bfhi(d.x), x.z * alpha + bflo(d.y), x.w * alpha + bfhi(d.y)}; s += (v[j].x + v[j].y) + (v[j].z + v[j].w); }
;         const float mean = wave_sum(s) * (1.f / DM); float s2 = 0.f;
; #pragma unroll
;         for (int j = 0; j < 4; ++j) { v[j] = v[j] - mean; s2 += (v[j].x * v[j].x + v[j].y * v[j].y) + (v[j].z * v[j].z + v[j].w * v[j].w); }
;         const float rstd = 1.f / sqrtf(wave_sum(s2) * (1.f / DM) + LN_EPS);
.Lmy_ln2h_entry:
	v_lshlrev_b32_e32 v150, 16, v66
	v_and_b32_e32 v151, 0xffff0000, v66
	v_lshlrev_b32_e32 v152, 16, v74
	v_and_b32_e32 v153, 0xffff0000, v74
	v_add_f32_e32 v150, v150, v152
	v_add_f32_e32 v151, v151, v153
	v_lshlrev_b32_e32 v152, 16, v82
	v_and_b32_e32 v153, 0xffff0000, v82
	v_fma_f32 v114, v150, v164, v152
	v_fma_f32 v115, v151, v165, v153
	v_lshlrev_b32_e32 v150, 16, v67
	v_and_b32_e32 v151, 0xffff0000, v67
	v_lshlrev_b32_e32 v152, 16, v75
	v_and_b32_e32 v153, 0xffff0000, v75
	v_add_f32_e32 v150, v150, v152
	v_add_f32_e32 v151, v151, v153
	v_lshlrev_b32_e32 v152, 16, v83
	v_and_b32_e32 v153, 0xffff0000, v83
	v_fma_f32 v116, v150, v164, v152
	v_fma_f32 v117, v151, v165, v153
	v_lshlrev_b32_e32 v150, 16, v68
	v_and_b32_e32 v151, 0xffff0000, v68
	v_lshlrev_b32_e32 v152, 16, v76
	v_and_b32_e32 v153, 0xffff0000, v76
	v_add_f32_e32 v150, v150, v152
	v_add_f32_e32 v151, v151, v153
	v_lshlrev_b32_e32 v152, 16, v84
	v_and_b32_e32 v153, 0xffff0000, v84
	v_fma_f32 v118, v150, v164, v152
	v_fma_f32 v119, v151, v165, v153
	v_lshlrev_b32_e32 v150, 16, v69
	v_and_b32_e32 v151, 0xffff0000, v69
	v_lshlrev_b32_e32 v152, 16, v77
	v_and_b32_e32 v153, 0xffff0000, v77
	v_add_f32_e32 v150, v150, v152
	v_add_f32_e32 v151, v151, v153
	v_lshlrev_b32_e32 v152, 16, v85
	v_and_b32_e32 v153, 0xffff0000, v85
	v_fma_f32 v120, v150, v164, v152
	v_fma_f32 v121, v151, v165, v153
	v_lshlrev_b32_e32 v150, 16, v70
	v_and_b32_e32 v151, 0xffff0000, v70
	v_lshlrev_b32_e32 v152, 16, v78
	v_and_b32_e32 v153, 0xffff0000, v78
	v_add_f32_e32 v150, v150, v152
	v_add_f32_e32 v151, v151, v153
	v_lshlrev_b32_e32 v152, 16, v86
	v_and_b32_e32 v153, 0xffff0000, v86
	v_fma_f32 v122, v150, v164, v152
	v_fma_f32 v123, v151, v165, v153
	v_lshlrev_b32_e32 v150, 16, v71
	v_and_b32_e32 v151, 0xffff0000, v71
	v_lshlrev_b32_e32 v152, 16, v79
	v_and_b32_e32 v153, 0xffff0000, v79
	v_add_f32_e32 v150, v150, v152
	v_add_f32_e32 v151, v151, v153
	v_lshlrev_b32_e32 v152, 16, v87
	v_and_b32_e32 v153, 0xffff0000, v87
	v_fma_f32 v124, v150, v164, v152
	v_fma_f32 v125, v151, v165, v153
	v_lshlrev_b32_e32 v150, 16, v72
	v_and_b32_e32 v151, 0xffff0000, v72
	v_lshlrev_b32_e32 v152, 16, v80
	v_and_b32_e32 v153, 0xffff0000, v80
	v_add_f32_e32 v150, v150, v152
	v_add_f32_e32 v151, v151, v153
	v_lshlrev_b32_e32 v152, 16, v88
	v_and_b32_e32 v153, 0xffff0000, v88
	v_fma_f32 v126, v150, v164, v152
	v_fma_f32 v127, v151, v165, v153
	v_lshlrev_b32_e32 v150, 16, v73
	v_and_b32_e32 v151, 0xffff0000, v73
	v_lshlrev_b32_e32 v152, 16, v81
	v_and_b32_e32 v153, 0xffff0000, v81
	v_add_f32_e32 v150, v150, v152
	v_add_f32_e32 v151, v151, v153
	v_lshlrev_b32_e32 v152, 16, v89
	v_and_b32_e32 v153, 0xffff0000, v89
	v_fma_f32 v128, v150, v164, v152
	v_fma_f32 v129, v151, v165, v153
	v_add_f32_e32 v154, v114, v116
	v_add_f32_e32 v155, v115, v117
	v_add_f32_e32 v156, v118, v120
	v_add_f32_e32 v157, v119, v121
	v_add_f32_e32 v154, v154, v156
	v_add_f32_e32 v155, v155, v157
	v_add_f32_e32 v156, v122, v124
	v_add_f32_e32 v157, v123, v125
	v_add_f32_e32 v154, v154, v156
	v_add_f32_e32 v155, v155, v157
	v_add_f32_e32 v156, v126, v128
	v_add_f32_e32 v157, v127, v129
	v_add_f32_e32 v154, v154, v156
	v_add_f32_e32 v155, v155, v157
	v_add_f32_e32 v154, v154, v155
	s_nop 1
	v_add_f32_dpp v160, v154, v154 quad_perm:[1,0,3,2] row_mask:0xf bank_mask:0xf
	s_nop 1
	v_add_f32_dpp v160, v160, v160 quad_perm:[2,3,0,1] row_mask:0xf bank_mask:0xf
	s_nop 1
	v_add_f32_dpp v160, v160, v160 row_half_mirror row_mask:0xf bank_mask:0xf
	s_nop 1
	v_add_f32_dpp v160, v160, v160 row_mirror row_mask:0xf bank_mask:0xf
	s_nop 1
	v_add_f32_dpp v160, v160, v160 row_bcast:15 row_mask:0xa bank_mask:0xf
	s_nop 1
	v_add_f32_dpp v160, v160, v160 row_bcast:31 row_mask:0xc bank_mask:0xf
	s_nop 1
	v_readlane_b32 s0, v160, 63
	s_nop 2
	v_mov_b32_e32 v170, s0
	v_mul_f32_e32 v156, 0xba800000, v170
	v_mul_f32_e32 v157, 0xba800000, v170
	v_add_f32_e32 v114, v114, v156
	v_add_f32_e32 v115, v115, v157
	v_add_f32_e32 v116, v116, v156
	v_add_f32_e32 v117, v117, v157
	v_add_f32_e32 v118, v118, v156
	v_add_f32_e32 v119, v119, v157
	v_add_f32_e32 v120, v120, v156
	v_add_f32_e32 v121, v121, v157
	v_add_f32_e32 v122, v122, v156
	v_add_f32_e32 v123, v123, v157
	v_add_f32_e32 v124, v124, v156
	v_add_f32_e32 v125, v125, v157
	v_add_f32_e32 v126, v126, v156
	v_add_f32_e32 v127, v127, v157
	v_add_f32_e32 v128, v128, v156
	v_add_f32_e32 v129, v129, v157
	v_mul_f32_e32 v154, v114, v114
	v_mul_f32_e32 v155, v115, v115
	v_fma_f32 v154, v116, v116, v154
	v_fma_f32 v155, v117, v117, v155
	v_fma_f32 v154, v118, v118, v154
	v_fma_f32 v155, v119, v119, v155
	v_fma_f32 v154, v120, v120, v154
	v_fma_f32 v155, v121, v121, v155
	v_fma_f32 v154, v122, v122, v154
	v_fma_f32 v155, v123, v123, v155
	v_fma_f32 v154, v124, v124, v154
	v_fma_f32 v155, v125, v125, v155
	v_fma_f32 v154, v126, v126, v154
	v_fma_f32 v155, v127, v127, v155
	v_fma_f32 v154, v128, v128, v154
	v_fma_f32 v155, v129, v129, v155
	v_add_f32_e32 v154, v154, v155
	s_nop 1
	v_add_f32_dpp v160, v154, v154 quad_perm:[1,0,3,2] row_mask:0xf bank_mask:0xf
	s_nop 1
	v_add_f32_dpp v160, v160, v160 quad_perm:[2,3,0,1] row_mask:0xf bank_mask:0xf
	s_nop 1
	v_add_f32_dpp v160, v160, v160 row_half_mirror row_mask:0xf bank_mask:0xf
	s_nop 1
	v_add_f32_dpp v160, v160, v160 row_mirror row_mask:0xf bank_mask:0xf
	s_nop 1
	v_add_f32_dpp v160, v160, v160 row_bcast:15 row_mask:0xa bank_mask:0xf
	s_nop 1
	v_add_f32_dpp v160, v160, v160 row_bcast:31 row_mask:0xc bank_mask:0xf
	s_nop 1
	v_readlane_b32 s0, v160, 63
	s_nop 2
	v_mov_b32_e32 v170, s0
	v_fmamk_f32 v154, v170, 0x3a800000, v166
	s_mov_b32 s0, 0xf800000
	v_mul_f32_e32 v155, 0x4f800000, v154
; __device__ __forceinline__ unsigned pk2(float lo, float hi) { return pg8::cvt_pk_bf16(lo, hi); }
; __device__ __forceinline__ float bflo(unsigned u) { return __uint_as_float(u << 16); }
; __device__ __forceinline__ float bfhi(unsigned u) { return __uint_as_float(u & 0xffff0000u); }
; __device__ __forceinline__ void ln_panel(int pm, const float* resf, const bf16* rlo, const bf16* dlt, float* xo, const float* gam, const float* bet, bf16* xb, bf16* wlo, bool fin, float alpha) {
;     ...
;         const float rstd = 1.f / sqrtf(wave_sum(s2) * (1.f / DM) + LN_EPS);
; #pragma unroll
;         for (int j = 0; j < 4; ++j) { const f32x4 o = v[j] * rstd * gv[j] + bv[j];
;             if (fin) *(f32x4*)(xo + grow + 256 * j) = o;
;             else { u32x2 w; w.x = pk2(o.x, o.y); w.y = pk2(o.z, o.w); *(u32x2*)(xb + grow + 256 * j) = w;
;                    u32x2 q; q.x = pk2(o.x - bflo(w.x), o.y - bfhi(w.x)); q.y = pk2(o.z - bflo(w.y), o.w - bfhi(w.y)); *(u32x2*)(wlo + prow + 256 * j) = q; } }
	v_cmp_gt_f32_e32 vcc, s0, v154
	s_nop 1
	v_cndmask_b32_e32 v154, v154, v155, vcc
	v_sqrt_f32_e32 v155, v154
	s_nop 0
	v_add_u32_e32 v156, -1, v155
	v_fma_f32 v157, -v156, v155, v154
	v_cmp_ge_f32_e64 s[0:1], 0, v157
	v_add_u32_e32 v157, 1, v155
	s_nop 0
	v_cndmask_b32_e64 v156, v155, v156, s[0:1]
	v_fma_f32 v155, -v157, v155, v154
	v_cmp_lt_f32_e64 s[0:1], 0, v155
	s_nop 1
	v_cndmask_b32_e64 v155, v156, v157, s[0:1]
	v_mul_f32_e32 v156, 0x37800000, v155
	v_cndmask_b32_e32 v155, v155, v156, vcc
	v_cmp_class_f32_e32 vcc, v154, v167
	s_nop 1
	v_cndmask_b32_e32 v154, v155, v154, vcc
	v_div_scale_f32 v155, s[0:1], v154, v154, 1.0
	v_rcp_f32_e32 v156, v155
	s_nop 0
	v_fma_f32 v157, -v155, v156, 1.0
	v_fmac_f32_e32 v156, v157, v156
	v_div_scale_f32 v157, vcc, 1.0, v154, 1.0
	v_mul_f32_e32 v158, v157, v156
	v_fma_f32 v159, -v155, v158, v157
	v_fmac_f32_e32 v158, v159, v156
	v_fma_f32 v155, -v155, v158, v157
	s_nop 0
	v_div_fmas_f32 v155, v155, v156, v158
	v_div_fixup_f32 v168, v155, v154, 1.0
	s_add_i32 s0, s98, 0
	s_lshl_b32 s0, s0, 11
	s_mov_b32 s1, 0
	v_lshl_add_u64 v[184:185], s[0:1], 0, v[172:173]
	v_lshl_add_u64 v[186:187], s[0:1], 0, v[180:181]
	v_mul_f32_e32 v150, v114, v168
	v_mul_f32_e32 v151, v115, v168
	v_fma_f32 v150, v0, v150, v8
	v_fma_f32 v151, v1, v151, v9
	v_mul_f32_e32 v152, v116, v168
	v_mul_f32_e32 v153, v117, v168
	v_fma_f32 v152, v2, v152, v10
	v_fma_f32 v153, v3, v153, v11
	v_cvt_pk_bf16_f32 v190, v150, v151
	v_cvt_pk_bf16_f32 v191, v152, v153
	v_lshlrev_b32_e32 v154, 16, v190
	v_and_b32_e32 v155, 0xffff0000, v190
	v_sub_f32_e32 v150, v150, v154
	v_sub_f32_e32 v151, v151, v155
	v_cvt_pk_bf16_f32 v198, v150, v151
	v_lshlrev_b32_e32 v154, 16, v191
	v_and_b32_e32 v155, 0xffff0000, v191
	v_sub_f32_e32 v152, v152, v154
	v_sub_f32_e32 v153, v153, v155
	v_cvt_pk_bf16_f32 v199, v152, v153
	v_mul_f32_e32 v150, v118, v168
	v_mul_f32_e32 v151, v119, v168
	v_fma_f32 v150, v4, v150, v12
	v_fma_f32 v151, v5, v151, v13
	v_mul_f32_e32 v152, v120, v168
	v_mul_f32_e32 v153, v121, v168
	v_fma_f32 v152, v6, v152, v14
	v_fma_f32 v153, v7, v153, v15
	v_cvt_pk_bf16_f32 v192, v150, v151
	v_cvt_pk_bf16_f32 v193, v152, v153
	v_lshlrev_b32_e32 v154, 16, v192
	v_and_b32_e32 v155, 0xffff0000, v192
	v_sub_f32_e32 v150, v150, v154
	v_sub_f32_e32 v151, v151, v155
	v_cvt_pk_bf16_f32 v200, v150, v151
	v_lshlrev_b32_e32 v154, 16, v193
	v_and_b32_e32 v155, 0xffff0000, v193
	v_sub_f32_e32 v152, v152, v154
	v_sub_f32_e32 v153, v153, v155
	v_cvt_pk_bf16_f32 v201, v152, v153
	v_mul_f32_e32 v150, v122, v168
	v_mul_f32_e32 v151, v123, v168
	v_fma_f32 v150, v16, v150, v24
	v_fma_f32 v151, v17, v151, v25
	v_mul_f32_e32 v152, v124, v168
	v_mul_f32_e32 v153, v125, v168
	v_fma_f32 v152, v18, v152, v26
	v_fma_f32 v153, v19, v153, v27
	v_cvt_pk_bf16_f32 v194, v150, v151
	v_cvt_pk_bf16_f32 v195, v152, v153
	v_lshlrev_b32_e32 v154, 16, v194
	v_and_b32_e32 v155, 0xffff0000, v194
	v_sub_f32_e32 v150, v150, v154
	v_sub_f32_e32 v151, v151, v155
	v_cvt_pk_bf16_f32 v202, v150, v151
	v_lshlrev_b32_e32 v154, 16, v195
	v_and_b32_e32 v155, 0xffff0000, v195
	v_sub_f32_e32 v152, v152, v154
	v_sub_f32_e32 v153, v153, v155
	v_cvt_pk_bf16_f32 v203, v152, v153
	v_mul_f32_e32 v150, v126, v168
	v_mul_f32_e32 v151, v127, v168
	v_fma_f32 v150, v20, v150, v28
	v_fma_f32 v151, v21, v151, v29
	v_mul_f32_e32 v152, v128, v168
	v_mul_f32_e32 v153, v129, v168
	v_fma_f32 v152, v22, v152, v30
	v_fma_f32 v153, v23, v153, v31
	v_cvt_pk_bf16_f32 v196, v150, v151
	v_cvt_pk_bf16_f32 v197, v152, v153
	v_lshlrev_b32_e32 v154, 16, v196
	v_and_b32_e32 v155, 0xffff0000, v196
	v_sub_f32_e32 v150, v150, v154
	v_sub_f32_e32 v151, v151, v155
	v_cvt_pk_bf16_f32 v204, v150, v151
	v_lshlrev_b32_e32 v154, 16, v197
	v_and_b32_e32 v155, 0xffff0000, v197
	v_sub_f32_e32 v152, v152, v154
	v_sub_f32_e32 v153, v153, v155
	v_cvt_pk_bf16_f32 v205, v152, v153
	global_store_dwordx2 v[184:185], v[190:191], off offset:-1024
	global_store_dwordx2 v[184:185], v[192:193], off offset:-512
	global_store_dwordx2 v[184:185], v[194:195], off offset:0
	global_store_dwordx2 v[184:185], v[196:197], off offset:512
	global_store_dwordx2 v[186:187], v[198:199], off offset:0
	global_store_dwordx2 v[186:187], v[200:201], off offset:512
	global_store_dwordx2 v[186:187], v[202:203], off offset:1024
	global_store_dwordx2 v[186:187], v[204:205], off offset:1536
	s_add_i32 s0, s98, 2
	s_min_u32 s0, s0, 31
	s_lshl_b32 s0, s0, 11
	s_mov_b32 s1, 0
	v_lshl_add_u64 v[184:185], s[0:1], 0, v[178:179]
	v_lshl_add_u64 v[186:187], s[0:1], 0, v[172:173]
	v_lshl_add_u64 v[188:189], s[0:1], 0, v[176:177]
	global_load_dwordx2 v[82:83], v[184:185], off offset:-1024
	global_load_dwordx2 v[84:85], v[184:185], off offset:-512
	global_load_dwordx2 v[86:87], v[184:185], off offset:0
	global_load_dwordx2 v[88:89], v[184:185], off offset:512
	global_load_dwordx2 v[66:67], v[186:187], off offset:-1024
	global_load_dwordx2 v[68:69], v[186:187], off offset:-512
	global_load_dwordx2 v[70:71], v[186:187], off offset:0
	global_load_dwordx2 v[72:73], v[186:187], off offset:512
	global_load_dwordx2 v[74:75], v[188:189], off offset:-1024
	global_load_dwordx2 v[76:77], v[188:189], off offset:-512
	global_load_dwordx2 v[78:79], v[188:189], off offset:0
	global_load_dwordx2 v[80:81], v[188:189], off offset:512
	s_waitcnt vmcnt(20)
; __device__ __forceinline__ float bflo(unsigned u) { return __uint_as_float(u << 16); }
; __device__ __forceinline__ float bfhi(unsigned u) { return __uint_as_float(u & 0xffff0000u); }
; __device__ __forceinline__ void ln_panel(int pm, const float* resf, const bf16* rlo, const bf16* dlt, float* xo, const float* gam, const float* bet, bf16* xb, bf16* wlo, bool fin, float alpha) {
;     ...
;         for (int j = 0; j < 4; ++j) { f32x4 x; const u32x2 d = *(const u32x2*)(dlt + prow + 256 * j);
;             if (resf) x = *(const f32x4*)(resf + grow + 256 * j);
;             else { const u32x2 h = *(const u32x2*)(xb + grow + 256 * j), l = *(const u32x2*)(rlo + prow + 256 * j);
;                    x = (f32x4){bflo(h.x) + bflo(l.x), bfhi(h.x) + bfhi(l.x), bflo(h.y) + bflo(l.y), bfhi(h.y) + bfhi(l.y)}; }
;             v[j] = (f32x4){x.x * alpha + bflo(d.x), x.y * alpha + bfhi(d.x), x.z * alpha + bflo(d.y), x.w * alpha + bfhi(d.y)}; s += (v[j].x + v[j].y) + (v[j].z + v[j].w); }
;         const float mean = wave_sum(s) * (1.f / DM); float s2 = 0.f;
; #pragma unroll
;         for (int j = 0; j < 4; ++j) { v[j] = v[j] - mean; s2 += (v[j].x * v[j].x + v[j].y * v[j].y) + (v[j].z * v[j].z + v[j].w * v[j].w); }
;         const float rstd = 1.f / sqrtf(wave_sum(s2) * (1.f / DM) + LN_EPS);
	v_lshlrev_b32_e32 v150, 16, v90
	v_and_b32_e32 v151, 0xffff0000, v90
	v_lshlrev_b32_e32 v152, 16, v98
	v_and_b32_e32 v153, 0xffff0000, v98
	v_add_f32_e32 v150, v150, v152
	v_add_f32_e32 v151, v151, v153
	v_lshlrev_b32_e32 v152, 16, v106
	v_and_b32_e32 v153, 0xffff0000, v106
	v_fma_f32 v114, v150, v164, v152
	v_fma_f32 v115, v151, v165, v153
	v_lshlrev_b32_e32 v150, 16, v91
	v_and_b32_e32 v151, 0xffff0000, v91
	v_lshlrev_b32_e32 v152, 16, v99
	v_and_b32_e32 v153, 0xffff0000, v99
	v_add_f32_e32 v150, v150, v152
	v_add_f32_e32 v151, v151, v153
	v_lshlrev_b32_e32 v152, 16, v107
	v_and_b32_e32 v153, 0xffff0000, v107
	v_fma_f32 v116, v150, v164, v152
	v_fma_f32 v117, v151, v165, v153
	v_lshlrev_b32_e32 v150, 16, v92
	v_and_b32_e32 v151, 0xffff0000, v92
	v_lshlrev_b32_e32 v152, 16, v100
	v_and_b32_e32 v153, 0xffff0000, v100
	v_add_f32_e32 v150, v150, v152
	v_add_f32_e32 v151, v151, v153
	v_lshlrev_b32_e32 v152, 16, v108
	v_and_b32_e32 v153, 0xffff0000, v108
	v_fma_f32 v118, v150, v164, v152
	v_fma_f32 v119, v151, v165, v153
	v_lshlrev_b32_e32 v150, 16, v93
	v_and_b32_e32 v151, 0xffff0000, v93
	v_lshlrev_b32_e32 v152, 16, v101
	v_and_b32_e32 v153, 0xffff0000, v101
	v_add_f32_e32 v150, v150, v152
	v_add_f32_e32 v151, v151, v153
	v_lshlrev_b32_e32 v152, 16, v109
	v_and_b32_e32 v153, 0xffff0000, v109
	v_fma_f32 v120, v150, v164, v152
	v_fma_f32 v121, v151, v165, v153
	v_lshlrev_b32_e32 v150, 16, v94
	v_and_b32_e32 v151, 0xffff0000, v94
	v_lshlrev_b32_e32 v152, 16, v102
	v_and_b32_e32 v153, 0xffff0000, v102
	v_add_f32_e32 v150, v150, v152
	v_add_f32_e32 v151, v151, v153
	v_lshlrev_b32_e32 v152, 16, v110
	v_and_b32_e32 v153, 0xffff0000, v110
	v_fma_f32 v122, v150, v164, v152
	v_fma_f32 v123, v151, v165, v153
	v_lshlrev_b32_e32 v150, 16, v95
	v_and_b32_e32 v151, 0xffff0000, v95
	v_lshlrev_b32_e32 v152, 16, v103
	v_and_b32_e32 v153, 0xffff0000, v103
	v_add_f32_e32 v150, v150, v152
	v_add_f32_e32 v151, v151, v153
	v_lshlrev_b32_e32 v152, 16, v111
	v_and_b32_e32 v153, 0xffff0000, v111
	v_fma_f32 v124, v150, v164, v152
	v_fma_f32 v125, v151, v165, v153
	v_lshlrev_b32_e32 v150, 16, v96
	v_and_b32_e32 v151, 0xffff0000, v96
	v_lshlrev_b32_e32 v152, 16, v104
	v_and_b32_e32 v153, 0xffff0000, v104
	v_add_f32_e32 v150, v150, v152
	v_add_f32_e32 v151, v151, v153
	v_lshlrev_b32_e32 v152, 16, v112
	v_and_b32_e32 v153, 0xffff0000, v112
	v_fma_f32 v126, v150, v164, v152
	v_fma_f32 v127, v151, v165, v153
	v_lshlrev_b32_e32 v150, 16, v97
	v_and_b32_e32 v151, 0xffff0000, v97
	v_lshlrev_b32_e32 v152, 16, v105
	v_and_b32_e32 v153, 0xffff0000, v105
	v_add_f32_e32 v150, v150, v152
	v_add_f32_e32 v151, v151, v153
	v_lshlrev_b32_e32 v152, 16, v113
	v_and_b32_e32 v153, 0xffff0000, v113
	v_fma_f32 v128, v150, v164, v152
	v_fma_f32 v129, v151, v165, v153
	v_add_f32_e32 v154, v114, v116
	v_add_f32_e32 v155, v115, v117
	v_add_f32_e32 v156, v118, v120
	v_add_f32_e32 v157, v119, v121
	v_add_f32_e32 v154, v154, v156
	v_add_f32_e32 v155, v155, v157
	v_add_f32_e32 v156, v122, v124
	v_add_f32_e32 v157, v123, v125
	v_add_f32_e32 v154, v154, v156
	v_add_f32_e32 v155, v155, v157
	v_add_f32_e32 v156, v126, v128
	v_add_f32_e32 v157, v127, v129
	v_add_f32_e32 v154, v154, v156
	v_add_f32_e32 v155, v155, v157
	v_add_f32_e32 v154, v154, v155
	s_nop 1
	v_add_f32_dpp v160, v154, v154 quad_perm:[1,0,3,2] row_mask:0xf bank_mask:0xf
	s_nop 1
	v_add_f32_dpp v160, v160, v160 quad_perm:[2,3,0,1] row_mask:0xf bank_mask:0xf
	s_nop 1
	v_add_f32_dpp v160, v160, v160 row_half_mirror row_mask:0xf bank_mask:0xf
	s_nop 1
	v_add_f32_dpp v160, v160, v160 row_mirror row_mask:0xf bank_mask:0xf
	s_nop 1
	v_add_f32_dpp v160, v160, v160 row_bcast:15 row_mask:0xa bank_mask:0xf
	s_nop 1
	v_add_f32_dpp v160, v160, v160 row_bcast:31 row_mask:0xc bank_mask:0xf
	s_nop 1
	v_readlane_b32 s0, v160, 63
	s_nop 2
	v_mov_b32_e32 v170, s0
	v_mul_f32_e32 v156, 0xba800000, v170
	v_mul_f32_e32 v157, 0xba800000, v170
	v_add_f32_e32 v114, v114, v156
	v_add_f32_e32 v115, v115, v157
	v_add_f32_e32 v116, v116, v156
	v_add_f32_e32 v117, v117, v157
	v_add_f32_e32 v118, v118, v156
	v_add_f32_e32 v119, v119, v157
	v_add_f32_e32 v120, v120, v156
	v_add_f32_e32 v121, v121, v157
	v_add_f32_e32 v122, v122, v156
	v_add_f32_e32 v123, v123, v157
	v_add_f32_e32 v124, v124, v156
	v_add_f32_e32 v125, v125, v157
	v_add_f32_e32 v126, v126, v156
	v_add_f32_e32 v127, v127, v157
	v_add_f32_e32 v128, v128, v156
	v_add_f32_e32 v129, v129, v157
	v_mul_f32_e32 v154, v114, v114
	v_mul_f32_e32 v155, v115, v115
	v_fma_f32 v154, v116, v116, v154
	v_fma_f32 v155, v117, v117, v155
	v_fma_f32 v154, v118, v118, v154
	v_fma_f32 v155, v119, v119, v155
	v_fma_f32 v154, v120, v120, v154
	v_fma_f32 v155, v121, v121, v155
	v_fma_f32 v154, v122, v122, v154
	v_fma_f32 v155, v123, v123, v155
	v_fma_f32 v154, v124, v124, v154
	v_fma_f32 v155, v125, v125, v155
	v_fma_f32 v154, v126, v126, v154
	v_fma_f32 v155, v127, v127, v155
	v_fma_f32 v154, v128, v128, v154
	v_fma_f32 v155, v129, v129, v155
	v_add_f32_e32 v154, v154, v155
	s_nop 1
	v_add_f32_dpp v160, v154, v154 quad_perm:[1,0,3,2] row_mask:0xf bank_mask:0xf
	s_nop 1
	v_add_f32_dpp v160, v160, v160 quad_perm:[2,3,0,1] row_mask:0xf bank_mask:0xf
	s_nop 1
	v_add_f32_dpp v160, v160, v160 row_half_mirror row_mask:0xf bank_mask:0xf
	s_nop 1
	v_add_f32_dpp v160, v160, v160 row_mirror row_mask:0xf bank_mask:0xf
	s_nop 1
	v_add_f32_dpp v160, v160, v160 row_bcast:15 row_mask:0xa bank_mask:0xf
	s_nop 1
	v_add_f32_dpp v160, v160, v160 row_bcast:31 row_mask:0xc bank_mask:0xf
	s_nop 1
	v_readlane_b32 s0, v160, 63
	s_nop 2
; __device__ __forceinline__ unsigned pk2(float lo, float hi) { return pg8::cvt_pk_bf16(lo, hi); }
; __device__ __forceinline__ float bflo(unsigned u) { return __uint_as_float(u << 16); }
; __device__ __forceinline__ float bfhi(unsigned u) { return __uint_as_float(u & 0xffff0000u); }
; __device__ __forceinline__ void ln_panel(int pm, const float* resf, const bf16* rlo, const bf16* dlt, float* xo, const float* gam, const float* bet, bf16* xb, bf16* wlo, bool fin, float alpha) {
;     ...
;         for (int j = 0; j < 4; ++j) { f32x4 x; const u32x2 d = *(const u32x2*)(dlt + prow + 256 * j);
;             if (resf) x = *(const f32x4*)(resf + grow + 256 * j);
;             else { const u32x2 h = *(const u32x2*)(xb + grow + 256 * j), l = *(const u32x2*)(rlo + prow + 256 * j);
;     ...
;         const float rstd = 1.f / sqrtf(wave_sum(s2) * (1.f / DM) + LN_EPS);
; #pragma unroll
;         for (int j = 0; j < 4; ++j) { const f32x4 o = v[j] * rstd * gv[j] + bv[j];
;             if (fin) *(f32x4*)(xo + grow + 256 * j) = o;
;             else { u32x2 w; w.x = pk2(o.x, o.y); w.y = pk2(o.z, o.w); *(u32x2*)(xb + grow + 256 * j) = w;
;                    u32x2 q; q.x = pk2(o.x - bflo(w.x), o.y - bfhi(w.x)); q.y = pk2(o.z - bflo(w.y), o.w - bfhi(w.y)); *(u32x2*)(wlo + prow + 256 * j) = q; } }
	v_mov_b32_e32 v170, s0
	v_fmamk_f32 v154, v170, 0x3a800000, v166
	s_mov_b32 s0, 0xf800000
	v_mul_f32_e32 v155, 0x4f800000, v154
	v_cmp_gt_f32_e32 vcc, s0, v154
	s_nop 1
	v_cndmask_b32_e32 v154, v154, v155, vcc
	v_sqrt_f32_e32 v155, v154
	s_nop 0
	v_add_u32_e32 v156, -1, v155
	v_fma_f32 v157, -v156, v155, v154
	v_cmp_ge_f32_e64 s[0:1], 0, v157
	v_add_u32_e32 v157, 1, v155
	s_nop 0
	v_cndmask_b32_e64 v156, v155, v156, s[0:1]
	v_fma_f32 v155, -v157, v155, v154
	v_cmp_lt_f32_e64 s[0:1], 0, v155
	s_nop 1
	v_cndmask_b32_e64 v155, v156, v157, s[0:1]
	v_mul_f32_e32 v156, 0x37800000, v155
	v_cndmask_b32_e32 v155, v155, v156, vcc
	v_cmp_class_f32_e32 vcc, v154, v167
	s_nop 1
	v_cndmask_b32_e32 v154, v155, v154, vcc
	v_div_scale_f32 v155, s[0:1], v154, v154, 1.0
	v_rcp_f32_e32 v156, v155
	s_nop 0
	v_fma_f32 v157, -v155, v156, 1.0
	v_fmac_f32_e32 v156, v157, v156
	v_div_scale_f32 v157, vcc, 1.0, v154, 1.0
	v_mul_f32_e32 v158, v157, v156
	v_fma_f32 v159, -v155, v158, v157
	v_fmac_f32_e32 v158, v159, v156
	v_fma_f32 v155, -v155, v158, v157
	s_nop 0
	v_div_fmas_f32 v155, v155, v156, v158
	v_div_fixup_f32 v168, v155, v154, 1.0
	s_add_i32 s0, s98, 1
	s_lshl_b32 s0, s0, 11
	s_mov_b32 s1, 0
	v_lshl_add_u64 v[184:185], s[0:1], 0, v[172:173]
	v_lshl_add_u64 v[186:187], s[0:1], 0, v[180:181]
	v_mul_f32_e32 v150, v114, v168
	v_mul_f32_e32 v151, v115, v168
	v_fma_f32 v150, v0, v150, v8
	v_fma_f32 v151, v1, v151, v9
	v_mul_f32_e32 v152, v116, v168
	v_mul_f32_e32 v153, v117, v168
	v_fma_f32 v152, v2, v152, v10
	v_fma_f32 v153, v3, v153, v11
	v_cvt_pk_bf16_f32 v190, v150, v151
	v_cvt_pk_bf16_f32 v191, v152, v153
	v_lshlrev_b32_e32 v154, 16, v190
	v_and_b32_e32 v155, 0xffff0000, v190
	v_sub_f32_e32 v150, v150, v154
	v_sub_f32_e32 v151, v151, v155
	v_cvt_pk_bf16_f32 v198, v150, v151
	v_lshlrev_b32_e32 v154, 16, v191
	v_and_b32_e32 v155, 0xffff0000, v191
	v_sub_f32_e32 v152, v152, v154
	v_sub_f32_e32 v153, v153, v155
	v_cvt_pk_bf16_f32 v199, v152, v153
	v_mul_f32_e32 v150, v118, v168
	v_mul_f32_e32 v151, v119, v168
	v_fma_f32 v150, v4, v150, v12
	v_fma_f32 v151, v5, v151, v13
	v_mul_f32_e32 v152, v120, v168
	v_mul_f32_e32 v153, v121, v168
	v_fma_f32 v152, v6, v152, v14
	v_fma_f32 v153, v7, v153, v15
	v_cvt_pk_bf16_f32 v192, v150, v151
	v_cvt_pk_bf16_f32 v193, v152, v153
	v_lshlrev_b32_e32 v154, 16, v192
	v_and_b32_e32 v155, 0xffff0000, v192
	v_sub_f32_e32 v150, v150, v154
	v_sub_f32_e32 v151, v151, v155
	v_cvt_pk_bf16_f32 v200, v150, v151
	v_lshlrev_b32_e32 v154, 16, v193
	v_and_b32_e32 v155, 0xffff0000, v193
	v_sub_f32_e32 v152, v152, v154
	v_sub_f32_e32 v153, v153, v155
	v_cvt_pk_bf16_f32 v201, v152, v153
	v_mul_f32_e32 v150, v122, v168
	v_mul_f32_e32 v151, v123, v168
	v_fma_f32 v150, v16, v150, v24
	v_fma_f32 v151, v17, v151, v25
	v_mul_f32_e32 v152, v124, v168
	v_mul_f32_e32 v153, v125, v168
	v_fma_f32 v152, v18, v152, v26
	v_fma_f32 v153, v19, v153, v27
	v_cvt_pk_bf16_f32 v194, v150, v151
	v_cvt_pk_bf16_f32 v195, v152, v153
	v_lshlrev_b32_e32 v154, 16, v194
	v_and_b32_e32 v155, 0xffff0000, v194
	v_sub_f32_e32 v150, v150, v154
	v_sub_f32_e32 v151, v151, v155
	v_cvt_pk_bf16_f32 v202, v150, v151
	v_lshlrev_b32_e32 v154, 16, v195
	v_and_b32_e32 v155, 0xffff0000, v195
	v_sub_f32_e32 v152, v152, v154
	v_sub_f32_e32 v153, v153, v155
	v_cvt_pk_bf16_f32 v203, v152, v153
	v_mul_f32_e32 v150, v126, v168
	v_mul_f32_e32 v151, v127, v168
	v_fma_f32 v150, v20, v150, v28
	v_fma_f32 v151, v21, v151, v29
	v_mul_f32_e32 v152, v128, v168
	v_mul_f32_e32 v153, v129, v168
	v_fma_f32 v152, v22, v152, v30
	v_fma_f32 v153, v23, v153, v31
	v_cvt_pk_bf16_f32 v196, v150, v151
	v_cvt_pk_bf16_f32 v197, v152, v153
	v_lshlrev_b32_e32 v154, 16, v196
	v_and_b32_e32 v155, 0xffff0000, v196
	v_sub_f32_e32 v150, v150, v154
	v_sub_f32_e32 v151, v151, v155
	v_cvt_pk_bf16_f32 v204, v150, v151
	v_lshlrev_b32_e32 v154, 16, v197
	v_and_b32_e32 v155, 0xffff0000, v197
	v_sub_f32_e32 v152, v152, v154
	v_sub_f32_e32 v153, v153, v155
	v_cvt_pk_bf16_f32 v205, v152, v153
	global_store_dwordx2 v[184:185], v[190:191], off offset:-1024
	global_store_dwordx2 v[184:185], v[192:193], off offset:-512
	global_store_dwordx2 v[184:185], v[194:195], off offset:0
	global_store_dwordx2 v[184:185], v[196:197], off offset:512
	global_store_dwordx2 v[186:187], v[198:199], off offset:0
	global_store_dwordx2 v[186:187], v[200:201], off offset:512
	global_store_dwordx2 v[186:187], v[202:203], off offset:1024
	global_store_dwordx2 v[186:187], v[204:205], off offset:1536
	s_add_i32 s0, s98, 3
	s_min_u32 s0, s0, 31
	s_lshl_b32 s0, s0, 11
	s_mov_b32 s1, 0
	v_lshl_add_u64 v[184:185], s[0:1], 0, v[178:179]
	v_lshl_add_u64 v[186:187], s[0:1], 0, v[172:173]
	v_lshl_add_u64 v[188:189], s[0:1], 0, v[176:177]
	global_load_dwordx2 v[106:107], v[184:185], off offset:-1024
	global_load_dwordx2 v[108:109], v[184:185], off offset:-512
	global_load_dwordx2 v[110:111], v[184:185], off offset:0
	global_load_dwordx2 v[112:113], v[184:185], off offset:512
	global_load_dwordx2 v[90:91], v[186:187], off offset:-1024
	global_load_dwordx2 v[92:93], v[186:187], off offset:-512
	global_load_dwordx2 v[94:95], v[186:187], off offset:0
	global_load_dwordx2 v[96:97], v[186:187], off offset:512
	global_load_dwordx2 v[98:99], v[188:189], off offset:-1024
	global_load_dwordx2 v[100:101], v[188:189], off offset:-512
	global_load_dwordx2 v[102:103], v[188:189], off offset:0
	global_load_dwordx2 v[104:105], v[188:189], off offset:512
	s_add_i32 s98, s98, 2
	s_cmp_lt_u32 s98, 32
	s_cbranch_scc1 .Lmy_ln2h_loop
	s_waitcnt vmcnt(0)
	s_branch .LBB0_467

; __device__ __forceinline__ float bflo(unsigned u) { return __uint_as_float(u << 16); }
; __device__ __forceinline__ float bfhi(unsigned u) { return __uint_as_float(u & 0xffff0000u); }
; __device__ __forceinline__ void ln_panel(int pm, const float* resf, const bf16* rlo, const bf16* dlt, float* xo, const float* gam, const float* bet, bf16* xb, bf16* wlo, bool fin, float alpha) {
;     ...
;         for (int j = 0; j < 4; ++j) { f32x4 x; const u32x2 d = *(const u32x2*)(dlt + prow + 256 * j);
;             if (resf) x = *(const f32x4*)(resf + grow + 256 * j);
;             else { const u32x2 h = *(const u32x2*)(xb + grow + 256 * j), l = *(const u32x2*)(rlo + prow + 256 * j);
;                    x = (f32x4){bflo(h.x) + bflo(l.x), bfhi(h.x) + bfhi(l.x), bflo(h.y) + bflo(l.y), bfhi(h.y) + bfhi(l.y)}; }
;             v[j] = (f32x4){x.x * alpha + bflo(d.x), x.y * alpha + bfhi(d.x), x.z * alpha + bflo(d.y), x.w * alpha + bfhi(d.y)}; s += (v[j].x + v[j].y) + (v[j].z + v[j].w); }
;         const float mean = wave_sum(s) * (1.f / DM); float s2 = 0.f;
; #pragma unroll
;         for (int j = 0; j < 4; ++j) { v[j] = v[j] - mean; s2 += (v[j].x * v[j].x + v[j].y * v[j].y) + (v[j].z * v[j].z + v[j].w * v[j].w); }
;         const float rstd = 1.f / sqrtf(wave_sum(s2) * (1.f / DM) + LN_EPS);
.Lmy_ln2f_entry:
	v_lshlrev_b32_e32 v150, 16, v66
	v_and_b32_e32 v151, 0xffff0000, v66
	v_lshlrev_b32_e32 v152, 16, v74
	v_and_b32_e32 v153, 0xffff0000, v74
	v_add_f32_e32 v150, v150, v152
	v_add_f32_e32 v151, v151, v153
	v_lshlrev_b32_e32 v152, 16, v82
	v_and_b32_e32 v153, 0xffff0000, v82
	v_fma_f32 v114, v150, v164, v152
	v_fma_f32 v115, v151, v165, v153
	v_lshlrev_b32_e32 v150, 16, v67
	v_and_b32_e32 v151, 0xffff0000, v67
	v_lshlrev_b32_e32 v152, 16, v75
	v_and_b32_e32 v153, 0xffff0000, v75
	v_add_f32_e32 v150, v150, v152
	v_add_f32_e32 v151, v151, v153
	v_lshlrev_b32_e32 v152, 16, v83
	v_and_b32_e32 v153, 0xffff0000, v83
	v_fma_f32 v116, v150, v164, v152
	v_fma_f32 v117, v151, v165, v153
	v_lshlrev_b32_e32 v150, 16, v68
	v_and_b32_e32 v151, 0xffff0000, v68
	v_lshlrev_b32_e32 v152, 16, v76
	v_and_b32_e32 v153, 0xffff0000, v76
	v_add_f32_e32 v150, v150, v152
	v_add_f32_e32 v151, v151, v153
	v_lshlrev_b32_e32 v152, 16, v84
	v_and_b32_e32 v153, 0xffff0000, v84
	v_fma_f32 v118, v150, v164, v152
	v_fma_f32 v119, v151, v165, v153
	v_lshlrev_b32_e32 v150, 16, v69
	v_and_b32_e32 v151, 0xffff0000, v69
	v_lshlrev_b32_e32 v152, 16, v77
	v_and_b32_e32 v153, 0xffff0000, v77
	v_add_f32_e32 v150, v150, v152
	v_add_f32_e32 v151, v151, v153
	v_lshlrev_b32_e32 v152, 16, v85
	v_and_b32_e32 v153, 0xffff0000, v85
	v_fma_f32 v120, v150, v164, v152
	v_fma_f32 v121, v151, v165, v153
	v_lshlrev_b32_e32 v150, 16, v70
	v_and_b32_e32 v151, 0xffff0000, v70
	v_lshlrev_b32_e32 v152, 16, v78
	v_and_b32_e32 v153, 0xffff0000, v78
	v_add_f32_e32 v150, v150, v152
	v_add_f32_e32 v151, v151, v153
	v_lshlrev_b32_e32 v152, 16, v86
	v_and_b32_e32 v153, 0xffff0000, v86
	v_fma_f32 v122, v150, v164, v152
	v_fma_f32 v123, v151, v165, v153
	v_lshlrev_b32_e32 v150, 16, v71
	v_and_b32_e32 v151, 0xffff0000, v71
	v_lshlrev_b32_e32 v152, 16, v79
	v_and_b32_e32 v153, 0xffff0000, v79
	v_add_f32_e32 v150, v150, v152
	v_add_f32_e32 v151, v151, v153
	v_lshlrev_b32_e32 v152, 16, v87
	v_and_b32_e32 v153, 0xffff0000, v87
	v_fma_f32 v124, v150, v164, v152
	v_fma_f32 v125, v151, v165, v153
	v_lshlrev_b32_e32 v150, 16, v72
	v_and_b32_e32 v151, 0xffff0000, v72
	v_lshlrev_b32_e32 v152, 16, v80
	v_and_b32_e32 v153, 0xffff0000, v80
	v_add_f32_e32 v150, v150, v152
	v_add_f32_e32 v151, v151, v153
	v_lshlrev_b32_e32 v152, 16, v88
	v_and_b32_e32 v153, 0xffff0000, v88
	v_fma_f32 v126, v150, v164, v152
	v_fma_f32 v127, v151, v165, v153
	v_lshlrev_b32_e32 v150, 16, v73
	v_and_b32_e32 v151, 0xffff0000, v73
	v_lshlrev_b32_e32 v152, 16, v81
	v_and_b32_e32 v153, 0xffff0000, v81
	v_add_f32_e32 v150, v150, v152
	v_add_f32_e32 v151, v151, v153
	v_lshlrev_b32_e32 v152, 16, v89
	v_and_b32_e32 v153, 0xffff0000, v89
	v_fma_f32 v128, v150, v164, v152
	v_fma_f32 v129, v151, v165, v153
	v_add_f32_e32 v154, v114, v116
	v_add_f32_e32 v155, v115, v117
	v_add_f32_e32 v156, v118, v120
	v_add_f32_e32 v157, v119, v121
	v_add_f32_e32 v154, v154, v156
	v_add_f32_e32 v155, v155, v157
	v_add_f32_e32 v156, v122, v124
	v_add_f32_e32 v157, v123, v125
	v_add_f32_e32 v154, v154, v156
	v_add_f32_e32 v155, v155, v157
	v_add_f32_e32 v156, v126, v128
	v_add_f32_e32 v157, v127, v129
	v_add_f32_e32 v154, v154, v156
	v_add_f32_e32 v155, v155, v157
	v_add_f32_e32 v154, v154, v155
	s_nop 1
	v_add_f32_dpp v160, v154, v154 quad_perm:[1,0,3,2] row_mask:0xf bank_mask:0xf
	s_nop 1
	v_add_f32_dpp v160, v160, v160 quad_perm:[2,3,0,1] row_mask:0xf bank_mask:0xf
	s_nop 1
	v_add_f32_dpp v160, v160, v160 row_half_mirror row_mask:0xf bank_mask:0xf
	s_nop 1
	v_add_f32_dpp v160, v160, v160 row_mirror row_mask:0xf bank_mask:0xf
	s_nop 1
	v_add_f32_dpp v160, v160, v160 row_bcast:15 row_mask:0xa bank_mask:0xf
	s_nop 1
	v_add_f32_dpp v160, v160, v160 row_bcast:31 row_mask:0xc bank_mask:0xf
	s_nop 1
	v_readlane_b32 s0, v160, 63
	s_nop 2
	v_mov_b32_e32 v170, s0
	v_mul_f32_e32 v156, 0xba800000, v170
	v_mul_f32_e32 v157, 0xba800000, v170
	v_add_f32_e32 v114, v114, v156
	v_add_f32_e32 v115, v115, v157
	v_add_f32_e32 v116, v116, v156
	v_add_f32_e32 v117, v117, v157
	v_add_f32_e32 v118, v118, v156
	v_add_f32_e32 v119, v119, v157
	v_add_f32_e32 v120, v120, v156
	v_add_f32_e32 v121, v121, v157
	v_add_f32_e32 v122, v122, v156
	v_add_f32_e32 v123, v123, v157
	v_add_f32_e32 v124, v124, v156
	v_add_f32_e32 v125, v125, v157
	v_add_f32_e32 v126, v126, v156
	v_add_f32_e32 v127, v127, v157
	v_add_f32_e32 v128, v128, v156
	v_add_f32_e32 v129, v129, v157
	v_mul_f32_e32 v154, v114, v114
	v_mul_f32_e32 v155, v115, v115
	v_fma_f32 v154, v116, v116, v154
	v_fma_f32 v155, v117, v117, v155
	v_fma_f32 v154, v118, v118, v154
	v_fma_f32 v155, v119, v119, v155
	v_fma_f32 v154, v120, v120, v154
	v_fma_f32 v155, v121, v121, v155
	v_fma_f32 v154, v122, v122, v154
	v_fma_f32 v155, v123, v123, v155
	v_fma_f32 v154, v124, v124, v154
	v_fma_f32 v155, v125, v125, v155
	v_fma_f32 v154, v126, v126, v154
	v_fma_f32 v155, v127, v127, v155
	v_fma_f32 v154, v128, v128, v154
	v_fma_f32 v155, v129, v129, v155
	v_add_f32_e32 v154, v154, v155
	s_nop 1
	v_add_f32_dpp v160, v154, v154 quad_perm:[1,0,3,2] row_mask:0xf bank_mask:0xf
	s_nop 1
	v_add_f32_dpp v160, v160, v160 quad_perm:[2,3,0,1] row_mask:0xf bank_mask:0xf
	s_nop 1
	v_add_f32_dpp v160, v160, v160 row_half_mirror row_mask:0xf bank_mask:0xf
	s_nop 1
	v_add_f32_dpp v160, v160, v160 row_mirror row_mask:0xf bank_mask:0xf
	s_nop 1
	v_add_f32_dpp v160, v160, v160 row_bcast:15 row_mask:0xa bank_mask:0xf
	s_nop 1
	v_add_f32_dpp v160, v160, v160 row_bcast:31 row_mask:0xc bank_mask:0xf
	s_nop 1
	v_readlane_b32 s0, v160, 63
	s_nop 2
	v_mov_b32_e32 v170, s0
	v_fmamk_f32 v154, v170, 0x3a800000, v166
	s_mov_b32 s0, 0xf800000
	v_mul_f32_e32 v155, 0x4f800000, v154
; __device__ __forceinline__ float bflo(unsigned u) { return __uint_as_float(u << 16); }
; __device__ __forceinline__ float bfhi(unsigned u) { return __uint_as_float(u & 0xffff0000u); }
; __device__ __forceinline__ void ln_panel(int pm, const float* resf, const bf16* rlo, const bf16* dlt, float* xo, const float* gam, const float* bet, bf16* xb, bf16* wlo, bool fin, float alpha) {
;     ...
;         for (int j = 0; j < 4; ++j) { f32x4 x; const u32x2 d = *(const u32x2*)(dlt + prow + 256 * j);
;             if (resf) x = *(const f32x4*)(resf + grow + 256 * j);
;             else { const u32x2 h = *(const u32x2*)(xb + grow + 256 * j), l = *(const u32x2*)(rlo + prow + 256 * j);
;                    x = (f32x4){bflo(h.x) + bflo(l.x), bfhi(h.x) + bfhi(l.x), bflo(h.y) + bflo(l.y), bfhi(h.y) + bfhi(l.y)}; }
;             v[j] = (f32x4){x.x * alpha + bflo(d.x), x.y * alpha + bfhi(d.x), x.z * alpha + bflo(d.y), x.w * alpha + bfhi(d.y)}; s += (v[j].x + v[j].y) + (v[j].z + v[j].w); }
;     ...
;         const float rstd = 1.f / sqrtf(wave_sum(s2) * (1.f / DM) + LN_EPS);
; #pragma unroll
;         for (int j = 0; j < 4; ++j) { const f32x4 o = v[j] * rstd * gv[j] + bv[j];
;             if (fin) *(f32x4*)(xo + grow + 256 * j) = o;
	v_cmp_gt_f32_e32 vcc, s0, v154
	s_nop 1
	v_cndmask_b32_e32 v154, v154, v155, vcc
	v_sqrt_f32_e32 v155, v154
	s_nop 0
	v_add_u32_e32 v156, -1, v155
	v_fma_f32 v157, -v156, v155, v154
	v_cmp_ge_f32_e64 s[0:1], 0, v157
	v_add_u32_e32 v157, 1, v155
	s_nop 0
	v_cndmask_b32_e64 v156, v155, v156, s[0:1]
	v_fma_f32 v155, -v157, v155, v154
	v_cmp_lt_f32_e64 s[0:1], 0, v155
	s_nop 1
	v_cndmask_b32_e64 v155, v156, v157, s[0:1]
	v_mul_f32_e32 v156, 0x37800000, v155
	v_cndmask_b32_e32 v155, v155, v156, vcc
	v_cmp_class_f32_e32 vcc, v154, v167
	s_nop 1
	v_cndmask_b32_e32 v154, v155, v154, vcc
	v_div_scale_f32 v155, s[0:1], v154, v154, 1.0
	v_rcp_f32_e32 v156, v155
	s_nop 0
	v_fma_f32 v157, -v155, v156, 1.0
	v_fmac_f32_e32 v156, v157, v156
	v_div_scale_f32 v157, vcc, 1.0, v154, 1.0
	v_mul_f32_e32 v158, v157, v156
	v_fma_f32 v159, -v155, v158, v157
	v_fmac_f32_e32 v158, v159, v156
	v_fma_f32 v155, -v155, v158, v157
	s_nop 0
	v_div_fmas_f32 v155, v155, v156, v158
	v_div_fixup_f32 v168, v155, v154, 1.0
	s_add_i32 s0, s98, 0
	s_lshl_b32 s0, s0, 11
	s_mov_b32 s1, 0
	v_lshl_add_u64 v[184:185], s[0:1], 1, v[182:183]
	v_mul_f32_e32 v190, v114, v168
	v_mul_f32_e32 v191, v115, v168
	v_fma_f32 v190, v0, v190, v8
	v_fma_f32 v191, v1, v191, v9
	v_mul_f32_e32 v192, v116, v168
	v_mul_f32_e32 v193, v117, v168
	v_fma_f32 v192, v2, v192, v10
	v_fma_f32 v193, v3, v193, v11
	v_mul_f32_e32 v194, v118, v168
	v_mul_f32_e32 v195, v119, v168
	v_fma_f32 v194, v4, v194, v12
	v_fma_f32 v195, v5, v195, v13
	v_mul_f32_e32 v196, v120, v168
	v_mul_f32_e32 v197, v121, v168
	v_fma_f32 v196, v6, v196, v14
	v_fma_f32 v197, v7, v197, v15
	v_mul_f32_e32 v198, v122, v168
	v_mul_f32_e32 v199, v123, v168
	v_fma_f32 v198, v16, v198, v24
	v_fma_f32 v199, v17, v199, v25
	v_mul_f32_e32 v200, v124, v168
	v_mul_f32_e32 v201, v125, v168
	v_fma_f32 v200, v18, v200, v26
	v_fma_f32 v201, v19, v201, v27
	v_mul_f32_e32 v202, v126, v168
	v_mul_f32_e32 v203, v127, v168
	v_fma_f32 v202, v20, v202, v28
	v_fma_f32 v203, v21, v203, v29
	v_mul_f32_e32 v204, v128, v168
	v_mul_f32_e32 v205, v129, v168
	v_fma_f32 v204, v22, v204, v30
	v_fma_f32 v205, v23, v205, v31
	global_store_dwordx4 v[184:185], v[190:193], off offset:-2048
	global_store_dwordx4 v[184:185], v[194:197], off offset:-1024
	global_store_dwordx4 v[184:185], v[198:201], off offset:0
	global_store_dwordx4 v[184:185], v[202:205], off offset:1024
	s_add_i32 s0, s98, 2
	s_min_u32 s0, s0, 31
	s_lshl_b32 s0, s0, 11
	s_mov_b32 s1, 0
	v_lshl_add_u64 v[184:185], s[0:1], 0, v[178:179]
	v_lshl_add_u64 v[186:187], s[0:1], 0, v[172:173]
	v_lshl_add_u64 v[188:189], s[0:1], 0, v[176:177]
	global_load_dwordx2 v[82:83], v[184:185], off offset:-1024
	global_load_dwordx2 v[84:85], v[184:185], off offset:-512
	global_load_dwordx2 v[86:87], v[184:185], off offset:0
	global_load_dwordx2 v[88:89], v[184:185], off offset:512
	global_load_dwordx2 v[66:67], v[186:187], off offset:-1024
	global_load_dwordx2 v[68:69], v[186:187], off offset:-512
	global_load_dwordx2 v[70:71], v[186:187], off offset:0
	global_load_dwordx2 v[72:73], v[186:187], off offset:512
	global_load_dwordx2 v[74:75], v[188:189], off offset:-1024
	global_load_dwordx2 v[76:77], v[188:189], off offset:-512
	global_load_dwordx2 v[78:79], v[188:189], off offset:0
	global_load_dwordx2 v[80:81], v[188:189], off offset:512
	s_waitcnt vmcnt(16)
	v_lshlrev_b32_e32 v150, 16, v90
	v_and_b32_e32 v151, 0xffff0000, v90
	v_lshlrev_b32_e32 v152, 16, v98
	v_and_b32_e32 v153, 0xffff0000, v98
	v_add_f32_e32 v150, v150, v152
	v_add_f32_e32 v151, v151, v153
	v_lshlrev_b32_e32 v152, 16, v106
	v_and_b32_e32 v153, 0xffff0000, v106
	v_fma_f32 v114, v150, v164, v152
	v_fma_f32 v115, v151, v165, v153
	v_lshlrev_b32_e32 v150, 16, v91
	v_and_b32_e32 v151, 0xffff0000, v91
	v_lshlrev_b32_e32 v152, 16, v99
	v_and_b32_e32 v153, 0xffff0000, v99
	v_add_f32_e32 v150, v150, v152
	v_add_f32_e32 v151, v151, v153
	v_lshlrev_b32_e32 v152, 16, v107
	v_and_b32_e32 v153, 0xffff0000, v107
	v_fma_f32 v116, v150, v164, v152
	v_fma_f32 v117, v151, v165, v153
	v_lshlrev_b32_e32 v150, 16, v92
	v_and_b32_e32 v151, 0xffff0000, v92
	v_lshlrev_b32_e32 v152, 16, v100
	v_and_b32_e32 v153, 0xffff0000, v100
	v_add_f32_e32 v150, v150, v152
	v_add_f32_e32 v151, v151, v153
	v_lshlrev_b32_e32 v152, 16, v108
	v_and_b32_e32 v153, 0xffff0000, v108
	v_fma_f32 v118, v150, v164, v152
	v_fma_f32 v119, v151, v165, v153
	v_lshlrev_b32_e32 v150, 16, v93
	v_and_b32_e32 v151, 0xffff0000, v93
	v_lshlrev_b32_e32 v152, 16, v101
	v_and_b32_e32 v153, 0xffff0000, v101
	v_add_f32_e32 v150, v150, v152
	v_add_f32_e32 v151, v151, v153
	v_lshlrev_b32_e32 v152, 16, v109
	v_and_b32_e32 v153, 0xffff0000, v109
	v_fma_f32 v120, v150, v164, v152
	v_fma_f32 v121, v151, v165, v153
	v_lshlrev_b32_e32 v150, 16, v94
	v_and_b32_e32 v151, 0xffff0000, v94
	v_lshlrev_b32_e32 v152, 16, v102
	v_and_b32_e32 v153, 0xffff0000, v102
	v_add_f32_e32 v150, v150, v152
	v_add_f32_e32 v151, v151, v153
	v_lshlrev_b32_e32 v152, 16, v110
	v_and_b32_e32 v153, 0xffff0000, v110
	v_fma_f32 v122, v150, v164, v152
	v_fma_f32 v123, v151, v165, v153
	v_lshlrev_b32_e32 v150, 16, v95
	v_and_b32_e32 v151, 0xffff0000, v95
	v_lshlrev_b32_e32 v152, 16, v103
	v_and_b32_e32 v153, 0xffff0000, v103
	v_add_f32_e32 v150, v150, v152
	v_add_f32_e32 v151, v151, v153
	v_lshlrev_b32_e32 v152, 16, v111
	v_and_b32_e32 v153, 0xffff0000, v111
	v_fma_f32 v124, v150, v164, v152
	v_fma_f32 v125, v151, v165, v153
	v_lshlrev_b32_e32 v150, 16, v96
	v_and_b32_e32 v151, 0xffff0000, v96
	v_lshlrev_b32_e32 v152, 16, v104
	v_and_b32_e32 v153, 0xffff0000, v104
	v_add_f32_e32 v150, v150, v152
	v_add_f32_e32 v151, v151, v153
	v_lshlrev_b32_e32 v152, 16, v112
; __device__ __forceinline__ float bflo(unsigned u) { return __uint_as_float(u << 16); }
; __device__ __forceinline__ float bfhi(unsigned u) { return __uint_as_float(u & 0xffff0000u); }
; __device__ __forceinline__ void ln_panel(int pm, const float* resf, const bf16* rlo, const bf16* dlt, float* xo, const float* gam, const float* bet, bf16* xb, bf16* wlo, bool fin, float alpha) {
;     ...
;         for (int j = 0; j < 4; ++j) { f32x4 x; const u32x2 d = *(const u32x2*)(dlt + prow + 256 * j);
;             if (resf) x = *(const f32x4*)(resf + grow + 256 * j);
;             else { const u32x2 h = *(const u32x2*)(xb + grow + 256 * j), l = *(const u32x2*)(rlo + prow + 256 * j);
;                    x = (f32x4){bflo(h.x) + bflo(l.x), bfhi(h.x) + bfhi(l.x), bflo(h.y) + bflo(l.y), bfhi(h.y) + bfhi(l.y)}; }
;             v[j] = (f32x4){x.x * alpha + bflo(d.x), x.y * alpha + bfhi(d.x), x.z * alpha + bflo(d.y), x.w * alpha + bfhi(d.y)}; s += (v[j].x + v[j].y) + (v[j].z + v[j].w); }
;         const float mean = wave_sum(s) * (1.f / DM); float s2 = 0.f;
; #pragma unroll
;         for (int j = 0; j < 4; ++j) { v[j] = v[j] - mean; s2 += (v[j].x * v[j].x + v[j].y * v[j].y) + (v[j].z * v[j].z + v[j].w * v[j].w); }
;         const float rstd = 1.f / sqrtf(wave_sum(s2) * (1.f / DM) + LN_EPS);
; #pragma unroll
;         for (int j = 0; j < 4; ++j) { const f32x4 o = v[j] * rstd * gv[j] + bv[j];
;             if (fin) *(f32x4*)(xo + grow + 256 * j) = o;
	v_and_b32_e32 v153, 0xffff0000, v112
	v_fma_f32 v126, v150, v164, v152
	v_fma_f32 v127, v151, v165, v153
	v_lshlrev_b32_e32 v150, 16, v97
	v_and_b32_e32 v151, 0xffff0000, v97
	v_lshlrev_b32_e32 v152, 16, v105
	v_and_b32_e32 v153, 0xffff0000, v105
	v_add_f32_e32 v150, v150, v152
	v_add_f32_e32 v151, v151, v153
	v_lshlrev_b32_e32 v152, 16, v113
	v_and_b32_e32 v153, 0xffff0000, v113
	v_fma_f32 v128, v150, v164, v152
	v_fma_f32 v129, v151, v165, v153
	v_add_f32_e32 v154, v114, v116
	v_add_f32_e32 v155, v115, v117
	v_add_f32_e32 v156, v118, v120
	v_add_f32_e32 v157, v119, v121
	v_add_f32_e32 v154, v154, v156
	v_add_f32_e32 v155, v155, v157
	v_add_f32_e32 v156, v122, v124
	v_add_f32_e32 v157, v123, v125
	v_add_f32_e32 v154, v154, v156
	v_add_f32_e32 v155, v155, v157
	v_add_f32_e32 v156, v126, v128
	v_add_f32_e32 v157, v127, v129
	v_add_f32_e32 v154, v154, v156
	v_add_f32_e32 v155, v155, v157
	v_add_f32_e32 v154, v154, v155
	s_nop 1
	v_add_f32_dpp v160, v154, v154 quad_perm:[1,0,3,2] row_mask:0xf bank_mask:0xf
	s_nop 1
	v_add_f32_dpp v160, v160, v160 quad_perm:[2,3,0,1] row_mask:0xf bank_mask:0xf
	s_nop 1
	v_add_f32_dpp v160, v160, v160 row_half_mirror row_mask:0xf bank_mask:0xf
	s_nop 1
	v_add_f32_dpp v160, v160, v160 row_mirror row_mask:0xf bank_mask:0xf
	s_nop 1
	v_add_f32_dpp v160, v160, v160 row_bcast:15 row_mask:0xa bank_mask:0xf
	s_nop 1
	v_add_f32_dpp v160, v160, v160 row_bcast:31 row_mask:0xc bank_mask:0xf
	s_nop 1
	v_readlane_b32 s0, v160, 63
	s_nop 2
	v_mov_b32_e32 v170, s0
	v_mul_f32_e32 v156, 0xba800000, v170
	v_mul_f32_e32 v157, 0xba800000, v170
	v_add_f32_e32 v114, v114, v156
	v_add_f32_e32 v115, v115, v157
	v_add_f32_e32 v116, v116, v156
	v_add_f32_e32 v117, v117, v157
	v_add_f32_e32 v118, v118, v156
	v_add_f32_e32 v119, v119, v157
	v_add_f32_e32 v120, v120, v156
	v_add_f32_e32 v121, v121, v157
	v_add_f32_e32 v122, v122, v156
	v_add_f32_e32 v123, v123, v157
	v_add_f32_e32 v124, v124, v156
	v_add_f32_e32 v125, v125, v157
	v_add_f32_e32 v126, v126, v156
	v_add_f32_e32 v127, v127, v157
	v_add_f32_e32 v128, v128, v156
	v_add_f32_e32 v129, v129, v157
	v_mul_f32_e32 v154, v114, v114
	v_mul_f32_e32 v155, v115, v115
	v_fma_f32 v154, v116, v116, v154
	v_fma_f32 v155, v117, v117, v155
	v_fma_f32 v154, v118, v118, v154
	v_fma_f32 v155, v119, v119, v155
	v_fma_f32 v154, v120, v120, v154
	v_fma_f32 v155, v121, v121, v155
	v_fma_f32 v154, v122, v122, v154
	v_fma_f32 v155, v123, v123, v155
	v_fma_f32 v154, v124, v124, v154
	v_fma_f32 v155, v125, v125, v155
	v_fma_f32 v154, v126, v126, v154
	v_fma_f32 v155, v127, v127, v155
	v_fma_f32 v154, v128, v128, v154
	v_fma_f32 v155, v129, v129, v155
	v_add_f32_e32 v154, v154, v155
	s_nop 1
	v_add_f32_dpp v160, v154, v154 quad_perm:[1,0,3,2] row_mask:0xf bank_mask:0xf
	s_nop 1
	v_add_f32_dpp v160, v160, v160 quad_perm:[2,3,0,1] row_mask:0xf bank_mask:0xf
	s_nop 1
	v_add_f32_dpp v160, v160, v160 row_half_mirror row_mask:0xf bank_mask:0xf
	s_nop 1
	v_add_f32_dpp v160, v160, v160 row_mirror row_mask:0xf bank_mask:0xf
	s_nop 1
	v_add_f32_dpp v160, v160, v160 row_bcast:15 row_mask:0xa bank_mask:0xf
	s_nop 1
	v_add_f32_dpp v160, v160, v160 row_bcast:31 row_mask:0xc bank_mask:0xf
	s_nop 1
	v_readlane_b32 s0, v160, 63
	s_nop 2
	v_mov_b32_e32 v170, s0
	v_fmamk_f32 v154, v170, 0x3a800000, v166
	s_mov_b32 s0, 0xf800000
	v_mul_f32_e32 v155, 0x4f800000, v154
	v_cmp_gt_f32_e32 vcc, s0, v154
	s_nop 1
	v_cndmask_b32_e32 v154, v154, v155, vcc
	v_sqrt_f32_e32 v155, v154
	s_nop 0
	v_add_u32_e32 v156, -1, v155
	v_fma_f32 v157, -v156, v155, v154
	v_cmp_ge_f32_e64 s[0:1], 0, v157
	v_add_u32_e32 v157, 1, v155
	s_nop 0
	v_cndmask_b32_e64 v156, v155, v156, s[0:1]
	v_fma_f32 v155, -v157, v155, v154
	v_cmp_lt_f32_e64 s[0:1], 0, v155
	s_nop 1
	v_cndmask_b32_e64 v155, v156, v157, s[0:1]
	v_mul_f32_e32 v156, 0x37800000, v155
	v_cndmask_b32_e32 v155, v155, v156, vcc
	v_cmp_class_f32_e32 vcc, v154, v167
	s_nop 1
	v_cndmask_b32_e32 v154, v155, v154, vcc
	v_div_scale_f32 v155, s[0:1], v154, v154, 1.0
	v_rcp_f32_e32 v156, v155
	s_nop 0
	v_fma_f32 v157, -v155, v156, 1.0
	v_fmac_f32_e32 v156, v157, v156
	v_div_scale_f32 v157, vcc, 1.0, v154, 1.0
	v_mul_f32_e32 v158, v157, v156
	v_fma_f32 v159, -v155, v158, v157
	v_fmac_f32_e32 v158, v159, v156
	v_fma_f32 v155, -v155, v158, v157
	s_nop 0
	v_div_fmas_f32 v155, v155, v156, v158
	v_div_fixup_f32 v168, v155, v154, 1.0
	s_add_i32 s0, s98, 1
	s_lshl_b32 s0, s0, 11
	s_mov_b32 s1, 0
	v_lshl_add_u64 v[184:185], s[0:1], 1, v[182:183]
	v_mul_f32_e32 v190, v114, v168
	v_mul_f32_e32 v191, v115, v168
	v_fma_f32 v190, v0, v190, v8
	v_fma_f32 v191, v1, v191, v9
	v_mul_f32_e32 v192, v116, v168
	v_mul_f32_e32 v193, v117, v168
	v_fma_f32 v192, v2, v192, v10
	v_fma_f32 v193, v3, v193, v11
	v_mul_f32_e32 v194, v118, v168
	v_mul_f32_e32 v195, v119, v168
	v_fma_f32 v194, v4, v194, v12
	v_fma_f32 v195, v5, v195, v13
	v_mul_f32_e32 v196, v120, v168
	v_mul_f32_e32 v197, v121, v168
	v_fma_f32 v196, v6, v196, v14
	v_fma_f32 v197, v7, v197, v15
	v_mul_f32_e32 v198, v122, v168
	v_mul_f32_e32 v199, v123, v168
	v_fma_f32 v198, v16, v198, v24
	v_fma_f32 v199, v17, v199, v25
	v_mul_f32_e32 v200, v124, v168
	v_mul_f32_e32 v201, v125, v168
	v_fma_f32 v200, v18, v200, v26
	v_fma_f32 v201, v19, v201, v27
	v_mul_f32_e32 v202, v126, v168
	v_mul_f32_e32 v203, v127, v168
	v_fma_f32 v202, v20, v202, v28
	v_fma_f32 v203, v21, v203, v29
	v_mul_f32_e32 v204, v128, v168
	v_mul_f32_e32 v205, v129, v168
	v_fma_f32 v204, v22, v204, v30
	v_fma_f32 v205, v23, v205, v31
	global_store_dwordx4 v[184:185], v[190:193], off offset:-2048
	global_store_dwordx4 v[184:185], v[194:197], off offset:-1024
	global_store_dwordx4 v[184:185], v[198:201], off offset:0
	global_store_dwordx4 v[184:185], v[202:205], off offset:1024
	s_add_i32 s0, s98, 3
	s_min_u32 s0, s0, 31
	s_lshl_b32 s0, s0, 11
	s_mov_b32 s1, 0
	v_lshl_add_u64 v[184:185], s[0:1], 0, v[178:179]
	v_lshl_add_u64 v[186:187], s[0:1], 0, v[172:173]
	v_lshl_add_u64 v[188:189], s[0:1], 0, v[176:177]
	global_load_dwordx2 v[106:107], v[184:185], off offset:-1024
	global_load_dwordx2 v[108:109], v[184:185], off offset:-512
	global_load_dwordx2 v[110:111], v[184:185], off offset:0
	global_load_dwordx2 v[112:113], v[184:185], off offset:512
	global_load_dwordx2 v[90:91], v[186:187], off offset:-1024
	global_load_dwordx2 v[92:93], v[186:187], off offset:-512
	global_load_dwordx2 v[94:95], v[186:187], off offset:0
	global_load_dwordx2 v[96:97], v[186:187], off offset:512
	global_load_dwordx2 v[98:99], v[188:189], off offset:-1024
	global_load_dwordx2 v[100:101], v[188:189], off offset:-512
	global_load_dwordx2 v[102:103], v[188:189], off offset:0
	global_load_dwordx2 v[104:105], v[188:189], off offset:512
	s_add_i32 s98, s98, 2
	s_cmp_lt_u32 s98, 32
	s_cbranch_scc1 .Lmy_ln2f_loop
	s_waitcnt vmcnt(0)
	s_branch .LBB0_467
